# GEMM loops: s_setprio 1 moved before barrier, duplicate lgkmcnt(0) after barrier removed, mid-segment setprio 0/1 pairs removed, setprio 0 moved after closing barrier
# baseline (speedup 1.0000x reference)
; #define PG8_STAGE(bufoff, gbase, voff) do { _Pragma("unroll") for (int _i = 0; _i < 2; ++_i) \
;         __builtin_amdgcn_global_load_lds((const unsigned*)((const char*)(gbase) + (voff)[_i]), (LAS unsigned*)(lds + (bufoff) + ldsw + _i * 8192), 16, 0, ((voff) == voffA ? AUXA : 0)); } while (0)
; #define PG8_LDA(dst, b, h) do { _Pragma("unroll") for (int m = 0; m < 4; ++m) _Pragma("unroll") for (int k = 0; k < 2; ++k) dst[m][k] = *(const LAS bf16x8*)(lds + PG8_SA(b, h) + aoff + m * 2048 + k * 1024); } while (0)
; #define PG8_LDB(dst, b, h) do { _Pragma("unroll") for (int n = 0; n < 2; ++n) _Pragma("unroll") for (int k = 0; k < 2; ++k) dst[n][k] = *(const LAS bf16x8*)(lds + PG8_SB(b, h) + boff + n * 2048 + k * 1024); } while (0)
; #define PG8_MMA(ai, bj, At, Bt) do { __builtin_amdgcn_s_setprio(1); _Pragma("unroll") for (int m = 0; m < 4; ++m) _Pragma("unroll") for (int n = 0; n < 2; ++n) _Pragma("unroll") for (int k = 0; k < 2; ++k) \
;         acc[ai][bj][m][n] = __builtin_amdgcn_mfma_f32_16x16x32_bf16(Bt[n][k], At[m][k], acc[ai][bj][m][n], 0, 0, 0); __builtin_amdgcn_s_setprio(0); } while (0)
; #define PG8_WAIT_V(n) asm volatile("s_waitcnt vmcnt(" #n ")" ::: "memory")
; #define PG8_WAIT_L(n) asm volatile("s_waitcnt lgkmcnt(" #n ")" ::: "memory")
; #define PG8_BAR __builtin_amdgcn_s_barrier()
; #define PG8_SCHED __builtin_amdgcn_sched_barrier(0)
;     ...
;             PG8_WAIT_L(0); PG8_BAR; PG8_MMA(1, 0, At, B0); PG8_MMA(1, 1, At, B1); PG8_BAR; PG8_SCHED;
;             PG8_LDB(B0, 1, 0); PG8_LDB(B1, 1, 1); PG8_SCHED; PG8_LDA(At, 1, 0); PG8_STAGE(PG8_SA(0, 1), a2 + hsA, voffA);
;             PG8_WAIT_V(8); PG8_WAIT_L(0); PG8_BAR; PG8_MMA(0, 0, At, B0); PG8_MMA(0, 1, At, B1); PG8_BAR; PG8_SCHED;
.LBB0_148:
	s_waitcnt lgkmcnt(0)
	s_add_i32 s61, s61, 2
	s_setprio 1
	s_barrier
	v_mfma_f32_16x16x32_bf16 v[60:63], v[144:147], v[184:187], v[60:63]
	v_mfma_f32_16x16x32_bf16 v[52:55], v[152:155], v[184:187], v[52:55]
	v_mfma_f32_16x16x32_bf16 v[44:47], v[144:147], v[176:179], v[44:47]
	v_mfma_f32_16x16x32_bf16 v[36:39], v[152:155], v[176:179], v[36:39]
	v_mfma_f32_16x16x32_bf16 v[28:31], v[144:147], v[168:171], v[28:31]
	v_mfma_f32_16x16x32_bf16 v[20:23], v[152:155], v[168:171], v[20:23]
	v_mfma_f32_16x16x32_bf16 v[12:15], v[144:147], v[160:163], v[12:15]
	v_mfma_f32_16x16x32_bf16 v[4:7], v[152:155], v[160:163], v[4:7]
	v_mfma_f32_16x16x32_bf16 v[60:63], v[148:151], v[188:191], v[60:63]
	v_mfma_f32_16x16x32_bf16 v[52:55], v[156:159], v[188:191], v[52:55]
	v_mfma_f32_16x16x32_bf16 v[44:47], v[148:151], v[180:183], v[44:47]
	v_mfma_f32_16x16x32_bf16 v[36:39], v[156:159], v[180:183], v[36:39]
	v_mfma_f32_16x16x32_bf16 v[28:31], v[148:151], v[172:175], v[28:31]
	v_mfma_f32_16x16x32_bf16 v[20:23], v[156:159], v[172:175], v[20:23]
	v_mfma_f32_16x16x32_bf16 v[12:15], v[148:151], v[164:167], v[12:15]
	v_mfma_f32_16x16x32_bf16 v[4:7], v[156:159], v[164:167], v[4:7]
	v_mfma_f32_16x16x32_bf16 v[56:59], v[128:131], v[184:187], v[56:59]
	v_mfma_f32_16x16x32_bf16 v[48:51], v[136:139], v[184:187], v[48:51]
	v_mfma_f32_16x16x32_bf16 v[40:43], v[128:131], v[176:179], v[40:43]
	v_mfma_f32_16x16x32_bf16 v[32:35], v[136:139], v[176:179], v[32:35]
	v_mfma_f32_16x16x32_bf16 v[24:27], v[128:131], v[168:171], v[24:27]
	v_mfma_f32_16x16x32_bf16 v[16:19], v[136:139], v[168:171], v[16:19]
	v_mfma_f32_16x16x32_bf16 v[8:11], v[128:131], v[160:163], v[8:11]
	v_mfma_f32_16x16x32_bf16 v[0:3], v[136:139], v[160:163], v[0:3]
	v_mfma_f32_16x16x32_bf16 v[56:59], v[132:135], v[188:191], v[56:59]
	v_mfma_f32_16x16x32_bf16 v[48:51], v[140:143], v[188:191], v[48:51]
	v_mfma_f32_16x16x32_bf16 v[40:43], v[132:135], v[180:183], v[40:43]
	v_mfma_f32_16x16x32_bf16 v[32:35], v[140:143], v[180:183], v[32:35]
	v_mfma_f32_16x16x32_bf16 v[24:27], v[132:135], v[172:175], v[24:27]
	v_mfma_f32_16x16x32_bf16 v[16:19], v[140:143], v[172:175], v[16:19]
	v_mfma_f32_16x16x32_bf16 v[8:11], v[132:135], v[164:167], v[8:11]
	v_mfma_f32_16x16x32_bf16 v[0:3], v[140:143], v[164:167], v[0:3]
	s_barrier
	s_setprio 0
	s_add_i32 s36, 0, 0x18000
	s_add_i32 s37, 0, 0x1c000
	v_add_u32_e32 v140, s36, v222
	v_add_u32_e32 v156, s37, v222
	ds_read_b128 v[128:131], v140
	ds_read_b128 v[132:135], v140 offset:1024
	ds_read_b128 v[136:139], v140 offset:2048
	ds_read_b128 v[140:143], v140 offset:3072
	ds_read_b128 v[144:147], v156
	ds_read_b128 v[148:151], v156 offset:1024
	ds_read_b128 v[152:155], v156 offset:2048
	ds_read_b128 v[156:159], v156 offset:3072
	s_add_u32 s34, s34, 0x80000
	s_addc_u32 s35, s35, 0
	s_mov_b32 m0, s46
	ds_read_b128 v[160:163], v226 offset:32768
	ds_read_b128 v[164:167], v226 offset:33792
	ds_read_b128 v[168:171], v226 offset:34816
	ds_read_b128 v[172:175], v226 offset:35840
	ds_read_b128 v[176:179], v226 offset:36864
	ds_read_b128 v[180:183], v226 offset:37888
	ds_read_b128 v[184:187], v226 offset:38912
	ds_read_b128 v[188:191], v226 offset:39936
	global_load_lds_dwordx4 v200, s[34:35]
	s_mov_b32 m0, s47
	s_nop 0
	global_load_lds_dwordx4 v196, s[34:35]
	s_waitcnt vmcnt(8)
	s_waitcnt lgkmcnt(0)
	s_setprio 1
	s_barrier
; #define PG8_STAGE(bufoff, gbase, voff) do { _Pragma("unroll") for (int _i = 0; _i < 2; ++_i) \
;         __builtin_amdgcn_global_load_lds((const unsigned*)((const char*)(gbase) + (voff)[_i]), (LAS unsigned*)(lds + (bufoff) + ldsw + _i * 8192), 16, 0, ((voff) == voffA ? AUXA : 0)); } while (0)
; #define PG8_LDA(dst, b, h) do { _Pragma("unroll") for (int m = 0; m < 4; ++m) _Pragma("unroll") for (int k = 0; k < 2; ++k) dst[m][k] = *(const LAS bf16x8*)(lds + PG8_SA(b, h) + aoff + m * 2048 + k * 1024); } while (0)
; #define PG8_MMA(ai, bj, At, Bt) do { __builtin_amdgcn_s_setprio(1); _Pragma("unroll") for (int m = 0; m < 4; ++m) _Pragma("unroll") for (int n = 0; n < 2; ++n) _Pragma("unroll") for (int k = 0; k < 2; ++k) \
;         acc[ai][bj][m][n] = __builtin_amdgcn_mfma_f32_16x16x32_bf16(Bt[n][k], At[m][k], acc[ai][bj][m][n], 0, 0, 0); __builtin_amdgcn_s_setprio(0); } while (0)
; #define PG8_WAIT_V(n) asm volatile("s_waitcnt vmcnt(" #n ")" ::: "memory")
; #define PG8_WAIT_L(n) asm volatile("s_waitcnt lgkmcnt(" #n ")" ::: "memory")
; #define PG8_BAR __builtin_amdgcn_s_barrier()
; #define PG8_SCHED __builtin_amdgcn_sched_barrier(0)
;     ...
;             PG8_WAIT_V(8); PG8_WAIT_L(0); PG8_BAR; PG8_MMA(0, 0, At, B0); PG8_MMA(0, 1, At, B1); PG8_BAR; PG8_SCHED;
;             PG8_LDA(At, 1, 1); PG8_STAGE(PG8_SB(1, 0), b3, voffB); PG8_STAGE(PG8_SB(1, 1), b3 + hsB, voffB); PG8_STAGE(PG8_SA(1, 0), a3, voffA);
;             PG8_WAIT_V(8); PG8_WAIT_L(0); PG8_BAR; PG8_MMA(1, 0, At, B0); PG8_MMA(1, 1, At, B1); PG8_BAR; PG8_SCHED;
;         }
	v_mfma_f32_16x16x32_bf16 v[124:127], v[128:131], v[160:163], v[124:127]
	v_mfma_f32_16x16x32_bf16 v[116:119], v[136:139], v[160:163], v[116:119]
	v_mfma_f32_16x16x32_bf16 v[108:111], v[128:131], v[168:171], v[108:111]
	v_mfma_f32_16x16x32_bf16 v[100:103], v[136:139], v[168:171], v[100:103]
	v_mfma_f32_16x16x32_bf16 v[92:95], v[128:131], v[176:179], v[92:95]
	v_mfma_f32_16x16x32_bf16 v[84:87], v[136:139], v[176:179], v[84:87]
	v_mfma_f32_16x16x32_bf16 v[76:79], v[128:131], v[184:187], v[76:79]
	v_mfma_f32_16x16x32_bf16 v[68:71], v[136:139], v[184:187], v[68:71]
	v_mfma_f32_16x16x32_bf16 v[124:127], v[132:135], v[164:167], v[124:127]
	v_mfma_f32_16x16x32_bf16 v[116:119], v[140:143], v[164:167], v[116:119]
	v_mfma_f32_16x16x32_bf16 v[108:111], v[132:135], v[172:175], v[108:111]
	v_mfma_f32_16x16x32_bf16 v[100:103], v[140:143], v[172:175], v[100:103]
	v_mfma_f32_16x16x32_bf16 v[92:95], v[132:135], v[180:183], v[92:95]
	v_mfma_f32_16x16x32_bf16 v[84:87], v[140:143], v[180:183], v[84:87]
	v_mfma_f32_16x16x32_bf16 v[76:79], v[132:135], v[188:191], v[76:79]
	v_mfma_f32_16x16x32_bf16 v[68:71], v[140:143], v[188:191], v[68:71]
	v_mfma_f32_16x16x32_bf16 v[120:123], v[144:147], v[160:163], v[120:123]
	v_mfma_f32_16x16x32_bf16 v[112:115], v[152:155], v[160:163], v[112:115]
	v_mfma_f32_16x16x32_bf16 v[104:107], v[144:147], v[168:171], v[104:107]
	v_mfma_f32_16x16x32_bf16 v[96:99], v[152:155], v[168:171], v[96:99]
	v_mfma_f32_16x16x32_bf16 v[88:91], v[144:147], v[176:179], v[88:91]
	v_mfma_f32_16x16x32_bf16 v[80:83], v[152:155], v[176:179], v[80:83]
	v_mfma_f32_16x16x32_bf16 v[72:75], v[144:147], v[184:187], v[72:75]
	v_mfma_f32_16x16x32_bf16 v[64:67], v[152:155], v[184:187], v[64:67]
	v_mfma_f32_16x16x32_bf16 v[120:123], v[148:151], v[164:167], v[120:123]
	v_mfma_f32_16x16x32_bf16 v[112:115], v[156:159], v[164:167], v[112:115]
	v_mfma_f32_16x16x32_bf16 v[104:107], v[148:151], v[172:175], v[104:107]
	v_mfma_f32_16x16x32_bf16 v[96:99], v[156:159], v[172:175], v[96:99]
	v_mfma_f32_16x16x32_bf16 v[88:91], v[148:151], v[180:183], v[88:91]
	v_mfma_f32_16x16x32_bf16 v[80:83], v[156:159], v[180:183], v[80:83]
	v_mfma_f32_16x16x32_bf16 v[72:75], v[148:151], v[188:191], v[72:75]
	v_mfma_f32_16x16x32_bf16 v[64:67], v[156:159], v[188:191], v[64:67]
	s_barrier
	s_setprio 0
	s_add_i32 s34, s36, s3
	s_mov_b32 m0, s34
	ds_read_b128 v[160:163], v226 offset:49152
	ds_read_b128 v[164:167], v226 offset:50176
	ds_read_b128 v[168:171], v226 offset:51200
	ds_read_b128 v[172:175], v226 offset:52224
	ds_read_b128 v[176:179], v226 offset:53248
	ds_read_b128 v[180:183], v226 offset:54272
	ds_read_b128 v[184:187], v226 offset:55296
	ds_read_b128 v[188:191], v226 offset:56320
	global_load_lds_dwordx4 v198, s[98:99]
	s_add_i32 m0, s34, 0x2000
	s_add_u32 s30, s30, 0x80080
	s_addc_u32 s31, s31, 0
	s_add_i32 s34, s37, s3
	global_load_lds_dwordx4 v194, s[98:99]
	s_mov_b32 m0, s34
	s_nop 0
	global_load_lds_dwordx4 v198, s[30:31]
	s_add_i32 m0, s34, 0x2000
	s_nop 0
	global_load_lds_dwordx4 v194, s[30:31]
	s_mov_b32 m0, s50
	s_nop 0
	global_load_lds_dwordx4 v200, s[100:101]
	s_mov_b32 m0, s51
	s_nop 0
	global_load_lds_dwordx4 v196, s[100:101]
	s_waitcnt vmcnt(8)
	s_waitcnt lgkmcnt(0)
	s_setprio 1
	s_barrier
	v_mfma_f32_16x16x32_bf16 v[60:63], v[128:131], v[160:163], v[60:63]
	v_mfma_f32_16x16x32_bf16 v[52:55], v[136:139], v[160:163], v[52:55]
	v_mfma_f32_16x16x32_bf16 v[44:47], v[128:131], v[168:171], v[44:47]
	v_mfma_f32_16x16x32_bf16 v[36:39], v[136:139], v[168:171], v[36:39]
	v_mfma_f32_16x16x32_bf16 v[28:31], v[128:131], v[176:179], v[28:31]
	v_mfma_f32_16x16x32_bf16 v[20:23], v[136:139], v[176:179], v[20:23]
	v_mfma_f32_16x16x32_bf16 v[12:15], v[128:131], v[184:187], v[12:15]
	v_mfma_f32_16x16x32_bf16 v[4:7], v[136:139], v[184:187], v[4:7]
	v_mfma_f32_16x16x32_bf16 v[60:63], v[132:135], v[164:167], v[60:63]
	v_mfma_f32_16x16x32_bf16 v[52:55], v[140:143], v[164:167], v[52:55]
	v_mfma_f32_16x16x32_bf16 v[44:47], v[132:135], v[172:175], v[44:47]
	v_mfma_f32_16x16x32_bf16 v[36:39], v[140:143], v[172:175], v[36:39]
	v_mfma_f32_16x16x32_bf16 v[28:31], v[132:135], v[180:183], v[28:31]
	v_mfma_f32_16x16x32_bf16 v[20:23], v[140:143], v[180:183], v[20:23]
	v_mfma_f32_16x16x32_bf16 v[12:15], v[132:135], v[188:191], v[12:15]
	v_mfma_f32_16x16x32_bf16 v[4:7], v[140:143], v[188:191], v[4:7]
	v_mfma_f32_16x16x32_bf16 v[56:59], v[144:147], v[160:163], v[56:59]
	v_mfma_f32_16x16x32_bf16 v[48:51], v[152:155], v[160:163], v[48:51]
	v_mfma_f32_16x16x32_bf16 v[40:43], v[144:147], v[168:171], v[40:43]
	v_mfma_f32_16x16x32_bf16 v[32:35], v[152:155], v[168:171], v[32:35]
	v_mfma_f32_16x16x32_bf16 v[24:27], v[144:147], v[176:179], v[24:27]
	v_mfma_f32_16x16x32_bf16 v[16:19], v[152:155], v[176:179], v[16:19]
	v_mfma_f32_16x16x32_bf16 v[8:11], v[144:147], v[184:187], v[8:11]
	v_mfma_f32_16x16x32_bf16 v[0:3], v[152:155], v[184:187], v[0:3]
	v_mfma_f32_16x16x32_bf16 v[56:59], v[148:151], v[164:167], v[56:59]
	v_mfma_f32_16x16x32_bf16 v[48:51], v[156:159], v[164:167], v[48:51]
	v_mfma_f32_16x16x32_bf16 v[40:43], v[148:151], v[172:175], v[40:43]
	v_mfma_f32_16x16x32_bf16 v[32:35], v[156:159], v[172:175], v[32:35]
	v_mfma_f32_16x16x32_bf16 v[24:27], v[148:151], v[180:183], v[24:27]
	v_mfma_f32_16x16x32_bf16 v[16:19], v[156:159], v[180:183], v[16:19]
	v_mfma_f32_16x16x32_bf16 v[8:11], v[148:151], v[188:191], v[8:11]
	v_mfma_f32_16x16x32_bf16 v[0:3], v[156:159], v[188:191], v[0:3]
	s_barrier
	s_setprio 0
	s_add_u32 s28, s28, 0x100
	s_addc_u32 s29, s29, 0
	s_add_u32 s59, s59, 0x100
	s_addc_u32 s60, s60, 0
	s_cmp_ge_i32 s61, s49
	s_cbranch_scc1 .LBB0_158

; #define PG8_STAGE(bufoff, gbase, voff) do { _Pragma("unroll") for (int _i = 0; _i < 2; ++_i) \
;         __builtin_amdgcn_global_load_lds((const unsigned*)((const char*)(gbase) + (voff)[_i]), (LAS unsigned*)(lds + (bufoff) + ldsw + _i * 8192), 16, 0, ((voff) == voffA ? AUXA : 0)); } while (0)
; #define PG8_LDA(dst, b, h) do { _Pragma("unroll") for (int m = 0; m < 4; ++m) _Pragma("unroll") for (int k = 0; k < 2; ++k) dst[m][k] = *(const LAS bf16x8*)(lds + PG8_SA(b, h) + aoff + m * 2048 + k * 1024); } while (0)
; #define PG8_LDB(dst, b, h) do { _Pragma("unroll") for (int n = 0; n < 2; ++n) _Pragma("unroll") for (int k = 0; k < 2; ++k) dst[n][k] = *(const LAS bf16x8*)(lds + PG8_SB(b, h) + boff + n * 2048 + k * 1024); } while (0)
; #define PG8_MMA(ai, bj, At, Bt) do { __builtin_amdgcn_s_setprio(1); _Pragma("unroll") for (int m = 0; m < 4; ++m) _Pragma("unroll") for (int n = 0; n < 2; ++n) _Pragma("unroll") for (int k = 0; k < 2; ++k) \
;         acc[ai][bj][m][n] = __builtin_amdgcn_mfma_f32_16x16x32_bf16(Bt[n][k], At[m][k], acc[ai][bj][m][n], 0, 0, 0); __builtin_amdgcn_s_setprio(0); } while (0)
; #define PG8_WAIT_V(n) asm volatile("s_waitcnt vmcnt(" #n ")" ::: "memory")
; #define PG8_WAIT_L(n) asm volatile("s_waitcnt lgkmcnt(" #n ")" ::: "memory")
; #define PG8_BAR __builtin_amdgcn_s_barrier()
; #define PG8_SCHED __builtin_amdgcn_sched_barrier(0)
;     ...
;             const char* a2 = last ? nA : cA + (size_t)(t + 2) * kstep; const char* b2 = last ? nB : cB + (size_t)(t + 2) * kstep;
;             const char* a3 = a2 + kstep; const char* b3 = b2 + kstep;
;             PG8_LDB(B0, 0, 0); PG8_LDB(B1, 0, 1); PG8_SCHED; PG8_LDA(At, 0, 0); PG8_STAGE(PG8_SA(1, 1), a1 + hsA, voffA);
;             if (Epi::NPRE != 0 && last) { E.pre(sv, cur, wr, fr); PG8_WAIT_V(16); } else { PG8_WAIT_V(8); }
;             PG8_WAIT_L(0); PG8_BAR; PG8_MMA(0, 0, At, B0); PG8_MMA(0, 1, At, B1); PG8_BAR; PG8_SCHED;
;             PG8_LDA(At, 0, 1); PG8_STAGE(PG8_SB(0, 0), b2, voffB); PG8_STAGE(PG8_SB(0, 1), b2 + hsB, voffB); PG8_STAGE(PG8_SA(0, 0), a2, voffA);
;             if (Epi::NPRE != 0 && last) { PG8_WAIT_V(16); } else { PG8_WAIT_V(8); }
.LBB0_153:
	s_add_u32 s34, s28, 0xfff80080
	s_addc_u32 s35, s29, -1
	s_waitcnt lgkmcnt(0)
	s_and_b64 s[30:31], s[30:31], exec
	s_cselect_b32 s35, s21, s35
	s_cselect_b32 s34, s23, s34
	s_cselect_b32 s31, s57, s60
	s_cselect_b32 s30, s58, s59
	s_setprio 1
	s_barrier
	v_mfma_f32_16x16x32_bf16 v[124:127], v[144:147], v[184:187], v[124:127]
	v_mfma_f32_16x16x32_bf16 v[116:119], v[152:155], v[184:187], v[116:119]
	v_mfma_f32_16x16x32_bf16 v[108:111], v[144:147], v[176:179], v[108:111]
	v_mfma_f32_16x16x32_bf16 v[100:103], v[152:155], v[176:179], v[100:103]
	v_mfma_f32_16x16x32_bf16 v[92:95], v[144:147], v[168:171], v[92:95]
	v_mfma_f32_16x16x32_bf16 v[84:87], v[152:155], v[168:171], v[84:87]
	v_mfma_f32_16x16x32_bf16 v[76:79], v[144:147], v[160:163], v[76:79]
	v_mfma_f32_16x16x32_bf16 v[68:71], v[152:155], v[160:163], v[68:71]
	v_mfma_f32_16x16x32_bf16 v[124:127], v[148:151], v[188:191], v[124:127]
	v_mfma_f32_16x16x32_bf16 v[116:119], v[156:159], v[188:191], v[116:119]
	v_mfma_f32_16x16x32_bf16 v[108:111], v[148:151], v[180:183], v[108:111]
	v_mfma_f32_16x16x32_bf16 v[100:103], v[156:159], v[180:183], v[100:103]
	v_mfma_f32_16x16x32_bf16 v[92:95], v[148:151], v[172:175], v[92:95]
	v_mfma_f32_16x16x32_bf16 v[84:87], v[156:159], v[172:175], v[84:87]
	v_mfma_f32_16x16x32_bf16 v[76:79], v[148:151], v[164:167], v[76:79]
	v_mfma_f32_16x16x32_bf16 v[68:71], v[156:159], v[164:167], v[68:71]
	v_mfma_f32_16x16x32_bf16 v[120:123], v[128:131], v[184:187], v[120:123]
	v_mfma_f32_16x16x32_bf16 v[112:115], v[136:139], v[184:187], v[112:115]
	v_mfma_f32_16x16x32_bf16 v[104:107], v[128:131], v[176:179], v[104:107]
	v_mfma_f32_16x16x32_bf16 v[96:99], v[136:139], v[176:179], v[96:99]
	v_mfma_f32_16x16x32_bf16 v[88:91], v[128:131], v[168:171], v[88:91]
	v_mfma_f32_16x16x32_bf16 v[80:83], v[136:139], v[168:171], v[80:83]
	v_mfma_f32_16x16x32_bf16 v[72:75], v[128:131], v[160:163], v[72:75]
	v_mfma_f32_16x16x32_bf16 v[64:67], v[136:139], v[160:163], v[64:67]
	v_mfma_f32_16x16x32_bf16 v[120:123], v[132:135], v[188:191], v[120:123]
	v_mfma_f32_16x16x32_bf16 v[112:115], v[140:143], v[188:191], v[112:115]
	v_mfma_f32_16x16x32_bf16 v[104:107], v[132:135], v[180:183], v[104:107]
	v_mfma_f32_16x16x32_bf16 v[96:99], v[140:143], v[180:183], v[96:99]
	v_mfma_f32_16x16x32_bf16 v[88:91], v[132:135], v[172:175], v[88:91]
	v_mfma_f32_16x16x32_bf16 v[80:83], v[140:143], v[172:175], v[80:83]
	v_mfma_f32_16x16x32_bf16 v[72:75], v[132:135], v[164:167], v[72:75]
	v_mfma_f32_16x16x32_bf16 v[64:67], v[140:143], v[164:167], v[64:67]
	s_barrier
	s_setprio 0
	s_add_u32 s98, s30, s16
	s_addc_u32 s99, s31, s17
	s_add_u32 s100, s34, s16
	s_addc_u32 s101, s35, s17
	s_mov_b32 m0, s41
	s_add_u32 s38, s30, 0x80000
	ds_read_b128 v[184:187], v226 offset:16384
	ds_read_b128 v[188:191], v226 offset:17408
	ds_read_b128 v[176:179], v226 offset:18432
	ds_read_b128 v[180:183], v226 offset:19456
	ds_read_b128 v[168:171], v226 offset:20480
	ds_read_b128 v[172:175], v226 offset:21504
	ds_read_b128 v[160:163], v226 offset:22528
	ds_read_b128 v[164:167], v226 offset:23552
	global_load_lds_dwordx4 v198, s[30:31]
	s_mov_b32 m0, s42
	s_addc_u32 s39, s31, 0
	global_load_lds_dwordx4 v194, s[30:31]
	s_mov_b32 m0, s43
	s_nop 0
	global_load_lds_dwordx4 v198, s[38:39]
	s_mov_b32 m0, s44
	s_nop 0
	global_load_lds_dwordx4 v194, s[38:39]
	s_mov_b64 s[38:39], -1
	s_mov_b32 m0, s40
	s_and_b64 vcc, exec, s[36:37]
	global_load_lds_dwordx4 v200, s[34:35]
	s_mov_b32 m0, s45
	s_nop 0
	global_load_lds_dwordx4 v196, s[34:35]
	s_cbranch_vccz .LBB0_155
	s_waitcnt vmcnt(8)
	s_mov_b64 s[38:39], 0

; #define PG8_STAGE(bufoff, gbase, voff) do { _Pragma("unroll") for (int _i = 0; _i < 2; ++_i) \
;         __builtin_amdgcn_global_load_lds((const unsigned*)((const char*)(gbase) + (voff)[_i]), (LAS unsigned*)(lds + (bufoff) + ldsw + _i * 8192), 16, 0, ((voff) == voffA ? AUXA : 0)); } while (0)
; #define PG8_LDA(dst, b, h) do { _Pragma("unroll") for (int m = 0; m < 4; ++m) _Pragma("unroll") for (int k = 0; k < 2; ++k) dst[m][k] = *(const LAS bf16x8*)(lds + PG8_SA(b, h) + aoff + m * 2048 + k * 1024); } while (0)
; #define PG8_LDB(dst, b, h) do { _Pragma("unroll") for (int n = 0; n < 2; ++n) _Pragma("unroll") for (int k = 0; k < 2; ++k) dst[n][k] = *(const LAS bf16x8*)(lds + PG8_SB(b, h) + boff + n * 2048 + k * 1024); } while (0)
; #define PG8_MMA(ai, bj, At, Bt) do { __builtin_amdgcn_s_setprio(1); _Pragma("unroll") for (int m = 0; m < 4; ++m) _Pragma("unroll") for (int n = 0; n < 2; ++n) _Pragma("unroll") for (int k = 0; k < 2; ++k) \
;         acc[ai][bj][m][n] = __builtin_amdgcn_mfma_f32_16x16x32_bf16(Bt[n][k], At[m][k], acc[ai][bj][m][n], 0, 0, 0); __builtin_amdgcn_s_setprio(0); } while (0)
; #define PG8_WAIT_V(n) asm volatile("s_waitcnt vmcnt(" #n ")" ::: "memory")
; #define PG8_WAIT_L(n) asm volatile("s_waitcnt lgkmcnt(" #n ")" ::: "memory")
; #define PG8_BAR __builtin_amdgcn_s_barrier()
; #define PG8_SCHED __builtin_amdgcn_sched_barrier(0)
;     ...
;             PG8_LDB(B0, 0, 0); PG8_LDB(B1, 0, 1); PG8_SCHED; PG8_LDA(At, 0, 0); PG8_STAGE(PG8_SA(1, 1), a1 + hsA, voffA);
;             if (Epi::NPRE != 0 && last) { E.pre(sv, cur, wr, fr); PG8_WAIT_V(16); } else { PG8_WAIT_V(8); }
;             PG8_WAIT_L(0); PG8_BAR; PG8_MMA(0, 0, At, B0); PG8_MMA(0, 1, At, B1); PG8_BAR; PG8_SCHED;
;             PG8_LDA(At, 0, 1); PG8_STAGE(PG8_SB(0, 0), b2, voffB); PG8_STAGE(PG8_SB(0, 1), b2 + hsB, voffB); PG8_STAGE(PG8_SA(0, 0), a2, voffA);
;             if (Epi::NPRE != 0 && last) { PG8_WAIT_V(16); } else { PG8_WAIT_V(8); }
;             PG8_WAIT_L(0); PG8_BAR; PG8_MMA(1, 0, At, B0); PG8_MMA(1, 1, At, B1); PG8_BAR; PG8_SCHED;
.LBB0_246:
	ds_read_b128 v[144:147], v208
	ds_read_b128 v[148:151], v208 offset:1024
	ds_read_b128 v[152:155], v208 offset:2048
	ds_read_b128 v[156:159], v208 offset:3072
	ds_read_b128 v[160:163], v209
	ds_read_b128 v[164:167], v209 offset:1024
	ds_read_b128 v[168:171], v209 offset:2048
	ds_read_b128 v[172:175], v209 offset:3072
	s_add_i32 s52, s26, 2
	s_add_u32 s27, s24, 0xffea0080
	s_addc_u32 s28, s25, -1
	s_cmp_eq_u32 s41, s26
	s_cselect_b32 s26, s22, s50
	s_cselect_b32 s29, s11, s28
	s_cselect_b32 s28, s10, s27
	s_cselect_b32 s27, s23, s51
	s_add_i32 m0, s30, 0xc000
	ds_read_b128 v[176:179], v210
	ds_read_b128 v[180:183], v210 offset:1024
	ds_read_b128 v[184:187], v210 offset:2048
	ds_read_b128 v[188:191], v210 offset:3072
	ds_read_b128 v[194:197], v210 offset:4096
	ds_read_b128 v[198:201], v210 offset:5120
	ds_read_b128 v[202:205], v210 offset:6144
	ds_read_b128 v[212:215], v210 offset:7168
	global_load_lds_dwordx4 v136, s[24:25]
	s_add_i32 m0, s30, 0xe000
	s_nop 0
	global_load_lds_dwordx4 v138, s[24:25]
	s_waitcnt vmcnt(8)
	s_waitcnt lgkmcnt(0)
	s_setprio 1
	s_barrier
	v_mfma_f32_16x16x32_bf16 v[124:127], v[144:147], v[176:179], v[124:127]
	v_mfma_f32_16x16x32_bf16 v[120:123], v[152:155], v[176:179], v[120:123]
	v_mfma_f32_16x16x32_bf16 v[116:119], v[144:147], v[184:187], v[116:119]
	v_mfma_f32_16x16x32_bf16 v[112:115], v[152:155], v[184:187], v[112:115]
	v_mfma_f32_16x16x32_bf16 v[104:107], v[144:147], v[194:197], v[104:107]
	v_mfma_f32_16x16x32_bf16 v[96:99], v[152:155], v[194:197], v[96:99]
	v_mfma_f32_16x16x32_bf16 v[88:91], v[144:147], v[202:205], v[88:91]
	v_mfma_f32_16x16x32_bf16 v[80:83], v[152:155], v[202:205], v[80:83]
	v_mfma_f32_16x16x32_bf16 v[124:127], v[148:151], v[180:183], v[124:127]
	v_mfma_f32_16x16x32_bf16 v[120:123], v[156:159], v[180:183], v[120:123]
	v_mfma_f32_16x16x32_bf16 v[116:119], v[148:151], v[188:191], v[116:119]
	v_mfma_f32_16x16x32_bf16 v[112:115], v[156:159], v[188:191], v[112:115]
	v_mfma_f32_16x16x32_bf16 v[104:107], v[148:151], v[198:201], v[104:107]
	v_mfma_f32_16x16x32_bf16 v[96:99], v[156:159], v[198:201], v[96:99]
	v_mfma_f32_16x16x32_bf16 v[88:91], v[148:151], v[212:215], v[88:91]
	v_mfma_f32_16x16x32_bf16 v[80:83], v[156:159], v[212:215], v[80:83]
	v_mfma_f32_16x16x32_bf16 v[108:111], v[160:163], v[176:179], v[108:111]
	v_mfma_f32_16x16x32_bf16 v[100:103], v[168:171], v[176:179], v[100:103]
	v_mfma_f32_16x16x32_bf16 v[92:95], v[160:163], v[184:187], v[92:95]
	v_mfma_f32_16x16x32_bf16 v[84:87], v[168:171], v[184:187], v[84:87]
	v_mfma_f32_16x16x32_bf16 v[76:79], v[160:163], v[194:197], v[76:79]
	v_mfma_f32_16x16x32_bf16 v[72:75], v[168:171], v[194:197], v[72:75]
	v_mfma_f32_16x16x32_bf16 v[68:71], v[160:163], v[202:205], v[68:71]
	v_mfma_f32_16x16x32_bf16 v[64:67], v[168:171], v[202:205], v[64:67]
	v_mfma_f32_16x16x32_bf16 v[108:111], v[164:167], v[180:183], v[108:111]
	v_mfma_f32_16x16x32_bf16 v[100:103], v[172:175], v[180:183], v[100:103]
	v_mfma_f32_16x16x32_bf16 v[92:95], v[164:167], v[188:191], v[92:95]
	v_mfma_f32_16x16x32_bf16 v[84:87], v[172:175], v[188:191], v[84:87]
	v_mfma_f32_16x16x32_bf16 v[76:79], v[164:167], v[198:201], v[76:79]
	v_mfma_f32_16x16x32_bf16 v[72:75], v[172:175], v[198:201], v[72:75]
	v_mfma_f32_16x16x32_bf16 v[68:71], v[164:167], v[212:215], v[68:71]
	v_mfma_f32_16x16x32_bf16 v[64:67], v[172:175], v[212:215], v[64:67]
	s_barrier
	s_setprio 0
	s_add_u32 s98, s26, s16
	s_addc_u32 s99, s27, s17
	s_add_u32 s100, s28, s16
	s_addc_u32 s101, s29, s17
	s_add_i32 s53, s44, s5
	s_mov_b32 m0, s53
	ds_read_b128 v[176:179], v210 offset:16384
	ds_read_b128 v[180:183], v210 offset:17408
	ds_read_b128 v[184:187], v210 offset:18432
	ds_read_b128 v[188:191], v210 offset:19456
	ds_read_b128 v[194:197], v210 offset:20480
	ds_read_b128 v[198:201], v210 offset:21504
	ds_read_b128 v[202:205], v210 offset:22528
	ds_read_b128 v[212:215], v210 offset:23552
	global_load_lds_dwordx4 v130, s[26:27]
	s_add_i32 m0, s53, 0x2000
	s_add_u32 s54, s26, 0x160000
	s_addc_u32 s55, s27, 0
	s_add_i32 s53, s45, s5
	global_load_lds_dwordx4 v134, s[26:27]
	s_mov_b32 m0, s53
	s_nop 0
	global_load_lds_dwordx4 v130, s[54:55]
	s_add_i32 m0, s53, 0x2000
	s_nop 0
	global_load_lds_dwordx4 v134, s[54:55]
	s_mov_b32 m0, s30
	s_nop 0
	global_load_lds_dwordx4 v128, s[28:29]
	s_mov_b32 m0, s31
	s_nop 0
	global_load_lds_dwordx4 v132, s[28:29]
	s_waitcnt vmcnt(8)
	s_waitcnt lgkmcnt(0)
	s_setprio 1
	s_barrier
	v_mfma_f32_16x16x32_bf16 v[60:63], v[144:147], v[176:179], v[60:63]
	v_mfma_f32_16x16x32_bf16 v[56:59], v[152:155], v[176:179], v[56:59]
	v_mfma_f32_16x16x32_bf16 v[52:55], v[144:147], v[184:187], v[52:55]
	v_mfma_f32_16x16x32_bf16 v[48:51], v[152:155], v[184:187], v[48:51]
	v_mfma_f32_16x16x32_bf16 v[40:43], v[144:147], v[194:197], v[40:43]
	v_mfma_f32_16x16x32_bf16 v[32:35], v[152:155], v[194:197], v[32:35]
	v_mfma_f32_16x16x32_bf16 v[24:27], v[144:147], v[202:205], v[24:27]
	v_mfma_f32_16x16x32_bf16 v[16:19], v[152:155], v[202:205], v[16:19]
	v_mfma_f32_16x16x32_bf16 v[60:63], v[148:151], v[180:183], v[60:63]
	v_mfma_f32_16x16x32_bf16 v[56:59], v[156:159], v[180:183], v[56:59]
	v_mfma_f32_16x16x32_bf16 v[52:55], v[148:151], v[188:191], v[52:55]
	v_mfma_f32_16x16x32_bf16 v[48:51], v[156:159], v[188:191], v[48:51]
	v_mfma_f32_16x16x32_bf16 v[40:43], v[148:151], v[198:201], v[40:43]
	v_mfma_f32_16x16x32_bf16 v[32:35], v[156:159], v[198:201], v[32:35]
	v_mfma_f32_16x16x32_bf16 v[24:27], v[148:151], v[212:215], v[24:27]
	v_mfma_f32_16x16x32_bf16 v[16:19], v[156:159], v[212:215], v[16:19]
	v_mfma_f32_16x16x32_bf16 v[44:47], v[160:163], v[176:179], v[44:47]
	v_mfma_f32_16x16x32_bf16 v[36:39], v[168:171], v[176:179], v[36:39]
	v_mfma_f32_16x16x32_bf16 v[28:31], v[160:163], v[184:187], v[28:31]
	v_mfma_f32_16x16x32_bf16 v[20:23], v[168:171], v[184:187], v[20:23]
	v_mfma_f32_16x16x32_bf16 v[12:15], v[160:163], v[194:197], v[12:15]
	v_mfma_f32_16x16x32_bf16 v[8:11], v[168:171], v[194:197], v[8:11]
	v_mfma_f32_16x16x32_bf16 v[4:7], v[160:163], v[202:205], v[4:7]
	v_mfma_f32_16x16x32_bf16 v[0:3], v[168:171], v[202:205], v[0:3]
	v_mfma_f32_16x16x32_bf16 v[44:47], v[164:167], v[180:183], v[44:47]
	v_mfma_f32_16x16x32_bf16 v[36:39], v[172:175], v[180:183], v[36:39]
	v_mfma_f32_16x16x32_bf16 v[28:31], v[164:167], v[188:191], v[28:31]
	v_mfma_f32_16x16x32_bf16 v[20:23], v[172:175], v[188:191], v[20:23]
	v_mfma_f32_16x16x32_bf16 v[12:15], v[164:167], v[198:201], v[12:15]
	v_mfma_f32_16x16x32_bf16 v[8:11], v[172:175], v[198:201], v[8:11]
	v_mfma_f32_16x16x32_bf16 v[4:7], v[164:167], v[212:215], v[4:7]
	v_mfma_f32_16x16x32_bf16 v[0:3], v[172:175], v[212:215], v[0:3]
	s_barrier
; #define PG8_STAGE(bufoff, gbase, voff) do { _Pragma("unroll") for (int _i = 0; _i < 2; ++_i) \
;         __builtin_amdgcn_global_load_lds((const unsigned*)((const char*)(gbase) + (voff)[_i]), (LAS unsigned*)(lds + (bufoff) + ldsw + _i * 8192), 16, 0, ((voff) == voffA ? AUXA : 0)); } while (0)
; #define PG8_LDA(dst, b, h) do { _Pragma("unroll") for (int m = 0; m < 4; ++m) _Pragma("unroll") for (int k = 0; k < 2; ++k) dst[m][k] = *(const LAS bf16x8*)(lds + PG8_SA(b, h) + aoff + m * 2048 + k * 1024); } while (0)
; #define PG8_LDB(dst, b, h) do { _Pragma("unroll") for (int n = 0; n < 2; ++n) _Pragma("unroll") for (int k = 0; k < 2; ++k) dst[n][k] = *(const LAS bf16x8*)(lds + PG8_SB(b, h) + boff + n * 2048 + k * 1024); } while (0)
; #define PG8_MMA(ai, bj, At, Bt) do { __builtin_amdgcn_s_setprio(1); _Pragma("unroll") for (int m = 0; m < 4; ++m) _Pragma("unroll") for (int n = 0; n < 2; ++n) _Pragma("unroll") for (int k = 0; k < 2; ++k) \
;         acc[ai][bj][m][n] = __builtin_amdgcn_mfma_f32_16x16x32_bf16(Bt[n][k], At[m][k], acc[ai][bj][m][n], 0, 0, 0); __builtin_amdgcn_s_setprio(0); } while (0)
; #define PG8_WAIT_V(n) asm volatile("s_waitcnt vmcnt(" #n ")" ::: "memory")
; #define PG8_WAIT_L(n) asm volatile("s_waitcnt lgkmcnt(" #n ")" ::: "memory")
; #define PG8_BAR __builtin_amdgcn_s_barrier()
; #define PG8_SCHED __builtin_amdgcn_sched_barrier(0)
;     ...
;             PG8_LDB(B0, 1, 0); PG8_LDB(B1, 1, 1); PG8_SCHED; PG8_LDA(At, 1, 0); PG8_STAGE(PG8_SA(0, 1), a2 + hsA, voffA);
;             PG8_WAIT_V(8); PG8_WAIT_L(0); PG8_BAR; PG8_MMA(0, 0, At, B0); PG8_MMA(0, 1, At, B1); PG8_BAR; PG8_SCHED;
;             PG8_LDA(At, 1, 1); PG8_STAGE(PG8_SB(1, 0), b3, voffB); PG8_STAGE(PG8_SB(1, 1), b3 + hsB, voffB); PG8_STAGE(PG8_SA(1, 0), a3, voffA);
	s_setprio 0
	s_add_i32 s53, 0, 0x18000
	s_add_i32 s54, 0, 0x1c000
	v_add_u32_e32 v156, s53, v206
	v_add_u32_e32 v172, s54, v206
	ds_read_b128 v[144:147], v156
	ds_read_b128 v[148:151], v156 offset:1024
	ds_read_b128 v[152:155], v156 offset:2048
	ds_read_b128 v[156:159], v156 offset:3072
	ds_read_b128 v[160:163], v172
	ds_read_b128 v[164:167], v172 offset:1024
	ds_read_b128 v[168:171], v172 offset:2048
	ds_read_b128 v[172:175], v172 offset:3072
	s_add_u32 s28, s28, 0x160000
	s_addc_u32 s29, s29, 0
	s_mov_b32 m0, s34
	ds_read_b128 v[176:179], v210 offset:32768
	ds_read_b128 v[180:183], v210 offset:33792
	ds_read_b128 v[184:187], v210 offset:34816
	ds_read_b128 v[188:191], v210 offset:35840
	ds_read_b128 v[194:197], v210 offset:36864
	ds_read_b128 v[198:201], v210 offset:37888
	ds_read_b128 v[202:205], v210 offset:38912
	ds_read_b128 v[212:215], v210 offset:39936
	global_load_lds_dwordx4 v128, s[28:29]
	s_mov_b32 m0, s35
	s_nop 0
	global_load_lds_dwordx4 v132, s[28:29]
	s_waitcnt vmcnt(8)
	s_waitcnt lgkmcnt(0)
	s_setprio 1
	s_barrier
	v_mfma_f32_16x16x32_bf16 v[124:127], v[144:147], v[176:179], v[124:127]
	v_mfma_f32_16x16x32_bf16 v[120:123], v[152:155], v[176:179], v[120:123]
	v_mfma_f32_16x16x32_bf16 v[116:119], v[144:147], v[184:187], v[116:119]
	v_mfma_f32_16x16x32_bf16 v[112:115], v[152:155], v[184:187], v[112:115]
	v_mfma_f32_16x16x32_bf16 v[104:107], v[144:147], v[194:197], v[104:107]
	v_mfma_f32_16x16x32_bf16 v[96:99], v[152:155], v[194:197], v[96:99]
	v_mfma_f32_16x16x32_bf16 v[88:91], v[144:147], v[202:205], v[88:91]
	v_mfma_f32_16x16x32_bf16 v[80:83], v[152:155], v[202:205], v[80:83]
	v_mfma_f32_16x16x32_bf16 v[124:127], v[148:151], v[180:183], v[124:127]
	v_mfma_f32_16x16x32_bf16 v[120:123], v[156:159], v[180:183], v[120:123]
	v_mfma_f32_16x16x32_bf16 v[116:119], v[148:151], v[188:191], v[116:119]
	v_mfma_f32_16x16x32_bf16 v[112:115], v[156:159], v[188:191], v[112:115]
	v_mfma_f32_16x16x32_bf16 v[104:107], v[148:151], v[198:201], v[104:107]
	v_mfma_f32_16x16x32_bf16 v[96:99], v[156:159], v[198:201], v[96:99]
	v_mfma_f32_16x16x32_bf16 v[88:91], v[148:151], v[212:215], v[88:91]
	v_mfma_f32_16x16x32_bf16 v[80:83], v[156:159], v[212:215], v[80:83]
	v_mfma_f32_16x16x32_bf16 v[108:111], v[160:163], v[176:179], v[108:111]
	v_mfma_f32_16x16x32_bf16 v[100:103], v[168:171], v[176:179], v[100:103]
	v_mfma_f32_16x16x32_bf16 v[92:95], v[160:163], v[184:187], v[92:95]
	v_mfma_f32_16x16x32_bf16 v[84:87], v[168:171], v[184:187], v[84:87]
	v_mfma_f32_16x16x32_bf16 v[76:79], v[160:163], v[194:197], v[76:79]
	v_mfma_f32_16x16x32_bf16 v[72:75], v[168:171], v[194:197], v[72:75]
	v_mfma_f32_16x16x32_bf16 v[68:71], v[160:163], v[202:205], v[68:71]
	v_mfma_f32_16x16x32_bf16 v[64:67], v[168:171], v[202:205], v[64:67]
	v_mfma_f32_16x16x32_bf16 v[108:111], v[164:167], v[180:183], v[108:111]
	v_mfma_f32_16x16x32_bf16 v[100:103], v[172:175], v[180:183], v[100:103]
	v_mfma_f32_16x16x32_bf16 v[92:95], v[164:167], v[188:191], v[92:95]
	v_mfma_f32_16x16x32_bf16 v[84:87], v[172:175], v[188:191], v[84:87]
	v_mfma_f32_16x16x32_bf16 v[76:79], v[164:167], v[198:201], v[76:79]
	v_mfma_f32_16x16x32_bf16 v[72:75], v[172:175], v[198:201], v[72:75]
	v_mfma_f32_16x16x32_bf16 v[68:71], v[164:167], v[212:215], v[68:71]
	v_mfma_f32_16x16x32_bf16 v[64:67], v[172:175], v[212:215], v[64:67]
	s_barrier
	s_setprio 0
	s_add_i32 s28, s53, s5
	s_mov_b32 m0, s28
	ds_read_b128 v[176:179], v210 offset:49152
	ds_read_b128 v[180:183], v210 offset:50176
	ds_read_b128 v[184:187], v210 offset:51200
	ds_read_b128 v[188:191], v210 offset:52224
	ds_read_b128 v[194:197], v210 offset:53248
	ds_read_b128 v[198:201], v210 offset:54272
	ds_read_b128 v[202:205], v210 offset:55296
	ds_read_b128 v[212:215], v210 offset:56320
	global_load_lds_dwordx4 v130, s[98:99]
	s_add_i32 m0, s28, 0x2000
	s_add_u32 s26, s26, 0x160080
	s_addc_u32 s27, s27, 0
	s_add_i32 s28, s54, s5
	global_load_lds_dwordx4 v134, s[98:99]
	s_mov_b32 m0, s28
	s_nop 0
	global_load_lds_dwordx4 v130, s[26:27]
	s_add_i32 m0, s28, 0x2000
	s_nop 0
	global_load_lds_dwordx4 v134, s[26:27]
	s_mov_b32 m0, s39
	s_nop 0
	global_load_lds_dwordx4 v128, s[100:101]
	s_mov_b32 m0, s40
	s_nop 0
	global_load_lds_dwordx4 v132, s[100:101]
	s_waitcnt vmcnt(8)
	s_waitcnt lgkmcnt(0)
	s_setprio 1
	s_barrier
; #define PG8_MMA(ai, bj, At, Bt) do { __builtin_amdgcn_s_setprio(1); _Pragma("unroll") for (int m = 0; m < 4; ++m) _Pragma("unroll") for (int n = 0; n < 2; ++n) _Pragma("unroll") for (int k = 0; k < 2; ++k) \
;         acc[ai][bj][m][n] = __builtin_amdgcn_mfma_f32_16x16x32_bf16(Bt[n][k], At[m][k], acc[ai][bj][m][n], 0, 0, 0); __builtin_amdgcn_s_setprio(0); } while (0)
; #define PG8_WAIT_V(n) asm volatile("s_waitcnt vmcnt(" #n ")" ::: "memory")
; #define PG8_WAIT_L(n) asm volatile("s_waitcnt lgkmcnt(" #n ")" ::: "memory")
; #define PG8_BAR __builtin_amdgcn_s_barrier()
; #define PG8_SCHED __builtin_amdgcn_sched_barrier(0)
;     ...
;             PG8_WAIT_V(8); PG8_WAIT_L(0); PG8_BAR; PG8_MMA(1, 0, At, B0); PG8_MMA(1, 1, At, B1); PG8_BAR; PG8_SCHED;
;         }
;     __device__ __forceinline__ void operator()(const Acc& acc, const Unit& u, int wr, int wc, int fr, int fq, const float (&sv8)[8]) const {
;     ...
;                     const f32x4 y0 = xr[m][bj][0] + acc[ai][bj][m][0] * scale, y1 = xr[m][bj][1] + acc[ai][bj][m][1] * scale;
	v_mfma_f32_16x16x32_bf16 v[60:63], v[144:147], v[176:179], v[60:63]
	v_mfma_f32_16x16x32_bf16 v[56:59], v[152:155], v[176:179], v[56:59]
	v_mfma_f32_16x16x32_bf16 v[52:55], v[144:147], v[184:187], v[52:55]
	v_mfma_f32_16x16x32_bf16 v[48:51], v[152:155], v[184:187], v[48:51]
	v_mfma_f32_16x16x32_bf16 v[40:43], v[144:147], v[194:197], v[40:43]
	v_mfma_f32_16x16x32_bf16 v[32:35], v[152:155], v[194:197], v[32:35]
	v_mfma_f32_16x16x32_bf16 v[24:27], v[144:147], v[202:205], v[24:27]
	v_mfma_f32_16x16x32_bf16 v[16:19], v[152:155], v[202:205], v[16:19]
	v_mfma_f32_16x16x32_bf16 v[60:63], v[148:151], v[180:183], v[60:63]
	v_mfma_f32_16x16x32_bf16 v[56:59], v[156:159], v[180:183], v[56:59]
	v_mfma_f32_16x16x32_bf16 v[52:55], v[148:151], v[188:191], v[52:55]
	v_mfma_f32_16x16x32_bf16 v[48:51], v[156:159], v[188:191], v[48:51]
	v_mfma_f32_16x16x32_bf16 v[40:43], v[148:151], v[198:201], v[40:43]
	v_mfma_f32_16x16x32_bf16 v[32:35], v[156:159], v[198:201], v[32:35]
	v_mfma_f32_16x16x32_bf16 v[24:27], v[148:151], v[212:215], v[24:27]
	v_mfma_f32_16x16x32_bf16 v[16:19], v[156:159], v[212:215], v[16:19]
	v_mfma_f32_16x16x32_bf16 v[44:47], v[160:163], v[176:179], v[44:47]
	v_mfma_f32_16x16x32_bf16 v[36:39], v[168:171], v[176:179], v[36:39]
	v_mfma_f32_16x16x32_bf16 v[28:31], v[160:163], v[184:187], v[28:31]
	v_mfma_f32_16x16x32_bf16 v[20:23], v[168:171], v[184:187], v[20:23]
	v_mfma_f32_16x16x32_bf16 v[12:15], v[160:163], v[194:197], v[12:15]
	v_mfma_f32_16x16x32_bf16 v[8:11], v[168:171], v[194:197], v[8:11]
	v_mfma_f32_16x16x32_bf16 v[4:7], v[160:163], v[202:205], v[4:7]
	v_mfma_f32_16x16x32_bf16 v[0:3], v[168:171], v[202:205], v[0:3]
	v_mfma_f32_16x16x32_bf16 v[44:47], v[164:167], v[180:183], v[44:47]
	v_mfma_f32_16x16x32_bf16 v[36:39], v[172:175], v[180:183], v[36:39]
	v_mfma_f32_16x16x32_bf16 v[28:31], v[164:167], v[188:191], v[28:31]
	v_mfma_f32_16x16x32_bf16 v[20:23], v[172:175], v[188:191], v[20:23]
	v_mfma_f32_16x16x32_bf16 v[12:15], v[164:167], v[198:201], v[12:15]
	v_mfma_f32_16x16x32_bf16 v[8:11], v[172:175], v[198:201], v[8:11]
	v_mfma_f32_16x16x32_bf16 v[4:7], v[164:167], v[212:215], v[4:7]
	v_mfma_f32_16x16x32_bf16 v[0:3], v[172:175], v[212:215], v[0:3]
	s_barrier
	s_setprio 0
	s_add_u32 s24, s24, 0x100
	s_addc_u32 s25, s25, 0
	s_add_u32 s50, s50, 0x100
	s_addc_u32 s51, s51, 0
	s_cmp_ge_i32 s52, s38
	s_mov_b32 s26, s52
	s_cbranch_scc0 .LBB0_246
	v_pk_mul_f32 v[178:179], v[126:127], 0.5 op_sel_hi:[1,0]
	v_pk_mul_f32 v[184:185], v[124:125], 0.5 op_sel_hi:[1,0]
	v_pk_mul_f32 v[182:183], v[122:123], 0.5 op_sel_hi:[1,0]
	v_pk_mul_f32 v[180:181], v[120:121], 0.5 op_sel_hi:[1,0]
	v_pk_mul_f32 v[194:195], v[110:111], 0.5 op_sel_hi:[1,0]
	v_pk_mul_f32 v[190:191], v[108:109], 0.5 op_sel_hi:[1,0]
	v_pk_mul_f32 v[188:189], v[102:103], 0.5 op_sel_hi:[1,0]
	v_pk_mul_f32 v[186:187], v[100:101], 0.5 op_sel_hi:[1,0]
	v_pk_mul_f32 v[168:169], v[118:119], 0.5 op_sel_hi:[1,0]
	v_pk_mul_f32 v[166:167], v[116:117], 0.5 op_sel_hi:[1,0]
	v_pk_mul_f32 v[164:165], v[114:115], 0.5 op_sel_hi:[1,0]
	v_pk_mul_f32 v[162:163], v[112:113], 0.5 op_sel_hi:[1,0]
	v_pk_mul_f32 v[176:177], v[94:95], 0.5 op_sel_hi:[1,0]
	v_pk_mul_f32 v[174:175], v[92:93], 0.5 op_sel_hi:[1,0]
	v_pk_mul_f32 v[172:173], v[86:87], 0.5 op_sel_hi:[1,0]
	v_pk_mul_f32 v[170:171], v[84:85], 0.5 op_sel_hi:[1,0]
	v_pk_mul_f32 v[152:153], v[106:107], 0.5 op_sel_hi:[1,0]
	v_pk_mul_f32 v[150:151], v[104:105], 0.5 op_sel_hi:[1,0]
	v_pk_mul_f32 v[148:149], v[98:99], 0.5 op_sel_hi:[1,0]
	v_pk_mul_f32 v[146:147], v[96:97], 0.5 op_sel_hi:[1,0]
	v_pk_mul_f32 v[160:161], v[78:79], 0.5 op_sel_hi:[1,0]
	v_pk_mul_f32 v[158:159], v[76:77], 0.5 op_sel_hi:[1,0]
	v_pk_mul_f32 v[156:157], v[74:75], 0.5 op_sel_hi:[1,0]
	v_pk_mul_f32 v[154:155], v[72:73], 0.5 op_sel_hi:[1,0]
	v_pk_mul_f32 v[120:121], v[90:91], 0.5 op_sel_hi:[1,0]
	v_pk_mul_f32 v[118:119], v[88:89], 0.5 op_sel_hi:[1,0]
	v_pk_mul_f32 v[116:117], v[82:83], 0.5 op_sel_hi:[1,0]
	v_pk_mul_f32 v[114:115], v[80:81], 0.5 op_sel_hi:[1,0]
	v_pk_mul_f32 v[144:145], v[70:71], 0.5 op_sel_hi:[1,0]
	v_pk_mul_f32 v[126:127], v[68:69], 0.5 op_sel_hi:[1,0]
	v_pk_mul_f32 v[124:125], v[66:67], 0.5 op_sel_hi:[1,0]
	v_pk_mul_f32 v[122:123], v[64:65], 0.5 op_sel_hi:[1,0]
	v_pk_mul_f32 v[102:103], v[62:63], 0.5 op_sel_hi:[1,0]
	v_pk_mul_f32 v[100:101], v[60:61], 0.5 op_sel_hi:[1,0]
	v_pk_mul_f32 v[98:99], v[58:59], 0.5 op_sel_hi:[1,0]
	v_pk_mul_f32 v[96:97], v[56:57], 0.5 op_sel_hi:[1,0]
	v_pk_mul_f32 v[110:111], v[46:47], 0.5 op_sel_hi:[1,0]
	v_pk_mul_f32 v[108:109], v[44:45], 0.5 op_sel_hi:[1,0]
	v_pk_mul_f32 v[106:107], v[38:39], 0.5 op_sel_hi:[1,0]
	v_pk_mul_f32 v[104:105], v[36:37], 0.5 op_sel_hi:[1,0]
	v_pk_mul_f32 v[86:87], v[54:55], 0.5 op_sel_hi:[1,0]
	v_pk_mul_f32 v[84:85], v[52:53], 0.5 op_sel_hi:[1,0]
	v_pk_mul_f32 v[82:83], v[50:51], 0.5 op_sel_hi:[1,0]
	v_pk_mul_f32 v[80:81], v[48:49], 0.5 op_sel_hi:[1,0]
	v_pk_mul_f32 v[94:95], v[30:31], 0.5 op_sel_hi:[1,0]
	v_pk_mul_f32 v[92:93], v[28:29], 0.5 op_sel_hi:[1,0]
	v_pk_mul_f32 v[90:91], v[22:23], 0.5 op_sel_hi:[1,0]
	v_pk_mul_f32 v[88:89], v[20:21], 0.5 op_sel_hi:[1,0]
	v_pk_mul_f32 v[70:71], v[42:43], 0.5 op_sel_hi:[1,0]
	v_pk_mul_f32 v[68:69], v[40:41], 0.5 op_sel_hi:[1,0]
	v_pk_mul_f32 v[66:67], v[34:35], 0.5 op_sel_hi:[1,0]
	v_pk_mul_f32 v[64:65], v[32:33], 0.5 op_sel_hi:[1,0]
	v_pk_mul_f32 v[78:79], v[14:15], 0.5 op_sel_hi:[1,0]
	v_pk_mul_f32 v[76:77], v[12:13], 0.5 op_sel_hi:[1,0]
	v_pk_mul_f32 v[74:75], v[10:11], 0.5 op_sel_hi:[1,0]
	v_pk_mul_f32 v[72:73], v[8:9], 0.5 op_sel_hi:[1,0]
	v_pk_mul_f32 v[54:55], v[26:27], 0.5 op_sel_hi:[1,0]
	v_pk_mul_f32 v[52:53], v[24:25], 0.5 op_sel_hi:[1,0]
	v_pk_mul_f32 v[50:51], v[18:19], 0.5 op_sel_hi:[1,0]
	v_pk_mul_f32 v[48:49], v[16:17], 0.5 op_sel_hi:[1,0]
	v_pk_mul_f32 v[62:63], v[6:7], 0.5 op_sel_hi:[1,0]
	v_pk_mul_f32 v[60:61], v[4:5], 0.5 op_sel_hi:[1,0]
	v_pk_mul_f32 v[58:59], v[2:3], 0.5 op_sel_hi:[1,0]
	v_pk_mul_f32 v[56:57], v[0:1], 0.5 op_sel_hi:[1,0]

; #define PG8_STAGE(bufoff, gbase, voff) do { _Pragma("unroll") for (int _i = 0; _i < 2; ++_i) \
;         __builtin_amdgcn_global_load_lds((const unsigned*)((const char*)(gbase) + (voff)[_i]), (LAS unsigned*)(lds + (bufoff) + ldsw + _i * 8192), 16, 0, ((voff) == voffA ? AUXA : 0)); } while (0)
; #define PG8_LDA(dst, b, h) do { _Pragma("unroll") for (int m = 0; m < 4; ++m) _Pragma("unroll") for (int k = 0; k < 2; ++k) dst[m][k] = *(const LAS bf16x8*)(lds + PG8_SA(b, h) + aoff + m * 2048 + k * 1024); } while (0)
; #define PG8_LDB(dst, b, h) do { _Pragma("unroll") for (int n = 0; n < 2; ++n) _Pragma("unroll") for (int k = 0; k < 2; ++k) dst[n][k] = *(const LAS bf16x8*)(lds + PG8_SB(b, h) + boff + n * 2048 + k * 1024); } while (0)
; #define PG8_MMA(ai, bj, At, Bt) do { __builtin_amdgcn_s_setprio(1); _Pragma("unroll") for (int m = 0; m < 4; ++m) _Pragma("unroll") for (int n = 0; n < 2; ++n) _Pragma("unroll") for (int k = 0; k < 2; ++k) \
;         acc[ai][bj][m][n] = __builtin_amdgcn_mfma_f32_16x16x32_bf16(Bt[n][k], At[m][k], acc[ai][bj][m][n], 0, 0, 0); __builtin_amdgcn_s_setprio(0); } while (0)
; #define PG8_WAIT_V(n) asm volatile("s_waitcnt vmcnt(" #n ")" ::: "memory")
; #define PG8_WAIT_L(n) asm volatile("s_waitcnt lgkmcnt(" #n ")" ::: "memory")
; #define PG8_BAR __builtin_amdgcn_s_barrier()
; #define PG8_SCHED __builtin_amdgcn_sched_barrier(0)
;     ...
;             PG8_WAIT_L(0); PG8_BAR; PG8_MMA(1, 0, At, B0); PG8_MMA(1, 1, At, B1); PG8_BAR; PG8_SCHED;
;             PG8_LDB(B0, 1, 0); PG8_LDB(B1, 1, 1); PG8_SCHED; PG8_LDA(At, 1, 0); PG8_STAGE(PG8_SA(0, 1), a2 + hsA, voffA);
;             PG8_WAIT_V(8); PG8_WAIT_L(0); PG8_BAR; PG8_MMA(0, 0, At, B0); PG8_MMA(0, 1, At, B1); PG8_BAR; PG8_SCHED;
.LBB0_370:
	s_waitcnt lgkmcnt(0)
	s_add_i32 s71, s71, 2
	s_setprio 1
	s_barrier
	v_mfma_f32_16x16x32_bf16 v[60:63], v[144:147], v[184:187], v[60:63]
	v_mfma_f32_16x16x32_bf16 v[56:59], v[152:155], v[184:187], v[56:59]
	v_mfma_f32_16x16x32_bf16 v[44:47], v[144:147], v[176:179], v[44:47]
	v_mfma_f32_16x16x32_bf16 v[40:43], v[152:155], v[176:179], v[40:43]
	v_mfma_f32_16x16x32_bf16 v[28:31], v[144:147], v[168:171], v[28:31]
	v_mfma_f32_16x16x32_bf16 v[24:27], v[152:155], v[168:171], v[24:27]
	v_mfma_f32_16x16x32_bf16 v[12:15], v[144:147], v[160:163], v[12:15]
	v_mfma_f32_16x16x32_bf16 v[8:11], v[152:155], v[160:163], v[8:11]
	v_mfma_f32_16x16x32_bf16 v[60:63], v[148:151], v[188:191], v[60:63]
	v_mfma_f32_16x16x32_bf16 v[56:59], v[156:159], v[188:191], v[56:59]
	v_mfma_f32_16x16x32_bf16 v[44:47], v[148:151], v[180:183], v[44:47]
	v_mfma_f32_16x16x32_bf16 v[40:43], v[156:159], v[180:183], v[40:43]
	v_mfma_f32_16x16x32_bf16 v[28:31], v[148:151], v[172:175], v[28:31]
	v_mfma_f32_16x16x32_bf16 v[24:27], v[156:159], v[172:175], v[24:27]
	v_mfma_f32_16x16x32_bf16 v[12:15], v[148:151], v[164:167], v[12:15]
	v_mfma_f32_16x16x32_bf16 v[8:11], v[156:159], v[164:167], v[8:11]
	v_mfma_f32_16x16x32_bf16 v[52:55], v[128:131], v[184:187], v[52:55]
	v_mfma_f32_16x16x32_bf16 v[48:51], v[136:139], v[184:187], v[48:51]
	v_mfma_f32_16x16x32_bf16 v[36:39], v[128:131], v[176:179], v[36:39]
	v_mfma_f32_16x16x32_bf16 v[32:35], v[136:139], v[176:179], v[32:35]
	v_mfma_f32_16x16x32_bf16 v[20:23], v[128:131], v[168:171], v[20:23]
	v_mfma_f32_16x16x32_bf16 v[16:19], v[136:139], v[168:171], v[16:19]
	v_mfma_f32_16x16x32_bf16 v[4:7], v[128:131], v[160:163], v[4:7]
	v_mfma_f32_16x16x32_bf16 v[0:3], v[136:139], v[160:163], v[0:3]
	v_mfma_f32_16x16x32_bf16 v[52:55], v[132:135], v[188:191], v[52:55]
	v_mfma_f32_16x16x32_bf16 v[48:51], v[140:143], v[188:191], v[48:51]
	v_mfma_f32_16x16x32_bf16 v[36:39], v[132:135], v[180:183], v[36:39]
	v_mfma_f32_16x16x32_bf16 v[32:35], v[140:143], v[180:183], v[32:35]
	v_mfma_f32_16x16x32_bf16 v[20:23], v[132:135], v[172:175], v[20:23]
	v_mfma_f32_16x16x32_bf16 v[16:19], v[140:143], v[172:175], v[16:19]
	v_mfma_f32_16x16x32_bf16 v[4:7], v[132:135], v[164:167], v[4:7]
	v_mfma_f32_16x16x32_bf16 v[0:3], v[140:143], v[164:167], v[0:3]
	s_barrier
	s_setprio 0
	s_add_i32 s36, 0, 0x18000
	s_add_i32 s37, 0, 0x1c000
	v_add_u32_e32 v140, s36, v235
	v_add_u32_e32 v156, s37, v235
	ds_read_b128 v[128:131], v140
	ds_read_b128 v[132:135], v140 offset:1024
	ds_read_b128 v[136:139], v140 offset:2048
	ds_read_b128 v[140:143], v140 offset:3072
	ds_read_b128 v[144:147], v156
	ds_read_b128 v[148:151], v156 offset:1024
	ds_read_b128 v[152:155], v156 offset:2048
	ds_read_b128 v[156:159], v156 offset:3072
	s_add_u32 s34, s34, 0x80000
	s_addc_u32 s35, s35, 0
	s_mov_b32 m0, s45
	ds_read_b128 v[160:163], v239 offset:32768
	ds_read_b128 v[164:167], v239 offset:33792
	ds_read_b128 v[168:171], v239 offset:34816
	ds_read_b128 v[172:175], v239 offset:35840
	ds_read_b128 v[176:179], v239 offset:36864
	ds_read_b128 v[180:183], v239 offset:37888
	ds_read_b128 v[184:187], v239 offset:38912
	ds_read_b128 v[188:191], v239 offset:39936
	global_load_lds_dwordx4 v194, s[34:35]
	s_mov_b32 m0, s46
	s_nop 0
	global_load_lds_dwordx4 v198, s[34:35]
	s_waitcnt vmcnt(8)
	s_waitcnt lgkmcnt(0)
	s_setprio 1
	s_barrier
; #define PG8_STAGE(bufoff, gbase, voff) do { _Pragma("unroll") for (int _i = 0; _i < 2; ++_i) \
;         __builtin_amdgcn_global_load_lds((const unsigned*)((const char*)(gbase) + (voff)[_i]), (LAS unsigned*)(lds + (bufoff) + ldsw + _i * 8192), 16, 0, ((voff) == voffA ? AUXA : 0)); } while (0)
; #define PG8_LDA(dst, b, h) do { _Pragma("unroll") for (int m = 0; m < 4; ++m) _Pragma("unroll") for (int k = 0; k < 2; ++k) dst[m][k] = *(const LAS bf16x8*)(lds + PG8_SA(b, h) + aoff + m * 2048 + k * 1024); } while (0)
; #define PG8_MMA(ai, bj, At, Bt) do { __builtin_amdgcn_s_setprio(1); _Pragma("unroll") for (int m = 0; m < 4; ++m) _Pragma("unroll") for (int n = 0; n < 2; ++n) _Pragma("unroll") for (int k = 0; k < 2; ++k) \
;         acc[ai][bj][m][n] = __builtin_amdgcn_mfma_f32_16x16x32_bf16(Bt[n][k], At[m][k], acc[ai][bj][m][n], 0, 0, 0); __builtin_amdgcn_s_setprio(0); } while (0)
; #define PG8_WAIT_V(n) asm volatile("s_waitcnt vmcnt(" #n ")" ::: "memory")
; #define PG8_WAIT_L(n) asm volatile("s_waitcnt lgkmcnt(" #n ")" ::: "memory")
; #define PG8_BAR __builtin_amdgcn_s_barrier()
; #define PG8_SCHED __builtin_amdgcn_sched_barrier(0)
;     ...
;             PG8_WAIT_V(8); PG8_WAIT_L(0); PG8_BAR; PG8_MMA(0, 0, At, B0); PG8_MMA(0, 1, At, B1); PG8_BAR; PG8_SCHED;
;             PG8_LDA(At, 1, 1); PG8_STAGE(PG8_SB(1, 0), b3, voffB); PG8_STAGE(PG8_SB(1, 1), b3 + hsB, voffB); PG8_STAGE(PG8_SA(1, 0), a3, voffA);
;             PG8_WAIT_V(8); PG8_WAIT_L(0); PG8_BAR; PG8_MMA(1, 0, At, B0); PG8_MMA(1, 1, At, B1); PG8_BAR; PG8_SCHED;
;         }
	v_mfma_f32_16x16x32_bf16 v[124:127], v[128:131], v[160:163], v[124:127]
	v_mfma_f32_16x16x32_bf16 v[120:123], v[136:139], v[160:163], v[120:123]
	v_mfma_f32_16x16x32_bf16 v[108:111], v[128:131], v[168:171], v[108:111]
	v_mfma_f32_16x16x32_bf16 v[104:107], v[136:139], v[168:171], v[104:107]
	v_mfma_f32_16x16x32_bf16 v[92:95], v[128:131], v[176:179], v[92:95]
	v_mfma_f32_16x16x32_bf16 v[88:91], v[136:139], v[176:179], v[88:91]
	v_mfma_f32_16x16x32_bf16 v[76:79], v[128:131], v[184:187], v[76:79]
	v_mfma_f32_16x16x32_bf16 v[72:75], v[136:139], v[184:187], v[72:75]
	v_mfma_f32_16x16x32_bf16 v[124:127], v[132:135], v[164:167], v[124:127]
	v_mfma_f32_16x16x32_bf16 v[120:123], v[140:143], v[164:167], v[120:123]
	v_mfma_f32_16x16x32_bf16 v[108:111], v[132:135], v[172:175], v[108:111]
	v_mfma_f32_16x16x32_bf16 v[104:107], v[140:143], v[172:175], v[104:107]
	v_mfma_f32_16x16x32_bf16 v[92:95], v[132:135], v[180:183], v[92:95]
	v_mfma_f32_16x16x32_bf16 v[88:91], v[140:143], v[180:183], v[88:91]
	v_mfma_f32_16x16x32_bf16 v[76:79], v[132:135], v[188:191], v[76:79]
	v_mfma_f32_16x16x32_bf16 v[72:75], v[140:143], v[188:191], v[72:75]
	v_mfma_f32_16x16x32_bf16 v[116:119], v[144:147], v[160:163], v[116:119]
	v_mfma_f32_16x16x32_bf16 v[112:115], v[152:155], v[160:163], v[112:115]
	v_mfma_f32_16x16x32_bf16 v[100:103], v[144:147], v[168:171], v[100:103]
	v_mfma_f32_16x16x32_bf16 v[96:99], v[152:155], v[168:171], v[96:99]
	v_mfma_f32_16x16x32_bf16 v[84:87], v[144:147], v[176:179], v[84:87]
	v_mfma_f32_16x16x32_bf16 v[80:83], v[152:155], v[176:179], v[80:83]
	v_mfma_f32_16x16x32_bf16 v[68:71], v[144:147], v[184:187], v[68:71]
	v_mfma_f32_16x16x32_bf16 v[64:67], v[152:155], v[184:187], v[64:67]
	v_mfma_f32_16x16x32_bf16 v[116:119], v[148:151], v[164:167], v[116:119]
	v_mfma_f32_16x16x32_bf16 v[112:115], v[156:159], v[164:167], v[112:115]
	v_mfma_f32_16x16x32_bf16 v[100:103], v[148:151], v[172:175], v[100:103]
	v_mfma_f32_16x16x32_bf16 v[96:99], v[156:159], v[172:175], v[96:99]
	v_mfma_f32_16x16x32_bf16 v[84:87], v[148:151], v[180:183], v[84:87]
	v_mfma_f32_16x16x32_bf16 v[80:83], v[156:159], v[180:183], v[80:83]
	v_mfma_f32_16x16x32_bf16 v[68:71], v[148:151], v[188:191], v[68:71]
	v_mfma_f32_16x16x32_bf16 v[64:67], v[156:159], v[188:191], v[64:67]
	s_barrier
	s_setprio 0
	s_add_i32 s34, s36, s5
	s_mov_b32 m0, s34
	ds_read_b128 v[160:163], v239 offset:49152
	ds_read_b128 v[164:167], v239 offset:50176
	ds_read_b128 v[168:171], v239 offset:51200
	ds_read_b128 v[172:175], v239 offset:52224
	ds_read_b128 v[176:179], v239 offset:53248
	ds_read_b128 v[180:183], v239 offset:54272
	ds_read_b128 v[184:187], v239 offset:55296
	ds_read_b128 v[188:191], v239 offset:56320
	global_load_lds_dwordx4 v196, s[98:99]
	s_add_i32 m0, s34, 0x2000
	s_add_u32 s30, s30, 0x80080
	s_addc_u32 s31, s31, 0
	s_add_i32 s34, s37, s5
	global_load_lds_dwordx4 v200, s[98:99]
	s_mov_b32 m0, s34
	s_nop 0
	global_load_lds_dwordx4 v196, s[30:31]
	s_add_i32 m0, s34, 0x2000
	s_nop 0
	global_load_lds_dwordx4 v200, s[30:31]
	s_mov_b32 m0, s50
	s_nop 0
	global_load_lds_dwordx4 v194, s[100:101]
	s_mov_b32 m0, s51
	s_nop 0
	global_load_lds_dwordx4 v198, s[100:101]
	s_waitcnt vmcnt(8)
	s_waitcnt lgkmcnt(0)
	s_setprio 1
	s_barrier
	v_mfma_f32_16x16x32_bf16 v[60:63], v[128:131], v[160:163], v[60:63]
	v_mfma_f32_16x16x32_bf16 v[56:59], v[136:139], v[160:163], v[56:59]
	v_mfma_f32_16x16x32_bf16 v[44:47], v[128:131], v[168:171], v[44:47]
	v_mfma_f32_16x16x32_bf16 v[40:43], v[136:139], v[168:171], v[40:43]
	v_mfma_f32_16x16x32_bf16 v[28:31], v[128:131], v[176:179], v[28:31]
	v_mfma_f32_16x16x32_bf16 v[24:27], v[136:139], v[176:179], v[24:27]
	v_mfma_f32_16x16x32_bf16 v[12:15], v[128:131], v[184:187], v[12:15]
	v_mfma_f32_16x16x32_bf16 v[8:11], v[136:139], v[184:187], v[8:11]
	v_mfma_f32_16x16x32_bf16 v[60:63], v[132:135], v[164:167], v[60:63]
	v_mfma_f32_16x16x32_bf16 v[56:59], v[140:143], v[164:167], v[56:59]
	v_mfma_f32_16x16x32_bf16 v[44:47], v[132:135], v[172:175], v[44:47]
	v_mfma_f32_16x16x32_bf16 v[40:43], v[140:143], v[172:175], v[40:43]
	v_mfma_f32_16x16x32_bf16 v[28:31], v[132:135], v[180:183], v[28:31]
	v_mfma_f32_16x16x32_bf16 v[24:27], v[140:143], v[180:183], v[24:27]
	v_mfma_f32_16x16x32_bf16 v[12:15], v[132:135], v[188:191], v[12:15]
	v_mfma_f32_16x16x32_bf16 v[8:11], v[140:143], v[188:191], v[8:11]
	v_mfma_f32_16x16x32_bf16 v[52:55], v[144:147], v[160:163], v[52:55]
	v_mfma_f32_16x16x32_bf16 v[48:51], v[152:155], v[160:163], v[48:51]
	v_mfma_f32_16x16x32_bf16 v[36:39], v[144:147], v[168:171], v[36:39]
	v_mfma_f32_16x16x32_bf16 v[32:35], v[152:155], v[168:171], v[32:35]
	v_mfma_f32_16x16x32_bf16 v[20:23], v[144:147], v[176:179], v[20:23]
	v_mfma_f32_16x16x32_bf16 v[16:19], v[152:155], v[176:179], v[16:19]
	v_mfma_f32_16x16x32_bf16 v[4:7], v[144:147], v[184:187], v[4:7]
	v_mfma_f32_16x16x32_bf16 v[0:3], v[152:155], v[184:187], v[0:3]
	v_mfma_f32_16x16x32_bf16 v[52:55], v[148:151], v[164:167], v[52:55]
	v_mfma_f32_16x16x32_bf16 v[48:51], v[156:159], v[164:167], v[48:51]
	v_mfma_f32_16x16x32_bf16 v[36:39], v[148:151], v[172:175], v[36:39]
	v_mfma_f32_16x16x32_bf16 v[32:35], v[156:159], v[172:175], v[32:35]
	v_mfma_f32_16x16x32_bf16 v[20:23], v[148:151], v[180:183], v[20:23]
	v_mfma_f32_16x16x32_bf16 v[16:19], v[156:159], v[180:183], v[16:19]
	v_mfma_f32_16x16x32_bf16 v[4:7], v[148:151], v[188:191], v[4:7]
	v_mfma_f32_16x16x32_bf16 v[0:3], v[156:159], v[188:191], v[0:3]
	s_barrier
	s_setprio 0
	s_add_u32 s28, s28, 0x100
	s_addc_u32 s29, s29, 0
	s_add_u32 s69, s69, 0x100
	s_addc_u32 s70, s70, 0
	s_cmp_ge_i32 s71, s48
	s_cbranch_scc1 .LBB0_380

; #define PG8_STAGE(bufoff, gbase, voff) do { _Pragma("unroll") for (int _i = 0; _i < 2; ++_i) \
;         __builtin_amdgcn_global_load_lds((const unsigned*)((const char*)(gbase) + (voff)[_i]), (LAS unsigned*)(lds + (bufoff) + ldsw + _i * 8192), 16, 0, ((voff) == voffA ? AUXA : 0)); } while (0)
; #define PG8_LDA(dst, b, h) do { _Pragma("unroll") for (int m = 0; m < 4; ++m) _Pragma("unroll") for (int k = 0; k < 2; ++k) dst[m][k] = *(const LAS bf16x8*)(lds + PG8_SA(b, h) + aoff + m * 2048 + k * 1024); } while (0)
; #define PG8_LDB(dst, b, h) do { _Pragma("unroll") for (int n = 0; n < 2; ++n) _Pragma("unroll") for (int k = 0; k < 2; ++k) dst[n][k] = *(const LAS bf16x8*)(lds + PG8_SB(b, h) + boff + n * 2048 + k * 1024); } while (0)
; #define PG8_MMA(ai, bj, At, Bt) do { __builtin_amdgcn_s_setprio(1); _Pragma("unroll") for (int m = 0; m < 4; ++m) _Pragma("unroll") for (int n = 0; n < 2; ++n) _Pragma("unroll") for (int k = 0; k < 2; ++k) \
;         acc[ai][bj][m][n] = __builtin_amdgcn_mfma_f32_16x16x32_bf16(Bt[n][k], At[m][k], acc[ai][bj][m][n], 0, 0, 0); __builtin_amdgcn_s_setprio(0); } while (0)
; #define PG8_WAIT_V(n) asm volatile("s_waitcnt vmcnt(" #n ")" ::: "memory")
; #define PG8_WAIT_L(n) asm volatile("s_waitcnt lgkmcnt(" #n ")" ::: "memory")
; #define PG8_BAR __builtin_amdgcn_s_barrier()
; #define PG8_SCHED __builtin_amdgcn_sched_barrier(0)
;     ...
;             const char* a2 = last ? nA : cA + (size_t)(t + 2) * kstep; const char* b2 = last ? nB : cB + (size_t)(t + 2) * kstep;
;             const char* a3 = a2 + kstep; const char* b3 = b2 + kstep;
;             PG8_LDB(B0, 0, 0); PG8_LDB(B1, 0, 1); PG8_SCHED; PG8_LDA(At, 0, 0); PG8_STAGE(PG8_SA(1, 1), a1 + hsA, voffA);
;             if (Epi::NPRE != 0 && last) { E.pre(sv, cur, wr, fr); PG8_WAIT_V(16); } else { PG8_WAIT_V(8); }
;             PG8_WAIT_L(0); PG8_BAR; PG8_MMA(0, 0, At, B0); PG8_MMA(0, 1, At, B1); PG8_BAR; PG8_SCHED;
;             PG8_LDA(At, 0, 1); PG8_STAGE(PG8_SB(0, 0), b2, voffB); PG8_STAGE(PG8_SB(0, 1), b2 + hsB, voffB); PG8_STAGE(PG8_SA(0, 0), a2, voffA);
;             if (Epi::NPRE != 0 && last) { PG8_WAIT_V(16); } else { PG8_WAIT_V(8); }
.LBB0_375:
	s_add_u32 s34, s28, 0xfff80080
	s_addc_u32 s35, s29, -1
	s_waitcnt lgkmcnt(0)
	s_and_b64 s[30:31], s[30:31], exec
	s_cselect_b32 s35, s7, s35
	s_cselect_b32 s34, s21, s34
	s_cselect_b32 s31, s23, s70
	s_cselect_b32 s30, s68, s69
	s_setprio 1
	s_barrier
	v_mfma_f32_16x16x32_bf16 v[124:127], v[144:147], v[184:187], v[124:127]
	v_mfma_f32_16x16x32_bf16 v[120:123], v[152:155], v[184:187], v[120:123]
	v_mfma_f32_16x16x32_bf16 v[108:111], v[144:147], v[176:179], v[108:111]
	v_mfma_f32_16x16x32_bf16 v[104:107], v[152:155], v[176:179], v[104:107]
	v_mfma_f32_16x16x32_bf16 v[92:95], v[144:147], v[168:171], v[92:95]
	v_mfma_f32_16x16x32_bf16 v[88:91], v[152:155], v[168:171], v[88:91]
	v_mfma_f32_16x16x32_bf16 v[76:79], v[144:147], v[160:163], v[76:79]
	v_mfma_f32_16x16x32_bf16 v[72:75], v[152:155], v[160:163], v[72:75]
	v_mfma_f32_16x16x32_bf16 v[124:127], v[148:151], v[188:191], v[124:127]
	v_mfma_f32_16x16x32_bf16 v[120:123], v[156:159], v[188:191], v[120:123]
	v_mfma_f32_16x16x32_bf16 v[108:111], v[148:151], v[180:183], v[108:111]
	v_mfma_f32_16x16x32_bf16 v[104:107], v[156:159], v[180:183], v[104:107]
	v_mfma_f32_16x16x32_bf16 v[92:95], v[148:151], v[172:175], v[92:95]
	v_mfma_f32_16x16x32_bf16 v[88:91], v[156:159], v[172:175], v[88:91]
	v_mfma_f32_16x16x32_bf16 v[76:79], v[148:151], v[164:167], v[76:79]
	v_mfma_f32_16x16x32_bf16 v[72:75], v[156:159], v[164:167], v[72:75]
	v_mfma_f32_16x16x32_bf16 v[116:119], v[128:131], v[184:187], v[116:119]
	v_mfma_f32_16x16x32_bf16 v[112:115], v[136:139], v[184:187], v[112:115]
	v_mfma_f32_16x16x32_bf16 v[100:103], v[128:131], v[176:179], v[100:103]
	v_mfma_f32_16x16x32_bf16 v[96:99], v[136:139], v[176:179], v[96:99]
	v_mfma_f32_16x16x32_bf16 v[84:87], v[128:131], v[168:171], v[84:87]
	v_mfma_f32_16x16x32_bf16 v[80:83], v[136:139], v[168:171], v[80:83]
	v_mfma_f32_16x16x32_bf16 v[68:71], v[128:131], v[160:163], v[68:71]
	v_mfma_f32_16x16x32_bf16 v[64:67], v[136:139], v[160:163], v[64:67]
	v_mfma_f32_16x16x32_bf16 v[116:119], v[132:135], v[188:191], v[116:119]
	v_mfma_f32_16x16x32_bf16 v[112:115], v[140:143], v[188:191], v[112:115]
	v_mfma_f32_16x16x32_bf16 v[100:103], v[132:135], v[180:183], v[100:103]
	v_mfma_f32_16x16x32_bf16 v[96:99], v[140:143], v[180:183], v[96:99]
	v_mfma_f32_16x16x32_bf16 v[84:87], v[132:135], v[172:175], v[84:87]
	v_mfma_f32_16x16x32_bf16 v[80:83], v[140:143], v[172:175], v[80:83]
	v_mfma_f32_16x16x32_bf16 v[68:71], v[132:135], v[164:167], v[68:71]
	v_mfma_f32_16x16x32_bf16 v[64:67], v[140:143], v[164:167], v[64:67]
	s_barrier
	s_setprio 0
	s_add_u32 s98, s30, s10
	s_addc_u32 s99, s31, s11
	s_add_u32 s100, s34, s10
	s_addc_u32 s101, s35, s11
	s_mov_b32 m0, s40
	s_add_u32 s38, s30, 0x80000
	ds_read_b128 v[184:187], v239 offset:16384
	ds_read_b128 v[188:191], v239 offset:17408
	ds_read_b128 v[176:179], v239 offset:18432
	ds_read_b128 v[180:183], v239 offset:19456
	ds_read_b128 v[168:171], v239 offset:20480
	ds_read_b128 v[172:175], v239 offset:21504
	ds_read_b128 v[160:163], v239 offset:22528
	ds_read_b128 v[164:167], v239 offset:23552
	global_load_lds_dwordx4 v196, s[30:31]
	s_mov_b32 m0, s41
	s_addc_u32 s39, s31, 0
	global_load_lds_dwordx4 v200, s[30:31]
	s_mov_b32 m0, s42
	s_nop 0
	global_load_lds_dwordx4 v196, s[38:39]
	s_mov_b32 m0, s43
	s_nop 0
	global_load_lds_dwordx4 v200, s[38:39]
	s_mov_b64 s[38:39], -1
	s_mov_b32 m0, s13
	s_and_b64 vcc, exec, s[36:37]
	global_load_lds_dwordx4 v194, s[34:35]
	s_mov_b32 m0, s44
	s_nop 0
	global_load_lds_dwordx4 v198, s[34:35]
	s_cbranch_vccz .LBB0_377
	s_waitcnt vmcnt(8)
	s_mov_b64 s[38:39], 0

; #define PG8_STAGE(bufoff, gbase, voff) do { _Pragma("unroll") for (int _i = 0; _i < 2; ++_i) \
;         __builtin_amdgcn_global_load_lds((const unsigned*)((const char*)(gbase) + (voff)[_i]), (LAS unsigned*)(lds + (bufoff) + ldsw + _i * 8192), 16, 0, ((voff) == voffA ? AUXA : 0)); } while (0)
; #define PG8_LDA(dst, b, h) do { _Pragma("unroll") for (int m = 0; m < 4; ++m) _Pragma("unroll") for (int k = 0; k < 2; ++k) dst[m][k] = *(const LAS bf16x8*)(lds + PG8_SA(b, h) + aoff + m * 2048 + k * 1024); } while (0)
; #define PG8_LDB(dst, b, h) do { _Pragma("unroll") for (int n = 0; n < 2; ++n) _Pragma("unroll") for (int k = 0; k < 2; ++k) dst[n][k] = *(const LAS bf16x8*)(lds + PG8_SB(b, h) + boff + n * 2048 + k * 1024); } while (0)
; #define PG8_MMA(ai, bj, At, Bt) do { __builtin_amdgcn_s_setprio(1); _Pragma("unroll") for (int m = 0; m < 4; ++m) _Pragma("unroll") for (int n = 0; n < 2; ++n) _Pragma("unroll") for (int k = 0; k < 2; ++k) \
;         acc[ai][bj][m][n] = __builtin_amdgcn_mfma_f32_16x16x32_bf16(Bt[n][k], At[m][k], acc[ai][bj][m][n], 0, 0, 0); __builtin_amdgcn_s_setprio(0); } while (0)
; #define PG8_WAIT_V(n) asm volatile("s_waitcnt vmcnt(" #n ")" ::: "memory")
; #define PG8_WAIT_L(n) asm volatile("s_waitcnt lgkmcnt(" #n ")" ::: "memory")
; #define PG8_BAR __builtin_amdgcn_s_barrier()
; #define PG8_SCHED __builtin_amdgcn_sched_barrier(0)
;     ...
;             PG8_LDB(B0, 0, 0); PG8_LDB(B1, 0, 1); PG8_SCHED; PG8_LDA(At, 0, 0); PG8_STAGE(PG8_SA(1, 1), a1 + hsA, voffA);
;             if (Epi::NPRE != 0 && last) { E.pre(sv, cur, wr, fr); PG8_WAIT_V(16); } else { PG8_WAIT_V(8); }
;             PG8_WAIT_L(0); PG8_BAR; PG8_MMA(0, 0, At, B0); PG8_MMA(0, 1, At, B1); PG8_BAR; PG8_SCHED;
;             PG8_LDA(At, 0, 1); PG8_STAGE(PG8_SB(0, 0), b2, voffB); PG8_STAGE(PG8_SB(0, 1), b2 + hsB, voffB); PG8_STAGE(PG8_SA(0, 0), a2, voffA);
;             if (Epi::NPRE != 0 && last) { PG8_WAIT_V(16); } else { PG8_WAIT_V(8); }
;             PG8_WAIT_L(0); PG8_BAR; PG8_MMA(1, 0, At, B0); PG8_MMA(1, 1, At, B1); PG8_BAR; PG8_SCHED;
.LBB0_648:
	ds_read_b128 v[148:151], v143
	ds_read_b128 v[152:155], v143 offset:1024
	ds_read_b128 v[156:159], v143 offset:2048
	ds_read_b128 v[160:163], v143 offset:3072
	ds_read_b128 v[164:167], v144
	ds_read_b128 v[168:171], v144 offset:1024
	ds_read_b128 v[172:175], v144 offset:2048
	ds_read_b128 v[176:179], v144 offset:3072
	s_add_i32 s56, s24, 2
	s_add_u32 s25, s22, 0xfffe0080
	s_addc_u32 s26, s23, -1
	s_cmp_eq_u32 s38, s24
	s_cselect_b32 s24, s53, s54
	s_cselect_b32 s27, s50, s26
	s_cselect_b32 s26, s51, s25
	s_cselect_b32 s25, s52, s55
	s_mov_b32 m0, s39
	ds_read_b128 v[180:183], v145
	ds_read_b128 v[184:187], v145 offset:1024
	ds_read_b128 v[188:191], v145 offset:2048
	ds_read_b128 v[194:197], v145 offset:3072
	ds_read_b128 v[198:201], v145 offset:4096
	ds_read_b128 v[202:205], v145 offset:5120
	ds_read_b128 v[206:209], v145 offset:6144
	ds_read_b128 v[210:213], v145 offset:7168
	global_load_lds_dwordx4 v138, s[22:23]
	s_mov_b32 m0, s40
	s_nop 0
	global_load_lds_dwordx4 v140, s[22:23]
	s_waitcnt vmcnt(8)
	s_waitcnt lgkmcnt(0)
	s_setprio 1
	s_barrier
	v_mfma_f32_16x16x32_bf16 v[124:127], v[148:151], v[180:183], v[124:127]
	v_mfma_f32_16x16x32_bf16 v[120:123], v[156:159], v[180:183], v[120:123]
	v_mfma_f32_16x16x32_bf16 v[108:111], v[148:151], v[188:191], v[108:111]
	v_mfma_f32_16x16x32_bf16 v[104:107], v[156:159], v[188:191], v[104:107]
	v_mfma_f32_16x16x32_bf16 v[92:95], v[148:151], v[198:201], v[92:95]
	v_mfma_f32_16x16x32_bf16 v[88:91], v[156:159], v[198:201], v[88:91]
	v_mfma_f32_16x16x32_bf16 v[76:79], v[148:151], v[206:209], v[76:79]
	v_mfma_f32_16x16x32_bf16 v[72:75], v[156:159], v[206:209], v[72:75]
	v_mfma_f32_16x16x32_bf16 v[124:127], v[152:155], v[184:187], v[124:127]
	v_mfma_f32_16x16x32_bf16 v[120:123], v[160:163], v[184:187], v[120:123]
	v_mfma_f32_16x16x32_bf16 v[108:111], v[152:155], v[194:197], v[108:111]
	v_mfma_f32_16x16x32_bf16 v[104:107], v[160:163], v[194:197], v[104:107]
	v_mfma_f32_16x16x32_bf16 v[92:95], v[152:155], v[202:205], v[92:95]
	v_mfma_f32_16x16x32_bf16 v[88:91], v[160:163], v[202:205], v[88:91]
	v_mfma_f32_16x16x32_bf16 v[76:79], v[152:155], v[210:213], v[76:79]
	v_mfma_f32_16x16x32_bf16 v[72:75], v[160:163], v[210:213], v[72:75]
	v_mfma_f32_16x16x32_bf16 v[116:119], v[164:167], v[180:183], v[116:119]
	v_mfma_f32_16x16x32_bf16 v[112:115], v[172:175], v[180:183], v[112:115]
	v_mfma_f32_16x16x32_bf16 v[100:103], v[164:167], v[188:191], v[100:103]
	v_mfma_f32_16x16x32_bf16 v[96:99], v[172:175], v[188:191], v[96:99]
	v_mfma_f32_16x16x32_bf16 v[84:87], v[164:167], v[198:201], v[84:87]
	v_mfma_f32_16x16x32_bf16 v[80:83], v[172:175], v[198:201], v[80:83]
	v_mfma_f32_16x16x32_bf16 v[68:71], v[164:167], v[206:209], v[68:71]
	v_mfma_f32_16x16x32_bf16 v[64:67], v[172:175], v[206:209], v[64:67]
	v_mfma_f32_16x16x32_bf16 v[116:119], v[168:171], v[184:187], v[116:119]
	v_mfma_f32_16x16x32_bf16 v[112:115], v[176:179], v[184:187], v[112:115]
	v_mfma_f32_16x16x32_bf16 v[100:103], v[168:171], v[194:197], v[100:103]
	v_mfma_f32_16x16x32_bf16 v[96:99], v[176:179], v[194:197], v[96:99]
	v_mfma_f32_16x16x32_bf16 v[84:87], v[168:171], v[202:205], v[84:87]
	v_mfma_f32_16x16x32_bf16 v[80:83], v[176:179], v[202:205], v[80:83]
	v_mfma_f32_16x16x32_bf16 v[68:71], v[168:171], v[210:213], v[68:71]
	v_mfma_f32_16x16x32_bf16 v[64:67], v[176:179], v[210:213], v[64:67]
	s_barrier
	s_setprio 0
	s_add_u32 s98, s24, s12
	s_addc_u32 s99, s25, s13
	s_add_u32 s100, s26, s12
	s_addc_u32 s101, s27, s13
	s_mov_b32 m0, s41
	s_add_u32 s66, s24, 0x10000
	ds_read_b128 v[180:183], v145 offset:16384
	ds_read_b128 v[184:187], v145 offset:17408
	ds_read_b128 v[188:191], v145 offset:18432
	ds_read_b128 v[194:197], v145 offset:19456
	ds_read_b128 v[198:201], v145 offset:20480
	ds_read_b128 v[202:205], v145 offset:21504
	ds_read_b128 v[206:209], v145 offset:22528
	ds_read_b128 v[210:213], v145 offset:23552
	global_load_lds_dwordx4 v132, s[24:25]
	s_mov_b32 m0, s42
	s_addc_u32 s67, s25, 0
	global_load_lds_dwordx4 v128, s[24:25]
	s_mov_b32 m0, s43
	s_nop 0
	global_load_lds_dwordx4 v132, s[66:67]
	s_mov_b32 m0, s44
	s_nop 0
	global_load_lds_dwordx4 v128, s[66:67]
	s_mov_b32 m0, s3
	s_nop 0
	global_load_lds_dwordx4 v134, s[26:27]
	s_mov_b32 m0, s29
	s_nop 0
	global_load_lds_dwordx4 v130, s[26:27]
	s_waitcnt vmcnt(8)
	s_waitcnt lgkmcnt(0)
	s_setprio 1
	s_barrier
	v_mfma_f32_16x16x32_bf16 v[60:63], v[148:151], v[180:183], v[60:63]
	v_mfma_f32_16x16x32_bf16 v[56:59], v[156:159], v[180:183], v[56:59]
	v_mfma_f32_16x16x32_bf16 v[44:47], v[148:151], v[188:191], v[44:47]
	v_mfma_f32_16x16x32_bf16 v[40:43], v[156:159], v[188:191], v[40:43]
	v_mfma_f32_16x16x32_bf16 v[28:31], v[148:151], v[198:201], v[28:31]
	v_mfma_f32_16x16x32_bf16 v[24:27], v[156:159], v[198:201], v[24:27]
	v_mfma_f32_16x16x32_bf16 v[12:15], v[148:151], v[206:209], v[12:15]
	v_mfma_f32_16x16x32_bf16 v[8:11], v[156:159], v[206:209], v[8:11]
	v_mfma_f32_16x16x32_bf16 v[60:63], v[152:155], v[184:187], v[60:63]
	v_mfma_f32_16x16x32_bf16 v[56:59], v[160:163], v[184:187], v[56:59]
	v_mfma_f32_16x16x32_bf16 v[44:47], v[152:155], v[194:197], v[44:47]
	v_mfma_f32_16x16x32_bf16 v[40:43], v[160:163], v[194:197], v[40:43]
	v_mfma_f32_16x16x32_bf16 v[28:31], v[152:155], v[202:205], v[28:31]
	v_mfma_f32_16x16x32_bf16 v[24:27], v[160:163], v[202:205], v[24:27]
	v_mfma_f32_16x16x32_bf16 v[12:15], v[152:155], v[210:213], v[12:15]
	v_mfma_f32_16x16x32_bf16 v[8:11], v[160:163], v[210:213], v[8:11]
	v_mfma_f32_16x16x32_bf16 v[52:55], v[164:167], v[180:183], v[52:55]
	v_mfma_f32_16x16x32_bf16 v[48:51], v[172:175], v[180:183], v[48:51]
	v_mfma_f32_16x16x32_bf16 v[36:39], v[164:167], v[188:191], v[36:39]
	v_mfma_f32_16x16x32_bf16 v[32:35], v[172:175], v[188:191], v[32:35]
	v_mfma_f32_16x16x32_bf16 v[20:23], v[164:167], v[198:201], v[20:23]
	v_mfma_f32_16x16x32_bf16 v[16:19], v[172:175], v[198:201], v[16:19]
	v_mfma_f32_16x16x32_bf16 v[4:7], v[164:167], v[206:209], v[4:7]
	v_mfma_f32_16x16x32_bf16 v[0:3], v[172:175], v[206:209], v[0:3]
	v_mfma_f32_16x16x32_bf16 v[52:55], v[168:171], v[184:187], v[52:55]
	v_mfma_f32_16x16x32_bf16 v[48:51], v[176:179], v[184:187], v[48:51]
	v_mfma_f32_16x16x32_bf16 v[36:39], v[168:171], v[194:197], v[36:39]
	v_mfma_f32_16x16x32_bf16 v[32:35], v[176:179], v[194:197], v[32:35]
	v_mfma_f32_16x16x32_bf16 v[20:23], v[168:171], v[202:205], v[20:23]
	v_mfma_f32_16x16x32_bf16 v[16:19], v[176:179], v[202:205], v[16:19]
	v_mfma_f32_16x16x32_bf16 v[4:7], v[168:171], v[210:213], v[4:7]
	v_mfma_f32_16x16x32_bf16 v[0:3], v[176:179], v[210:213], v[0:3]
	s_barrier
; #define PG8_STAGE(bufoff, gbase, voff) do { _Pragma("unroll") for (int _i = 0; _i < 2; ++_i) \
;         __builtin_amdgcn_global_load_lds((const unsigned*)((const char*)(gbase) + (voff)[_i]), (LAS unsigned*)(lds + (bufoff) + ldsw + _i * 8192), 16, 0, ((voff) == voffA ? AUXA : 0)); } while (0)
; #define PG8_LDA(dst, b, h) do { _Pragma("unroll") for (int m = 0; m < 4; ++m) _Pragma("unroll") for (int k = 0; k < 2; ++k) dst[m][k] = *(const LAS bf16x8*)(lds + PG8_SA(b, h) + aoff + m * 2048 + k * 1024); } while (0)
; #define PG8_LDB(dst, b, h) do { _Pragma("unroll") for (int n = 0; n < 2; ++n) _Pragma("unroll") for (int k = 0; k < 2; ++k) dst[n][k] = *(const LAS bf16x8*)(lds + PG8_SB(b, h) + boff + n * 2048 + k * 1024); } while (0)
; #define PG8_MMA(ai, bj, At, Bt) do { __builtin_amdgcn_s_setprio(1); _Pragma("unroll") for (int m = 0; m < 4; ++m) _Pragma("unroll") for (int n = 0; n < 2; ++n) _Pragma("unroll") for (int k = 0; k < 2; ++k) \
;         acc[ai][bj][m][n] = __builtin_amdgcn_mfma_f32_16x16x32_bf16(Bt[n][k], At[m][k], acc[ai][bj][m][n], 0, 0, 0); __builtin_amdgcn_s_setprio(0); } while (0)
; #define PG8_WAIT_V(n) asm volatile("s_waitcnt vmcnt(" #n ")" ::: "memory")
; #define PG8_WAIT_L(n) asm volatile("s_waitcnt lgkmcnt(" #n ")" ::: "memory")
; #define PG8_BAR __builtin_amdgcn_s_barrier()
; #define PG8_SCHED __builtin_amdgcn_sched_barrier(0)
;     ...
;             PG8_LDB(B0, 1, 0); PG8_LDB(B1, 1, 1); PG8_SCHED; PG8_LDA(At, 1, 0); PG8_STAGE(PG8_SA(0, 1), a2 + hsA, voffA);
;             PG8_WAIT_V(8); PG8_WAIT_L(0); PG8_BAR; PG8_MMA(0, 0, At, B0); PG8_MMA(0, 1, At, B1); PG8_BAR; PG8_SCHED;
;             PG8_LDA(At, 1, 1); PG8_STAGE(PG8_SB(1, 0), b3, voffB); PG8_STAGE(PG8_SB(1, 1), b3 + hsB, voffB); PG8_STAGE(PG8_SA(1, 0), a3, voffA);
;             PG8_WAIT_V(8); PG8_WAIT_L(0); PG8_BAR; PG8_MMA(1, 0, At, B0); PG8_MMA(1, 1, At, B1); PG8_BAR; PG8_SCHED;
;         }
	s_setprio 0
	ds_read_b128 v[148:151], v146
	ds_read_b128 v[152:155], v146 offset:1024
	ds_read_b128 v[156:159], v146 offset:2048
	ds_read_b128 v[160:163], v146 offset:3072
	ds_read_b128 v[164:167], v147
	ds_read_b128 v[168:171], v147 offset:1024
	ds_read_b128 v[172:175], v147 offset:2048
	ds_read_b128 v[176:179], v147 offset:3072
	s_add_u32 s26, s26, 0x20000
	s_addc_u32 s27, s27, 0
	s_mov_b32 m0, s30
	ds_read_b128 v[180:183], v145 offset:32768
	ds_read_b128 v[184:187], v145 offset:33792
	ds_read_b128 v[188:191], v145 offset:34816
	ds_read_b128 v[194:197], v145 offset:35840
	ds_read_b128 v[198:201], v145 offset:36864
	ds_read_b128 v[202:205], v145 offset:37888
	ds_read_b128 v[206:209], v145 offset:38912
	ds_read_b128 v[210:213], v145 offset:39936
	global_load_lds_dwordx4 v134, s[26:27]
	s_mov_b32 m0, s31
	s_nop 0
	global_load_lds_dwordx4 v130, s[26:27]
	s_waitcnt vmcnt(8)
	s_waitcnt lgkmcnt(0)
	s_setprio 1
	s_barrier
	v_mfma_f32_16x16x32_bf16 v[124:127], v[148:151], v[180:183], v[124:127]
	v_mfma_f32_16x16x32_bf16 v[120:123], v[156:159], v[180:183], v[120:123]
	v_mfma_f32_16x16x32_bf16 v[108:111], v[148:151], v[188:191], v[108:111]
	v_mfma_f32_16x16x32_bf16 v[104:107], v[156:159], v[188:191], v[104:107]
	v_mfma_f32_16x16x32_bf16 v[92:95], v[148:151], v[198:201], v[92:95]
	v_mfma_f32_16x16x32_bf16 v[88:91], v[156:159], v[198:201], v[88:91]
	v_mfma_f32_16x16x32_bf16 v[76:79], v[148:151], v[206:209], v[76:79]
	v_mfma_f32_16x16x32_bf16 v[72:75], v[156:159], v[206:209], v[72:75]
	v_mfma_f32_16x16x32_bf16 v[124:127], v[152:155], v[184:187], v[124:127]
	v_mfma_f32_16x16x32_bf16 v[120:123], v[160:163], v[184:187], v[120:123]
	v_mfma_f32_16x16x32_bf16 v[108:111], v[152:155], v[194:197], v[108:111]
	v_mfma_f32_16x16x32_bf16 v[104:107], v[160:163], v[194:197], v[104:107]
	v_mfma_f32_16x16x32_bf16 v[92:95], v[152:155], v[202:205], v[92:95]
	v_mfma_f32_16x16x32_bf16 v[88:91], v[160:163], v[202:205], v[88:91]
	v_mfma_f32_16x16x32_bf16 v[76:79], v[152:155], v[210:213], v[76:79]
	v_mfma_f32_16x16x32_bf16 v[72:75], v[160:163], v[210:213], v[72:75]
	v_mfma_f32_16x16x32_bf16 v[116:119], v[164:167], v[180:183], v[116:119]
	v_mfma_f32_16x16x32_bf16 v[112:115], v[172:175], v[180:183], v[112:115]
	v_mfma_f32_16x16x32_bf16 v[100:103], v[164:167], v[188:191], v[100:103]
	v_mfma_f32_16x16x32_bf16 v[96:99], v[172:175], v[188:191], v[96:99]
	v_mfma_f32_16x16x32_bf16 v[84:87], v[164:167], v[198:201], v[84:87]
	v_mfma_f32_16x16x32_bf16 v[80:83], v[172:175], v[198:201], v[80:83]
	v_mfma_f32_16x16x32_bf16 v[68:71], v[164:167], v[206:209], v[68:71]
	v_mfma_f32_16x16x32_bf16 v[64:67], v[172:175], v[206:209], v[64:67]
	v_mfma_f32_16x16x32_bf16 v[116:119], v[168:171], v[184:187], v[116:119]
	v_mfma_f32_16x16x32_bf16 v[112:115], v[176:179], v[184:187], v[112:115]
	v_mfma_f32_16x16x32_bf16 v[100:103], v[168:171], v[194:197], v[100:103]
	v_mfma_f32_16x16x32_bf16 v[96:99], v[176:179], v[194:197], v[96:99]
	v_mfma_f32_16x16x32_bf16 v[84:87], v[168:171], v[202:205], v[84:87]
	v_mfma_f32_16x16x32_bf16 v[80:83], v[176:179], v[202:205], v[80:83]
	v_mfma_f32_16x16x32_bf16 v[68:71], v[168:171], v[210:213], v[68:71]
	v_mfma_f32_16x16x32_bf16 v[64:67], v[176:179], v[210:213], v[64:67]
	s_barrier
	s_setprio 0
	s_add_i32 s26, s45, s28
	s_mov_b32 m0, s26
	ds_read_b128 v[180:183], v145 offset:49152
	ds_read_b128 v[184:187], v145 offset:50176
	ds_read_b128 v[188:191], v145 offset:51200
	ds_read_b128 v[194:197], v145 offset:52224
	ds_read_b128 v[198:201], v145 offset:53248
	ds_read_b128 v[202:205], v145 offset:54272
	ds_read_b128 v[206:209], v145 offset:55296
	ds_read_b128 v[210:213], v145 offset:56320
	global_load_lds_dwordx4 v132, s[98:99]
	s_add_i32 m0, s26, 0x2000
	s_add_u32 s24, s24, 0x10080
	s_addc_u32 s25, s25, 0
	s_add_i32 s26, s46, s28
	global_load_lds_dwordx4 v128, s[98:99]
	s_mov_b32 m0, s26
	s_nop 0
	global_load_lds_dwordx4 v132, s[24:25]
	s_add_i32 m0, s26, 0x2000
	s_nop 0
	global_load_lds_dwordx4 v128, s[24:25]
	s_mov_b32 m0, s36
	s_nop 0
	global_load_lds_dwordx4 v134, s[100:101]
	s_mov_b32 m0, s37
	s_nop 0
	global_load_lds_dwordx4 v130, s[100:101]
	s_waitcnt vmcnt(8)
	s_waitcnt lgkmcnt(0)
	s_setprio 1
	s_barrier
	v_mfma_f32_16x16x32_bf16 v[60:63], v[148:151], v[180:183], v[60:63]
	v_mfma_f32_16x16x32_bf16 v[56:59], v[156:159], v[180:183], v[56:59]
	v_mfma_f32_16x16x32_bf16 v[44:47], v[148:151], v[188:191], v[44:47]
	v_mfma_f32_16x16x32_bf16 v[40:43], v[156:159], v[188:191], v[40:43]
	v_mfma_f32_16x16x32_bf16 v[28:31], v[148:151], v[198:201], v[28:31]
	v_mfma_f32_16x16x32_bf16 v[24:27], v[156:159], v[198:201], v[24:27]
	v_mfma_f32_16x16x32_bf16 v[12:15], v[148:151], v[206:209], v[12:15]
	v_mfma_f32_16x16x32_bf16 v[8:11], v[156:159], v[206:209], v[8:11]
	v_mfma_f32_16x16x32_bf16 v[60:63], v[152:155], v[184:187], v[60:63]
	v_mfma_f32_16x16x32_bf16 v[56:59], v[160:163], v[184:187], v[56:59]
	v_mfma_f32_16x16x32_bf16 v[44:47], v[152:155], v[194:197], v[44:47]
	v_mfma_f32_16x16x32_bf16 v[40:43], v[160:163], v[194:197], v[40:43]
	v_mfma_f32_16x16x32_bf16 v[28:31], v[152:155], v[202:205], v[28:31]
	v_mfma_f32_16x16x32_bf16 v[24:27], v[160:163], v[202:205], v[24:27]
	v_mfma_f32_16x16x32_bf16 v[12:15], v[152:155], v[210:213], v[12:15]
	v_mfma_f32_16x16x32_bf16 v[8:11], v[160:163], v[210:213], v[8:11]
	v_mfma_f32_16x16x32_bf16 v[52:55], v[164:167], v[180:183], v[52:55]
	v_mfma_f32_16x16x32_bf16 v[48:51], v[172:175], v[180:183], v[48:51]
	v_mfma_f32_16x16x32_bf16 v[36:39], v[164:167], v[188:191], v[36:39]
	v_mfma_f32_16x16x32_bf16 v[32:35], v[172:175], v[188:191], v[32:35]
	v_mfma_f32_16x16x32_bf16 v[20:23], v[164:167], v[198:201], v[20:23]
	v_mfma_f32_16x16x32_bf16 v[16:19], v[172:175], v[198:201], v[16:19]
	v_mfma_f32_16x16x32_bf16 v[4:7], v[164:167], v[206:209], v[4:7]
	v_mfma_f32_16x16x32_bf16 v[0:3], v[172:175], v[206:209], v[0:3]
	v_mfma_f32_16x16x32_bf16 v[52:55], v[168:171], v[184:187], v[52:55]
	v_mfma_f32_16x16x32_bf16 v[48:51], v[176:179], v[184:187], v[48:51]
	v_mfma_f32_16x16x32_bf16 v[36:39], v[168:171], v[194:197], v[36:39]
	v_mfma_f32_16x16x32_bf16 v[32:35], v[176:179], v[194:197], v[32:35]
	v_mfma_f32_16x16x32_bf16 v[20:23], v[168:171], v[202:205], v[20:23]
	v_mfma_f32_16x16x32_bf16 v[16:19], v[176:179], v[202:205], v[16:19]
	v_mfma_f32_16x16x32_bf16 v[4:7], v[168:171], v[210:213], v[4:7]
	v_mfma_f32_16x16x32_bf16 v[0:3], v[176:179], v[210:213], v[0:3]
	s_barrier
	s_setprio 0
	s_add_u32 s22, s22, 0x100
	s_addc_u32 s23, s23, 0
	s_add_u32 s54, s54, 0x100
	s_addc_u32 s55, s55, 0
	s_cmp_ge_i32 s56, s35
	s_mov_b32 s24, s56
	s_cbranch_scc0 .LBB0_648

; #define PG8_STAGE(bufoff, gbase, voff) do { _Pragma("unroll") for (int _i = 0; _i < 2; ++_i) \
;         __builtin_amdgcn_global_load_lds((const unsigned*)((const char*)(gbase) + (voff)[_i]), (LAS unsigned*)(lds + (bufoff) + ldsw + _i * 8192), 16, 0, ((voff) == voffA ? AUXA : 0)); } while (0)
; #define PG8_LDA(dst, b, h) do { _Pragma("unroll") for (int m = 0; m < 4; ++m) _Pragma("unroll") for (int k = 0; k < 2; ++k) dst[m][k] = *(const LAS bf16x8*)(lds + PG8_SA(b, h) + aoff + m * 2048 + k * 1024); } while (0)
; #define PG8_LDB(dst, b, h) do { _Pragma("unroll") for (int n = 0; n < 2; ++n) _Pragma("unroll") for (int k = 0; k < 2; ++k) dst[n][k] = *(const LAS bf16x8*)(lds + PG8_SB(b, h) + boff + n * 2048 + k * 1024); } while (0)
; #define PG8_MMA(ai, bj, At, Bt) do { __builtin_amdgcn_s_setprio(1); _Pragma("unroll") for (int m = 0; m < 4; ++m) _Pragma("unroll") for (int n = 0; n < 2; ++n) _Pragma("unroll") for (int k = 0; k < 2; ++k) \
;         acc[ai][bj][m][n] = __builtin_amdgcn_mfma_f32_16x16x32_bf16(Bt[n][k], At[m][k], acc[ai][bj][m][n], 0, 0, 0); __builtin_amdgcn_s_setprio(0); } while (0)
; #define PG8_WAIT_V(n) asm volatile("s_waitcnt vmcnt(" #n ")" ::: "memory")
; #define PG8_WAIT_L(n) asm volatile("s_waitcnt lgkmcnt(" #n ")" ::: "memory")
; #define PG8_BAR __builtin_amdgcn_s_barrier()
; #define PG8_SCHED __builtin_amdgcn_sched_barrier(0)
;     ...
;             PG8_LDB(B0, 0, 0); PG8_LDB(B1, 0, 1); PG8_SCHED; PG8_LDA(At, 0, 0); PG8_STAGE(PG8_SA(1, 1), a1 + hsA, voffA);
;             if (Epi::NPRE != 0 && last) { E.pre(sv, cur, wr, fr); PG8_WAIT_V(16); } else { PG8_WAIT_V(8); }
;             PG8_WAIT_L(0); PG8_BAR; PG8_MMA(0, 0, At, B0); PG8_MMA(0, 1, At, B1); PG8_BAR; PG8_SCHED;
;             PG8_LDA(At, 0, 1); PG8_STAGE(PG8_SB(0, 0), b2, voffB); PG8_STAGE(PG8_SB(0, 1), b2 + hsB, voffB); PG8_STAGE(PG8_SA(0, 0), a2, voffA);
;             if (Epi::NPRE != 0 && last) { PG8_WAIT_V(16); } else { PG8_WAIT_V(8); }
;             PG8_WAIT_L(0); PG8_BAR; PG8_MMA(1, 0, At, B0); PG8_MMA(1, 1, At, B1); PG8_BAR; PG8_SCHED;
.LBB0_887:
	ds_read_b128 v[150:153], v146
	ds_read_b128 v[154:157], v146 offset:1024
	ds_read_b128 v[158:161], v146 offset:2048
	ds_read_b128 v[162:165], v146 offset:3072
	ds_read_b128 v[166:169], v147
	ds_read_b128 v[170:173], v147 offset:1024
	ds_read_b128 v[174:177], v147 offset:2048
	ds_read_b128 v[178:181], v147 offset:3072
	s_add_i32 s53, s26, 2
	s_add_u32 s27, s24, 0xfffe0080
	s_addc_u32 s28, s25, -1
	s_cmp_eq_u32 s42, s26
	s_cselect_b32 s26, s50, s51
	s_cselect_b32 s29, s23, s28
	s_cselect_b32 s28, s48, s27
	s_cselect_b32 s27, s49, s52
	s_add_i32 m0, s3, 0xc000
	ds_read_b128 v[182:185], v148
	ds_read_b128 v[186:189], v148 offset:1024
	ds_read_b128 v[194:197], v148 offset:2048
	ds_read_b128 v[198:201], v148 offset:3072
	ds_read_b128 v[202:205], v148 offset:4096
	ds_read_b128 v[206:209], v148 offset:5120
	ds_read_b128 v[210:213], v148 offset:6144
	ds_read_b128 v[214:217], v148 offset:7168
	global_load_lds_dwordx4 v138, s[24:25]
	s_add_i32 m0, s3, 0xe000
	s_nop 0
	global_load_lds_dwordx4 v140, s[24:25]
	s_waitcnt vmcnt(8)
	s_waitcnt lgkmcnt(0)
	s_setprio 1
	s_barrier
	v_mfma_f32_16x16x32_bf16 v[124:127], v[150:153], v[182:185], v[124:127]
	v_mfma_f32_16x16x32_bf16 v[120:123], v[158:161], v[182:185], v[120:123]
	v_mfma_f32_16x16x32_bf16 v[108:111], v[150:153], v[194:197], v[108:111]
	v_mfma_f32_16x16x32_bf16 v[104:107], v[158:161], v[194:197], v[104:107]
	v_mfma_f32_16x16x32_bf16 v[92:95], v[150:153], v[202:205], v[92:95]
	v_mfma_f32_16x16x32_bf16 v[88:91], v[158:161], v[202:205], v[88:91]
	v_mfma_f32_16x16x32_bf16 v[76:79], v[150:153], v[210:213], v[76:79]
	v_mfma_f32_16x16x32_bf16 v[72:75], v[158:161], v[210:213], v[72:75]
	v_mfma_f32_16x16x32_bf16 v[124:127], v[154:157], v[186:189], v[124:127]
	v_mfma_f32_16x16x32_bf16 v[120:123], v[162:165], v[186:189], v[120:123]
	v_mfma_f32_16x16x32_bf16 v[108:111], v[154:157], v[198:201], v[108:111]
	v_mfma_f32_16x16x32_bf16 v[104:107], v[162:165], v[198:201], v[104:107]
	v_mfma_f32_16x16x32_bf16 v[92:95], v[154:157], v[206:209], v[92:95]
	v_mfma_f32_16x16x32_bf16 v[88:91], v[162:165], v[206:209], v[88:91]
	v_mfma_f32_16x16x32_bf16 v[76:79], v[154:157], v[214:217], v[76:79]
	v_mfma_f32_16x16x32_bf16 v[72:75], v[162:165], v[214:217], v[72:75]
	v_mfma_f32_16x16x32_bf16 v[116:119], v[166:169], v[182:185], v[116:119]
	v_mfma_f32_16x16x32_bf16 v[112:115], v[174:177], v[182:185], v[112:115]
	v_mfma_f32_16x16x32_bf16 v[100:103], v[166:169], v[194:197], v[100:103]
	v_mfma_f32_16x16x32_bf16 v[96:99], v[174:177], v[194:197], v[96:99]
	v_mfma_f32_16x16x32_bf16 v[84:87], v[166:169], v[202:205], v[84:87]
	v_mfma_f32_16x16x32_bf16 v[80:83], v[174:177], v[202:205], v[80:83]
	v_mfma_f32_16x16x32_bf16 v[68:71], v[166:169], v[210:213], v[68:71]
	v_mfma_f32_16x16x32_bf16 v[64:67], v[174:177], v[210:213], v[64:67]
	v_mfma_f32_16x16x32_bf16 v[116:119], v[170:173], v[186:189], v[116:119]
	v_mfma_f32_16x16x32_bf16 v[112:115], v[178:181], v[186:189], v[112:115]
	v_mfma_f32_16x16x32_bf16 v[100:103], v[170:173], v[198:201], v[100:103]
	v_mfma_f32_16x16x32_bf16 v[96:99], v[178:181], v[198:201], v[96:99]
	v_mfma_f32_16x16x32_bf16 v[84:87], v[170:173], v[206:209], v[84:87]
	v_mfma_f32_16x16x32_bf16 v[80:83], v[178:181], v[206:209], v[80:83]
	v_mfma_f32_16x16x32_bf16 v[68:71], v[170:173], v[214:217], v[68:71]
	v_mfma_f32_16x16x32_bf16 v[64:67], v[178:181], v[214:217], v[64:67]
	s_barrier
	s_setprio 0
	s_add_u32 s98, s26, s12
	s_addc_u32 s99, s27, s13
	s_add_u32 s100, s28, s12
	s_addc_u32 s101, s29, s13
	s_add_i32 s54, s43, s34
	s_mov_b32 m0, s54
	ds_read_b128 v[182:185], v148 offset:16384
	ds_read_b128 v[186:189], v148 offset:17408
	ds_read_b128 v[194:197], v148 offset:18432
	ds_read_b128 v[198:201], v148 offset:19456
	ds_read_b128 v[202:205], v148 offset:20480
	ds_read_b128 v[206:209], v148 offset:21504
	ds_read_b128 v[210:213], v148 offset:22528
	ds_read_b128 v[214:217], v148 offset:23552
	global_load_lds_dwordx4 v132, s[26:27]
	s_add_i32 m0, s54, 0x2000
	s_add_u32 s54, s26, 0x20000
	s_addc_u32 s55, s27, 0
	s_add_i32 s56, s44, s34
	global_load_lds_dwordx4 v128, s[26:27]
	s_mov_b32 m0, s56
	s_nop 0
	global_load_lds_dwordx4 v132, s[54:55]
	s_add_i32 m0, s56, 0x2000
	s_nop 0
	global_load_lds_dwordx4 v128, s[54:55]
	s_mov_b32 m0, s3
	s_nop 0
	global_load_lds_dwordx4 v134, s[28:29]
	s_mov_b32 m0, s35
	s_nop 0
	global_load_lds_dwordx4 v130, s[28:29]
	s_waitcnt vmcnt(8)
	s_waitcnt lgkmcnt(0)
	s_setprio 1
	s_barrier
	v_mfma_f32_16x16x32_bf16 v[60:63], v[150:153], v[182:185], v[60:63]
	v_mfma_f32_16x16x32_bf16 v[56:59], v[158:161], v[182:185], v[56:59]
	v_mfma_f32_16x16x32_bf16 v[44:47], v[150:153], v[194:197], v[44:47]
	v_mfma_f32_16x16x32_bf16 v[40:43], v[158:161], v[194:197], v[40:43]
	v_mfma_f32_16x16x32_bf16 v[28:31], v[150:153], v[202:205], v[28:31]
	v_mfma_f32_16x16x32_bf16 v[24:27], v[158:161], v[202:205], v[24:27]
	v_mfma_f32_16x16x32_bf16 v[12:15], v[150:153], v[210:213], v[12:15]
	v_mfma_f32_16x16x32_bf16 v[8:11], v[158:161], v[210:213], v[8:11]
	v_mfma_f32_16x16x32_bf16 v[60:63], v[154:157], v[186:189], v[60:63]
	v_mfma_f32_16x16x32_bf16 v[56:59], v[162:165], v[186:189], v[56:59]
	v_mfma_f32_16x16x32_bf16 v[44:47], v[154:157], v[198:201], v[44:47]
	v_mfma_f32_16x16x32_bf16 v[40:43], v[162:165], v[198:201], v[40:43]
	v_mfma_f32_16x16x32_bf16 v[28:31], v[154:157], v[206:209], v[28:31]
	v_mfma_f32_16x16x32_bf16 v[24:27], v[162:165], v[206:209], v[24:27]
	v_mfma_f32_16x16x32_bf16 v[12:15], v[154:157], v[214:217], v[12:15]
	v_mfma_f32_16x16x32_bf16 v[8:11], v[162:165], v[214:217], v[8:11]
	v_mfma_f32_16x16x32_bf16 v[52:55], v[166:169], v[182:185], v[52:55]
	v_mfma_f32_16x16x32_bf16 v[48:51], v[174:177], v[182:185], v[48:51]
	v_mfma_f32_16x16x32_bf16 v[36:39], v[166:169], v[194:197], v[36:39]
	v_mfma_f32_16x16x32_bf16 v[32:35], v[174:177], v[194:197], v[32:35]
	v_mfma_f32_16x16x32_bf16 v[20:23], v[166:169], v[202:205], v[20:23]
	v_mfma_f32_16x16x32_bf16 v[16:19], v[174:177], v[202:205], v[16:19]
	v_mfma_f32_16x16x32_bf16 v[4:7], v[166:169], v[210:213], v[4:7]
	v_mfma_f32_16x16x32_bf16 v[0:3], v[174:177], v[210:213], v[0:3]
	v_mfma_f32_16x16x32_bf16 v[52:55], v[170:173], v[186:189], v[52:55]
	v_mfma_f32_16x16x32_bf16 v[48:51], v[178:181], v[186:189], v[48:51]
	v_mfma_f32_16x16x32_bf16 v[36:39], v[170:173], v[198:201], v[36:39]
	v_mfma_f32_16x16x32_bf16 v[32:35], v[178:181], v[198:201], v[32:35]
	v_mfma_f32_16x16x32_bf16 v[20:23], v[170:173], v[206:209], v[20:23]
	v_mfma_f32_16x16x32_bf16 v[16:19], v[178:181], v[206:209], v[16:19]
	v_mfma_f32_16x16x32_bf16 v[4:7], v[170:173], v[214:217], v[4:7]
	v_mfma_f32_16x16x32_bf16 v[0:3], v[178:181], v[214:217], v[0:3]
	s_barrier
; #define PG8_STAGE(bufoff, gbase, voff) do { _Pragma("unroll") for (int _i = 0; _i < 2; ++_i) \
;         __builtin_amdgcn_global_load_lds((const unsigned*)((const char*)(gbase) + (voff)[_i]), (LAS unsigned*)(lds + (bufoff) + ldsw + _i * 8192), 16, 0, ((voff) == voffA ? AUXA : 0)); } while (0)
; #define PG8_LDA(dst, b, h) do { _Pragma("unroll") for (int m = 0; m < 4; ++m) _Pragma("unroll") for (int k = 0; k < 2; ++k) dst[m][k] = *(const LAS bf16x8*)(lds + PG8_SA(b, h) + aoff + m * 2048 + k * 1024); } while (0)
; #define PG8_LDB(dst, b, h) do { _Pragma("unroll") for (int n = 0; n < 2; ++n) _Pragma("unroll") for (int k = 0; k < 2; ++k) dst[n][k] = *(const LAS bf16x8*)(lds + PG8_SB(b, h) + boff + n * 2048 + k * 1024); } while (0)
; #define PG8_MMA(ai, bj, At, Bt) do { __builtin_amdgcn_s_setprio(1); _Pragma("unroll") for (int m = 0; m < 4; ++m) _Pragma("unroll") for (int n = 0; n < 2; ++n) _Pragma("unroll") for (int k = 0; k < 2; ++k) \
;         acc[ai][bj][m][n] = __builtin_amdgcn_mfma_f32_16x16x32_bf16(Bt[n][k], At[m][k], acc[ai][bj][m][n], 0, 0, 0); __builtin_amdgcn_s_setprio(0); } while (0)
; #define PG8_WAIT_V(n) asm volatile("s_waitcnt vmcnt(" #n ")" ::: "memory")
; #define PG8_WAIT_L(n) asm volatile("s_waitcnt lgkmcnt(" #n ")" ::: "memory")
; #define PG8_BAR __builtin_amdgcn_s_barrier()
; #define PG8_SCHED __builtin_amdgcn_sched_barrier(0)
;     ...
;             PG8_LDB(B0, 1, 0); PG8_LDB(B1, 1, 1); PG8_SCHED; PG8_LDA(At, 1, 0); PG8_STAGE(PG8_SA(0, 1), a2 + hsA, voffA);
;             PG8_WAIT_V(8); PG8_WAIT_L(0); PG8_BAR; PG8_MMA(0, 0, At, B0); PG8_MMA(0, 1, At, B1); PG8_BAR; PG8_SCHED;
;             PG8_LDA(At, 1, 1); PG8_STAGE(PG8_SB(1, 0), b3, voffB); PG8_STAGE(PG8_SB(1, 1), b3 + hsB, voffB); PG8_STAGE(PG8_SA(1, 0), a3, voffA);
;             PG8_WAIT_V(8); PG8_WAIT_L(0); PG8_BAR; PG8_MMA(1, 0, At, B0); PG8_MMA(1, 1, At, B1); PG8_BAR; PG8_SCHED;
	s_setprio 0
	s_add_i32 s54, 0, 0x18000
	v_add_u32_e32 v149, s54, v143
	s_add_i32 s55, 0, 0x1c000
	ds_read_b128 v[150:153], v149
	ds_read_b128 v[154:157], v149 offset:1024
	ds_read_b128 v[158:161], v149 offset:2048
	ds_read_b128 v[162:165], v149 offset:3072
	v_add_u32_e32 v149, s55, v143
	ds_read_b128 v[166:169], v149
	ds_read_b128 v[170:173], v149 offset:1024
	ds_read_b128 v[174:177], v149 offset:2048
	ds_read_b128 v[178:181], v149 offset:3072
	s_add_u32 s28, s28, 0x20000
	s_addc_u32 s29, s29, 0
	s_mov_b32 m0, s36
	ds_read_b128 v[182:185], v148 offset:32768
	ds_read_b128 v[186:189], v148 offset:33792
	ds_read_b128 v[194:197], v148 offset:34816
	ds_read_b128 v[198:201], v148 offset:35840
	ds_read_b128 v[202:205], v148 offset:36864
	ds_read_b128 v[206:209], v148 offset:37888
	ds_read_b128 v[210:213], v148 offset:38912
	ds_read_b128 v[214:217], v148 offset:39936
	global_load_lds_dwordx4 v134, s[28:29]
	s_mov_b32 m0, s37
	s_nop 0
	global_load_lds_dwordx4 v130, s[28:29]
	s_waitcnt vmcnt(8)
	s_waitcnt lgkmcnt(0)
	s_setprio 1
	s_barrier
	v_mfma_f32_16x16x32_bf16 v[124:127], v[150:153], v[182:185], v[124:127]
	v_mfma_f32_16x16x32_bf16 v[120:123], v[158:161], v[182:185], v[120:123]
	v_mfma_f32_16x16x32_bf16 v[108:111], v[150:153], v[194:197], v[108:111]
	v_mfma_f32_16x16x32_bf16 v[104:107], v[158:161], v[194:197], v[104:107]
	v_mfma_f32_16x16x32_bf16 v[92:95], v[150:153], v[202:205], v[92:95]
	v_mfma_f32_16x16x32_bf16 v[88:91], v[158:161], v[202:205], v[88:91]
	v_mfma_f32_16x16x32_bf16 v[76:79], v[150:153], v[210:213], v[76:79]
	v_mfma_f32_16x16x32_bf16 v[72:75], v[158:161], v[210:213], v[72:75]
	v_mfma_f32_16x16x32_bf16 v[124:127], v[154:157], v[186:189], v[124:127]
	v_mfma_f32_16x16x32_bf16 v[120:123], v[162:165], v[186:189], v[120:123]
	v_mfma_f32_16x16x32_bf16 v[108:111], v[154:157], v[198:201], v[108:111]
	v_mfma_f32_16x16x32_bf16 v[104:107], v[162:165], v[198:201], v[104:107]
	v_mfma_f32_16x16x32_bf16 v[92:95], v[154:157], v[206:209], v[92:95]
	v_mfma_f32_16x16x32_bf16 v[88:91], v[162:165], v[206:209], v[88:91]
	v_mfma_f32_16x16x32_bf16 v[76:79], v[154:157], v[214:217], v[76:79]
	v_mfma_f32_16x16x32_bf16 v[72:75], v[162:165], v[214:217], v[72:75]
	v_mfma_f32_16x16x32_bf16 v[116:119], v[166:169], v[182:185], v[116:119]
	v_mfma_f32_16x16x32_bf16 v[112:115], v[174:177], v[182:185], v[112:115]
	v_mfma_f32_16x16x32_bf16 v[100:103], v[166:169], v[194:197], v[100:103]
	v_mfma_f32_16x16x32_bf16 v[96:99], v[174:177], v[194:197], v[96:99]
	v_mfma_f32_16x16x32_bf16 v[84:87], v[166:169], v[202:205], v[84:87]
	v_mfma_f32_16x16x32_bf16 v[80:83], v[174:177], v[202:205], v[80:83]
	v_mfma_f32_16x16x32_bf16 v[68:71], v[166:169], v[210:213], v[68:71]
	v_mfma_f32_16x16x32_bf16 v[64:67], v[174:177], v[210:213], v[64:67]
	v_mfma_f32_16x16x32_bf16 v[116:119], v[170:173], v[186:189], v[116:119]
	v_mfma_f32_16x16x32_bf16 v[112:115], v[178:181], v[186:189], v[112:115]
	v_mfma_f32_16x16x32_bf16 v[100:103], v[170:173], v[198:201], v[100:103]
	v_mfma_f32_16x16x32_bf16 v[96:99], v[178:181], v[198:201], v[96:99]
	v_mfma_f32_16x16x32_bf16 v[84:87], v[170:173], v[206:209], v[84:87]
	v_mfma_f32_16x16x32_bf16 v[80:83], v[178:181], v[206:209], v[80:83]
	v_mfma_f32_16x16x32_bf16 v[68:71], v[170:173], v[214:217], v[68:71]
	v_mfma_f32_16x16x32_bf16 v[64:67], v[178:181], v[214:217], v[64:67]
	s_barrier
	s_setprio 0
	s_add_i32 s28, s54, s34
	s_mov_b32 m0, s28
	ds_read_b128 v[182:185], v148 offset:49152
	ds_read_b128 v[186:189], v148 offset:50176
	ds_read_b128 v[194:197], v148 offset:51200
	ds_read_b128 v[198:201], v148 offset:52224
	ds_read_b128 v[202:205], v148 offset:53248
	ds_read_b128 v[206:209], v148 offset:54272
	ds_read_b128 v[210:213], v148 offset:55296
	ds_read_b128 v[214:217], v148 offset:56320
	global_load_lds_dwordx4 v132, s[98:99]
	s_add_i32 m0, s28, 0x2000
	s_add_u32 s26, s26, 0x20080
	s_addc_u32 s27, s27, 0
	s_add_i32 s28, s55, s34
	global_load_lds_dwordx4 v128, s[98:99]
	s_mov_b32 m0, s28
	s_nop 0
	global_load_lds_dwordx4 v132, s[26:27]
	s_add_i32 m0, s28, 0x2000
	s_nop 0
	global_load_lds_dwordx4 v128, s[26:27]
	s_mov_b32 m0, s40
	s_nop 0
	global_load_lds_dwordx4 v134, s[100:101]
	s_mov_b32 m0, s41
	s_nop 0
	global_load_lds_dwordx4 v130, s[100:101]
	s_waitcnt vmcnt(8)
	s_waitcnt lgkmcnt(0)
	s_setprio 1
	s_barrier
	v_mfma_f32_16x16x32_bf16 v[60:63], v[150:153], v[182:185], v[60:63]
	v_mfma_f32_16x16x32_bf16 v[56:59], v[158:161], v[182:185], v[56:59]
	v_mfma_f32_16x16x32_bf16 v[44:47], v[150:153], v[194:197], v[44:47]
	v_mfma_f32_16x16x32_bf16 v[40:43], v[158:161], v[194:197], v[40:43]
	v_mfma_f32_16x16x32_bf16 v[28:31], v[150:153], v[202:205], v[28:31]
	v_mfma_f32_16x16x32_bf16 v[24:27], v[158:161], v[202:205], v[24:27]
	v_mfma_f32_16x16x32_bf16 v[12:15], v[150:153], v[210:213], v[12:15]
	v_mfma_f32_16x16x32_bf16 v[8:11], v[158:161], v[210:213], v[8:11]
	v_mfma_f32_16x16x32_bf16 v[60:63], v[154:157], v[186:189], v[60:63]
	v_mfma_f32_16x16x32_bf16 v[56:59], v[162:165], v[186:189], v[56:59]
	v_mfma_f32_16x16x32_bf16 v[44:47], v[154:157], v[198:201], v[44:47]
	v_mfma_f32_16x16x32_bf16 v[40:43], v[162:165], v[198:201], v[40:43]
	v_mfma_f32_16x16x32_bf16 v[28:31], v[154:157], v[206:209], v[28:31]
	v_mfma_f32_16x16x32_bf16 v[24:27], v[162:165], v[206:209], v[24:27]
	v_mfma_f32_16x16x32_bf16 v[12:15], v[154:157], v[214:217], v[12:15]
	v_mfma_f32_16x16x32_bf16 v[8:11], v[162:165], v[214:217], v[8:11]
	v_mfma_f32_16x16x32_bf16 v[52:55], v[166:169], v[182:185], v[52:55]
	v_mfma_f32_16x16x32_bf16 v[48:51], v[174:177], v[182:185], v[48:51]
	v_mfma_f32_16x16x32_bf16 v[36:39], v[166:169], v[194:197], v[36:39]
	v_mfma_f32_16x16x32_bf16 v[32:35], v[174:177], v[194:197], v[32:35]
	v_mfma_f32_16x16x32_bf16 v[20:23], v[166:169], v[202:205], v[20:23]
	v_mfma_f32_16x16x32_bf16 v[16:19], v[174:177], v[202:205], v[16:19]
	v_mfma_f32_16x16x32_bf16 v[4:7], v[166:169], v[210:213], v[4:7]
	v_mfma_f32_16x16x32_bf16 v[0:3], v[174:177], v[210:213], v[0:3]
	v_mfma_f32_16x16x32_bf16 v[52:55], v[170:173], v[186:189], v[52:55]
	v_mfma_f32_16x16x32_bf16 v[48:51], v[178:181], v[186:189], v[48:51]
	v_mfma_f32_16x16x32_bf16 v[36:39], v[170:173], v[198:201], v[36:39]
	v_mfma_f32_16x16x32_bf16 v[32:35], v[178:181], v[198:201], v[32:35]
	v_mfma_f32_16x16x32_bf16 v[20:23], v[170:173], v[206:209], v[20:23]
	v_mfma_f32_16x16x32_bf16 v[16:19], v[178:181], v[206:209], v[16:19]
	v_mfma_f32_16x16x32_bf16 v[4:7], v[170:173], v[214:217], v[4:7]
	v_mfma_f32_16x16x32_bf16 v[0:3], v[178:181], v[214:217], v[0:3]
	s_barrier
	s_setprio 0
	s_add_u32 s24, s24, 0x100
	s_addc_u32 s25, s25, 0
	s_add_u32 s51, s51, 0x100
	s_addc_u32 s52, s52, 0
	s_cmp_ge_i32 s53, s39
	s_mov_b32 s26, s53
	s_cbranch_scc0 .LBB0_887

; #define PG8_STAGE(bufoff, gbase, voff) do { _Pragma("unroll") for (int _i = 0; _i < 2; ++_i) \
;         __builtin_amdgcn_global_load_lds((const unsigned*)((const char*)(gbase) + (voff)[_i]), (LAS unsigned*)(lds + (bufoff) + ldsw + _i * 8192), 16, 0, ((voff) == voffA ? AUXA : 0)); } while (0)
; #define PG8_LDA(dst, b, h) do { _Pragma("unroll") for (int m = 0; m < 4; ++m) _Pragma("unroll") for (int k = 0; k < 2; ++k) dst[m][k] = *(const LAS bf16x8*)(lds + PG8_SA(b, h) + aoff + m * 2048 + k * 1024); } while (0)
; #define PG8_LDB(dst, b, h) do { _Pragma("unroll") for (int n = 0; n < 2; ++n) _Pragma("unroll") for (int k = 0; k < 2; ++k) dst[n][k] = *(const LAS bf16x8*)(lds + PG8_SB(b, h) + boff + n * 2048 + k * 1024); } while (0)
; #define PG8_MMA(ai, bj, At, Bt) do { __builtin_amdgcn_s_setprio(1); _Pragma("unroll") for (int m = 0; m < 4; ++m) _Pragma("unroll") for (int n = 0; n < 2; ++n) _Pragma("unroll") for (int k = 0; k < 2; ++k) \
;         acc[ai][bj][m][n] = __builtin_amdgcn_mfma_f32_16x16x32_bf16(Bt[n][k], At[m][k], acc[ai][bj][m][n], 0, 0, 0); __builtin_amdgcn_s_setprio(0); } while (0)
; #define PG8_WAIT_V(n) asm volatile("s_waitcnt vmcnt(" #n ")" ::: "memory")
; #define PG8_WAIT_L(n) asm volatile("s_waitcnt lgkmcnt(" #n ")" ::: "memory")
; #define PG8_BAR __builtin_amdgcn_s_barrier()
; #define PG8_SCHED __builtin_amdgcn_sched_barrier(0)
;     ...
;             PG8_LDB(B0, 0, 0); PG8_LDB(B1, 0, 1); PG8_SCHED; PG8_LDA(At, 0, 0); PG8_STAGE(PG8_SA(1, 1), a1 + hsA, voffA);
;             if (Epi::NPRE != 0 && last) { E.pre(sv, cur, wr, fr); PG8_WAIT_V(16); } else { PG8_WAIT_V(8); }
;             PG8_WAIT_L(0); PG8_BAR; PG8_MMA(0, 0, At, B0); PG8_MMA(0, 1, At, B1); PG8_BAR; PG8_SCHED;
;             PG8_LDA(At, 0, 1); PG8_STAGE(PG8_SB(0, 0), b2, voffB); PG8_STAGE(PG8_SB(0, 1), b2 + hsB, voffB); PG8_STAGE(PG8_SA(0, 0), a2, voffA);
;             if (Epi::NPRE != 0 && last) { PG8_WAIT_V(16); } else { PG8_WAIT_V(8); }
;             PG8_WAIT_L(0); PG8_BAR; PG8_MMA(1, 0, At, B0); PG8_MMA(1, 1, At, B1); PG8_BAR; PG8_SCHED;
.LBB0_959:
	ds_read_b128 v[88:91], v196
	ds_read_b128 v[92:95], v196 offset:1024
	ds_read_b128 v[104:107], v196 offset:2048
	ds_read_b128 v[108:111], v196 offset:3072
	ds_read_b128 v[144:147], v197
	ds_read_b128 v[148:151], v197 offset:1024
	ds_read_b128 v[152:155], v197 offset:2048
	ds_read_b128 v[156:159], v197 offset:3072
	s_add_i32 s51, s30, 2
	s_add_u32 s31, s28, 0xfffc0080
	s_addc_u32 s34, s29, -1
	s_cmp_eq_u32 s42, s30
	s_cselect_b32 s30, s48, s49
	s_cselect_b32 s35, s19, s34
	s_cselect_b32 s34, s21, s31
	s_cselect_b32 s31, s47, s50
	s_add_i32 m0, s5, 0xc000
	ds_read_b128 v[160:163], v198
	ds_read_b128 v[180:183], v198 offset:1024
	ds_read_b128 v[184:187], v198 offset:2048
	ds_read_b128 v[188:191], v198 offset:3072
	ds_read_b128 v[200:203], v198 offset:4096
	ds_read_b128 v[204:207], v198 offset:5120
	ds_read_b128 v[208:211], v198 offset:6144
	ds_read_b128 v[212:215], v198 offset:7168
	global_load_lds_dwordx4 v172, s[28:29]
	s_add_i32 m0, s5, 0xe000
	s_nop 0
	global_load_lds_dwordx4 v174, s[28:29]
	s_waitcnt vmcnt(8)
	s_waitcnt lgkmcnt(0)
	s_setprio 1
	s_barrier
	v_mfma_f32_16x16x32_bf16 v[136:139], v[88:91], v[160:163], v[136:139]
	v_mfma_f32_16x16x32_bf16 v[140:143], v[104:107], v[160:163], v[140:143]
	v_mfma_f32_16x16x32_bf16 v[124:127], v[88:91], v[184:187], v[124:127]
	v_mfma_f32_16x16x32_bf16 v[120:123], v[104:107], v[184:187], v[120:123]
	v_mfma_f32_16x16x32_bf16 v[100:103], v[88:91], v[200:203], v[100:103]
	v_mfma_f32_16x16x32_bf16 v[96:99], v[104:107], v[200:203], v[96:99]
	v_mfma_f32_16x16x32_bf16 v[76:79], v[88:91], v[208:211], v[76:79]
	v_mfma_f32_16x16x32_bf16 v[72:75], v[104:107], v[208:211], v[72:75]
	v_mfma_f32_16x16x32_bf16 v[136:139], v[92:95], v[180:183], v[136:139]
	v_mfma_f32_16x16x32_bf16 v[140:143], v[108:111], v[180:183], v[140:143]
	v_mfma_f32_16x16x32_bf16 v[124:127], v[92:95], v[188:191], v[124:127]
	v_mfma_f32_16x16x32_bf16 v[120:123], v[108:111], v[188:191], v[120:123]
	v_mfma_f32_16x16x32_bf16 v[100:103], v[92:95], v[204:207], v[100:103]
	v_mfma_f32_16x16x32_bf16 v[96:99], v[108:111], v[204:207], v[96:99]
	v_mfma_f32_16x16x32_bf16 v[76:79], v[92:95], v[212:215], v[76:79]
	v_mfma_f32_16x16x32_bf16 v[72:75], v[108:111], v[212:215], v[72:75]
	v_mfma_f32_16x16x32_bf16 v[132:135], v[144:147], v[160:163], v[132:135]
	v_mfma_f32_16x16x32_bf16 v[128:131], v[152:155], v[160:163], v[128:131]
	v_mfma_f32_16x16x32_bf16 v[116:119], v[144:147], v[184:187], v[116:119]
	v_mfma_f32_16x16x32_bf16 v[112:115], v[152:155], v[184:187], v[112:115]
	v_mfma_f32_16x16x32_bf16 v[84:87], v[144:147], v[200:203], v[84:87]
	v_mfma_f32_16x16x32_bf16 v[80:83], v[152:155], v[200:203], v[80:83]
	v_mfma_f32_16x16x32_bf16 v[68:71], v[144:147], v[208:211], v[68:71]
	v_mfma_f32_16x16x32_bf16 v[64:67], v[152:155], v[208:211], v[64:67]
	v_mfma_f32_16x16x32_bf16 v[132:135], v[148:151], v[180:183], v[132:135]
	v_mfma_f32_16x16x32_bf16 v[128:131], v[156:159], v[180:183], v[128:131]
	v_mfma_f32_16x16x32_bf16 v[116:119], v[148:151], v[188:191], v[116:119]
	v_mfma_f32_16x16x32_bf16 v[112:115], v[156:159], v[188:191], v[112:115]
	v_mfma_f32_16x16x32_bf16 v[84:87], v[148:151], v[204:207], v[84:87]
	v_mfma_f32_16x16x32_bf16 v[80:83], v[156:159], v[204:207], v[80:83]
	v_mfma_f32_16x16x32_bf16 v[68:71], v[148:151], v[212:215], v[68:71]
	v_mfma_f32_16x16x32_bf16 v[64:67], v[156:159], v[212:215], v[64:67]
	s_barrier
	s_setprio 0
	s_add_u32 s98, s30, s12
	s_addc_u32 s99, s31, s13
	s_add_u32 s100, s34, s12
	s_addc_u32 s101, s35, s13
	s_add_i32 s52, s44, s3
	s_mov_b32 m0, s52
	ds_read_b128 v[160:163], v198 offset:16384
	ds_read_b128 v[180:183], v198 offset:17408
	ds_read_b128 v[184:187], v198 offset:18432
	ds_read_b128 v[188:191], v198 offset:19456
	ds_read_b128 v[200:203], v198 offset:20480
	ds_read_b128 v[204:207], v198 offset:21504
	ds_read_b128 v[208:211], v198 offset:22528
	ds_read_b128 v[212:215], v198 offset:23552
	global_load_lds_dwordx4 v168, s[30:31]
	s_add_i32 m0, s52, 0x2000
	s_add_u32 s52, s30, 0x40000
	s_addc_u32 s53, s31, 0
	s_add_i32 s54, s45, s3
	global_load_lds_dwordx4 v164, s[30:31]
	s_mov_b32 m0, s54
	s_nop 0
	global_load_lds_dwordx4 v168, s[52:53]
	s_add_i32 m0, s54, 0x2000
	s_nop 0
	global_load_lds_dwordx4 v164, s[52:53]
	s_mov_b32 m0, s5
	s_nop 0
	global_load_lds_dwordx4 v170, s[34:35]
	s_mov_b32 m0, s27
	s_nop 0
	global_load_lds_dwordx4 v166, s[34:35]
	s_waitcnt vmcnt(8)
	s_waitcnt lgkmcnt(0)
	s_setprio 1
	s_barrier
	v_mfma_f32_16x16x32_bf16 v[60:63], v[88:91], v[160:163], v[60:63]
	v_mfma_f32_16x16x32_bf16 v[56:59], v[104:107], v[160:163], v[56:59]
	v_mfma_f32_16x16x32_bf16 v[44:47], v[88:91], v[184:187], v[44:47]
	v_mfma_f32_16x16x32_bf16 v[40:43], v[104:107], v[184:187], v[40:43]
	v_mfma_f32_16x16x32_bf16 v[28:31], v[88:91], v[200:203], v[28:31]
	v_mfma_f32_16x16x32_bf16 v[24:27], v[104:107], v[200:203], v[24:27]
	v_mfma_f32_16x16x32_bf16 v[12:15], v[88:91], v[208:211], v[12:15]
	v_mfma_f32_16x16x32_bf16 v[8:11], v[104:107], v[208:211], v[8:11]
	v_mfma_f32_16x16x32_bf16 v[60:63], v[92:95], v[180:183], v[60:63]
	v_mfma_f32_16x16x32_bf16 v[56:59], v[108:111], v[180:183], v[56:59]
	v_mfma_f32_16x16x32_bf16 v[44:47], v[92:95], v[188:191], v[44:47]
	v_mfma_f32_16x16x32_bf16 v[40:43], v[108:111], v[188:191], v[40:43]
	v_mfma_f32_16x16x32_bf16 v[28:31], v[92:95], v[204:207], v[28:31]
	v_mfma_f32_16x16x32_bf16 v[24:27], v[108:111], v[204:207], v[24:27]
	v_mfma_f32_16x16x32_bf16 v[12:15], v[92:95], v[212:215], v[12:15]
	v_mfma_f32_16x16x32_bf16 v[8:11], v[108:111], v[212:215], v[8:11]
	v_mfma_f32_16x16x32_bf16 v[52:55], v[144:147], v[160:163], v[52:55]
	v_mfma_f32_16x16x32_bf16 v[48:51], v[152:155], v[160:163], v[48:51]
	v_mfma_f32_16x16x32_bf16 v[36:39], v[144:147], v[184:187], v[36:39]
	v_mfma_f32_16x16x32_bf16 v[32:35], v[152:155], v[184:187], v[32:35]
	v_mfma_f32_16x16x32_bf16 v[20:23], v[144:147], v[200:203], v[20:23]
	v_mfma_f32_16x16x32_bf16 v[16:19], v[152:155], v[200:203], v[16:19]
	v_mfma_f32_16x16x32_bf16 v[4:7], v[144:147], v[208:211], v[4:7]
	v_mfma_f32_16x16x32_bf16 v[0:3], v[152:155], v[208:211], v[0:3]
	v_mfma_f32_16x16x32_bf16 v[52:55], v[148:151], v[180:183], v[52:55]
	v_mfma_f32_16x16x32_bf16 v[48:51], v[156:159], v[180:183], v[48:51]
	v_mfma_f32_16x16x32_bf16 v[36:39], v[148:151], v[188:191], v[36:39]
	v_mfma_f32_16x16x32_bf16 v[32:35], v[156:159], v[188:191], v[32:35]
	v_mfma_f32_16x16x32_bf16 v[20:23], v[148:151], v[204:207], v[20:23]
	v_mfma_f32_16x16x32_bf16 v[16:19], v[156:159], v[204:207], v[16:19]
	v_mfma_f32_16x16x32_bf16 v[4:7], v[148:151], v[212:215], v[4:7]
	v_mfma_f32_16x16x32_bf16 v[0:3], v[156:159], v[212:215], v[0:3]
	s_barrier
; #define PG8_STAGE(bufoff, gbase, voff) do { _Pragma("unroll") for (int _i = 0; _i < 2; ++_i) \
;         __builtin_amdgcn_global_load_lds((const unsigned*)((const char*)(gbase) + (voff)[_i]), (LAS unsigned*)(lds + (bufoff) + ldsw + _i * 8192), 16, 0, ((voff) == voffA ? AUXA : 0)); } while (0)
; #define PG8_LDA(dst, b, h) do { _Pragma("unroll") for (int m = 0; m < 4; ++m) _Pragma("unroll") for (int k = 0; k < 2; ++k) dst[m][k] = *(const LAS bf16x8*)(lds + PG8_SA(b, h) + aoff + m * 2048 + k * 1024); } while (0)
; #define PG8_LDB(dst, b, h) do { _Pragma("unroll") for (int n = 0; n < 2; ++n) _Pragma("unroll") for (int k = 0; k < 2; ++k) dst[n][k] = *(const LAS bf16x8*)(lds + PG8_SB(b, h) + boff + n * 2048 + k * 1024); } while (0)
; #define PG8_MMA(ai, bj, At, Bt) do { __builtin_amdgcn_s_setprio(1); _Pragma("unroll") for (int m = 0; m < 4; ++m) _Pragma("unroll") for (int n = 0; n < 2; ++n) _Pragma("unroll") for (int k = 0; k < 2; ++k) \
;         acc[ai][bj][m][n] = __builtin_amdgcn_mfma_f32_16x16x32_bf16(Bt[n][k], At[m][k], acc[ai][bj][m][n], 0, 0, 0); __builtin_amdgcn_s_setprio(0); } while (0)
; #define PG8_WAIT_V(n) asm volatile("s_waitcnt vmcnt(" #n ")" ::: "memory")
; #define PG8_WAIT_L(n) asm volatile("s_waitcnt lgkmcnt(" #n ")" ::: "memory")
; #define PG8_BAR __builtin_amdgcn_s_barrier()
; #define PG8_SCHED __builtin_amdgcn_sched_barrier(0)
;     ...
;             PG8_LDB(B0, 1, 0); PG8_LDB(B1, 1, 1); PG8_SCHED; PG8_LDA(At, 1, 0); PG8_STAGE(PG8_SA(0, 1), a2 + hsA, voffA);
;             PG8_WAIT_V(8); PG8_WAIT_L(0); PG8_BAR; PG8_MMA(0, 0, At, B0); PG8_MMA(0, 1, At, B1); PG8_BAR; PG8_SCHED;
;             PG8_LDA(At, 1, 1); PG8_STAGE(PG8_SB(1, 0), b3, voffB); PG8_STAGE(PG8_SB(1, 1), b3 + hsB, voffB); PG8_STAGE(PG8_SA(1, 0), a3, voffA);
;             PG8_WAIT_V(8); PG8_WAIT_L(0); PG8_BAR; PG8_MMA(1, 0, At, B0); PG8_MMA(1, 1, At, B1); PG8_BAR; PG8_SCHED;
	s_setprio 0
	s_add_i32 s52, 0, 0x18000
	s_add_i32 s53, 0, 0x1c000
	v_add_u32_e32 v108, s52, v194
	v_add_u32_e32 v156, s53, v194
	ds_read_b128 v[88:91], v108
	ds_read_b128 v[92:95], v108 offset:1024
	ds_read_b128 v[104:107], v108 offset:2048
	ds_read_b128 v[108:111], v108 offset:3072
	ds_read_b128 v[144:147], v156
	ds_read_b128 v[148:151], v156 offset:1024
	ds_read_b128 v[152:155], v156 offset:2048
	ds_read_b128 v[156:159], v156 offset:3072
	s_add_u32 s34, s34, 0x40000
	s_addc_u32 s35, s35, 0
	s_mov_b32 m0, s36
	ds_read_b128 v[160:163], v198 offset:32768
	ds_read_b128 v[180:183], v198 offset:33792
	ds_read_b128 v[184:187], v198 offset:34816
	ds_read_b128 v[188:191], v198 offset:35840
	ds_read_b128 v[200:203], v198 offset:36864
	ds_read_b128 v[204:207], v198 offset:37888
	ds_read_b128 v[208:211], v198 offset:38912
	ds_read_b128 v[212:215], v198 offset:39936
	global_load_lds_dwordx4 v170, s[34:35]
	s_mov_b32 m0, s37
	s_nop 0
	global_load_lds_dwordx4 v166, s[34:35]
	s_waitcnt vmcnt(8)
	s_waitcnt lgkmcnt(0)
	s_setprio 1
	s_barrier
	v_mfma_f32_16x16x32_bf16 v[136:139], v[88:91], v[160:163], v[136:139]
	v_mfma_f32_16x16x32_bf16 v[140:143], v[104:107], v[160:163], v[140:143]
	v_mfma_f32_16x16x32_bf16 v[124:127], v[88:91], v[184:187], v[124:127]
	v_mfma_f32_16x16x32_bf16 v[120:123], v[104:107], v[184:187], v[120:123]
	v_mfma_f32_16x16x32_bf16 v[100:103], v[88:91], v[200:203], v[100:103]
	v_mfma_f32_16x16x32_bf16 v[96:99], v[104:107], v[200:203], v[96:99]
	v_mfma_f32_16x16x32_bf16 v[76:79], v[88:91], v[208:211], v[76:79]
	v_mfma_f32_16x16x32_bf16 v[72:75], v[104:107], v[208:211], v[72:75]
	v_mfma_f32_16x16x32_bf16 v[136:139], v[92:95], v[180:183], v[136:139]
	v_mfma_f32_16x16x32_bf16 v[140:143], v[108:111], v[180:183], v[140:143]
	v_mfma_f32_16x16x32_bf16 v[124:127], v[92:95], v[188:191], v[124:127]
	v_mfma_f32_16x16x32_bf16 v[120:123], v[108:111], v[188:191], v[120:123]
	v_mfma_f32_16x16x32_bf16 v[100:103], v[92:95], v[204:207], v[100:103]
	v_mfma_f32_16x16x32_bf16 v[96:99], v[108:111], v[204:207], v[96:99]
	v_mfma_f32_16x16x32_bf16 v[76:79], v[92:95], v[212:215], v[76:79]
	v_mfma_f32_16x16x32_bf16 v[72:75], v[108:111], v[212:215], v[72:75]
	v_mfma_f32_16x16x32_bf16 v[132:135], v[144:147], v[160:163], v[132:135]
	v_mfma_f32_16x16x32_bf16 v[128:131], v[152:155], v[160:163], v[128:131]
	v_mfma_f32_16x16x32_bf16 v[116:119], v[144:147], v[184:187], v[116:119]
	v_mfma_f32_16x16x32_bf16 v[112:115], v[152:155], v[184:187], v[112:115]
	v_mfma_f32_16x16x32_bf16 v[84:87], v[144:147], v[200:203], v[84:87]
	v_mfma_f32_16x16x32_bf16 v[80:83], v[152:155], v[200:203], v[80:83]
	v_mfma_f32_16x16x32_bf16 v[68:71], v[144:147], v[208:211], v[68:71]
	v_mfma_f32_16x16x32_bf16 v[64:67], v[152:155], v[208:211], v[64:67]
	v_mfma_f32_16x16x32_bf16 v[132:135], v[148:151], v[180:183], v[132:135]
	v_mfma_f32_16x16x32_bf16 v[128:131], v[156:159], v[180:183], v[128:131]
	v_mfma_f32_16x16x32_bf16 v[116:119], v[148:151], v[188:191], v[116:119]
	v_mfma_f32_16x16x32_bf16 v[112:115], v[156:159], v[188:191], v[112:115]
	v_mfma_f32_16x16x32_bf16 v[84:87], v[148:151], v[204:207], v[84:87]
	v_mfma_f32_16x16x32_bf16 v[80:83], v[156:159], v[204:207], v[80:83]
	v_mfma_f32_16x16x32_bf16 v[68:71], v[148:151], v[212:215], v[68:71]
	v_mfma_f32_16x16x32_bf16 v[64:67], v[156:159], v[212:215], v[64:67]
	s_barrier
	s_setprio 0
	s_add_i32 s34, s52, s3
	s_mov_b32 m0, s34
	ds_read_b128 v[160:163], v198 offset:49152
	ds_read_b128 v[180:183], v198 offset:50176
	ds_read_b128 v[184:187], v198 offset:51200
	ds_read_b128 v[188:191], v198 offset:52224
	ds_read_b128 v[200:203], v198 offset:53248
	ds_read_b128 v[204:207], v198 offset:54272
	ds_read_b128 v[208:211], v198 offset:55296
	ds_read_b128 v[212:215], v198 offset:56320
	global_load_lds_dwordx4 v168, s[98:99]
	s_add_i32 m0, s34, 0x2000
	s_add_u32 s30, s30, 0x40080
	s_addc_u32 s31, s31, 0
	s_add_i32 s34, s53, s3
	global_load_lds_dwordx4 v164, s[98:99]
	s_mov_b32 m0, s34
	s_nop 0
	global_load_lds_dwordx4 v168, s[30:31]
	s_add_i32 m0, s34, 0x2000
	s_nop 0
	global_load_lds_dwordx4 v164, s[30:31]
	s_mov_b32 m0, s40
	s_nop 0
	global_load_lds_dwordx4 v170, s[100:101]
	s_mov_b32 m0, s41
	s_nop 0
	global_load_lds_dwordx4 v166, s[100:101]
	s_waitcnt vmcnt(8)
	s_waitcnt lgkmcnt(0)
	s_setprio 1
	s_barrier
	v_mfma_f32_16x16x32_bf16 v[60:63], v[88:91], v[160:163], v[60:63]
	v_mfma_f32_16x16x32_bf16 v[56:59], v[104:107], v[160:163], v[56:59]
	v_mfma_f32_16x16x32_bf16 v[44:47], v[88:91], v[184:187], v[44:47]
	v_mfma_f32_16x16x32_bf16 v[40:43], v[104:107], v[184:187], v[40:43]
	v_mfma_f32_16x16x32_bf16 v[28:31], v[88:91], v[200:203], v[28:31]
	v_mfma_f32_16x16x32_bf16 v[24:27], v[104:107], v[200:203], v[24:27]
	v_mfma_f32_16x16x32_bf16 v[12:15], v[88:91], v[208:211], v[12:15]
	v_mfma_f32_16x16x32_bf16 v[8:11], v[104:107], v[208:211], v[8:11]
	v_mfma_f32_16x16x32_bf16 v[60:63], v[92:95], v[180:183], v[60:63]
	v_mfma_f32_16x16x32_bf16 v[56:59], v[108:111], v[180:183], v[56:59]
	v_mfma_f32_16x16x32_bf16 v[44:47], v[92:95], v[188:191], v[44:47]
	v_mfma_f32_16x16x32_bf16 v[40:43], v[108:111], v[188:191], v[40:43]
	v_mfma_f32_16x16x32_bf16 v[28:31], v[92:95], v[204:207], v[28:31]
	v_mfma_f32_16x16x32_bf16 v[24:27], v[108:111], v[204:207], v[24:27]
	v_mfma_f32_16x16x32_bf16 v[12:15], v[92:95], v[212:215], v[12:15]
	v_mfma_f32_16x16x32_bf16 v[8:11], v[108:111], v[212:215], v[8:11]
	v_mfma_f32_16x16x32_bf16 v[52:55], v[144:147], v[160:163], v[52:55]
	v_mfma_f32_16x16x32_bf16 v[48:51], v[152:155], v[160:163], v[48:51]
	v_mfma_f32_16x16x32_bf16 v[36:39], v[144:147], v[184:187], v[36:39]
	v_mfma_f32_16x16x32_bf16 v[32:35], v[152:155], v[184:187], v[32:35]
	v_mfma_f32_16x16x32_bf16 v[20:23], v[144:147], v[200:203], v[20:23]
	v_mfma_f32_16x16x32_bf16 v[16:19], v[152:155], v[200:203], v[16:19]
	v_mfma_f32_16x16x32_bf16 v[4:7], v[144:147], v[208:211], v[4:7]
	v_mfma_f32_16x16x32_bf16 v[0:3], v[152:155], v[208:211], v[0:3]
	v_mfma_f32_16x16x32_bf16 v[52:55], v[148:151], v[180:183], v[52:55]
	v_mfma_f32_16x16x32_bf16 v[48:51], v[156:159], v[180:183], v[48:51]
	v_mfma_f32_16x16x32_bf16 v[36:39], v[148:151], v[188:191], v[36:39]
	v_mfma_f32_16x16x32_bf16 v[32:35], v[156:159], v[188:191], v[32:35]
	v_mfma_f32_16x16x32_bf16 v[20:23], v[148:151], v[204:207], v[20:23]
	v_mfma_f32_16x16x32_bf16 v[16:19], v[156:159], v[204:207], v[16:19]
	v_mfma_f32_16x16x32_bf16 v[4:7], v[148:151], v[212:215], v[4:7]
	v_mfma_f32_16x16x32_bf16 v[0:3], v[156:159], v[212:215], v[0:3]
	s_barrier
	s_setprio 0
	s_add_u32 s28, s28, 0x100
	s_addc_u32 s29, s29, 0
	s_add_u32 s49, s49, 0x100
	s_addc_u32 s50, s50, 0
	s_cmp_ge_i32 s51, s39
	s_mov_b32 s30, s51
	s_cbranch_scc0 .LBB0_959

; #define PG8_STAGE(bufoff, gbase, voff) do { _Pragma("unroll") for (int _i = 0; _i < 2; ++_i) \
;         __builtin_amdgcn_global_load_lds((const unsigned*)((const char*)(gbase) + (voff)[_i]), (LAS unsigned*)(lds + (bufoff) + ldsw + _i * 8192), 16, 0, ((voff) == voffA ? AUXA : 0)); } while (0)
; #define PG8_LDA(dst, b, h) do { _Pragma("unroll") for (int m = 0; m < 4; ++m) _Pragma("unroll") for (int k = 0; k < 2; ++k) dst[m][k] = *(const LAS bf16x8*)(lds + PG8_SA(b, h) + aoff + m * 2048 + k * 1024); } while (0)
; #define PG8_LDB(dst, b, h) do { _Pragma("unroll") for (int n = 0; n < 2; ++n) _Pragma("unroll") for (int k = 0; k < 2; ++k) dst[n][k] = *(const LAS bf16x8*)(lds + PG8_SB(b, h) + boff + n * 2048 + k * 1024); } while (0)
; #define PG8_MMA(ai, bj, At, Bt) do { __builtin_amdgcn_s_setprio(1); _Pragma("unroll") for (int m = 0; m < 4; ++m) _Pragma("unroll") for (int n = 0; n < 2; ++n) _Pragma("unroll") for (int k = 0; k < 2; ++k) \
;         acc[ai][bj][m][n] = __builtin_amdgcn_mfma_f32_16x16x32_bf16(Bt[n][k], At[m][k], acc[ai][bj][m][n], 0, 0, 0); __builtin_amdgcn_s_setprio(0); } while (0)
; #define PG8_WAIT_V(n) asm volatile("s_waitcnt vmcnt(" #n ")" ::: "memory")
; #define PG8_WAIT_L(n) asm volatile("s_waitcnt lgkmcnt(" #n ")" ::: "memory")
; #define PG8_BAR __builtin_amdgcn_s_barrier()
; #define PG8_SCHED __builtin_amdgcn_sched_barrier(0)
;     ...
;             PG8_LDB(B0, 0, 0); PG8_LDB(B1, 0, 1); PG8_SCHED; PG8_LDA(At, 0, 0); PG8_STAGE(PG8_SA(1, 1), a1 + hsA, voffA);
;             if (Epi::NPRE != 0 && last) { E.pre(sv, cur, wr, fr); PG8_WAIT_V(16); } else { PG8_WAIT_V(8); }
;             PG8_WAIT_L(0); PG8_BAR; PG8_MMA(0, 0, At, B0); PG8_MMA(0, 1, At, B1); PG8_BAR; PG8_SCHED;
;             PG8_LDA(At, 0, 1); PG8_STAGE(PG8_SB(0, 0), b2, voffB); PG8_STAGE(PG8_SB(0, 1), b2 + hsB, voffB); PG8_STAGE(PG8_SA(0, 0), a2, voffA);
;             if (Epi::NPRE != 0 && last) { PG8_WAIT_V(16); } else { PG8_WAIT_V(8); }
;             PG8_WAIT_L(0); PG8_BAR; PG8_MMA(1, 0, At, B0); PG8_MMA(1, 1, At, B1); PG8_BAR; PG8_SCHED;
.LBB0_1040:
	ds_read_b128 v[150:153], v147
	ds_read_b128 v[154:157], v147 offset:1024
	ds_read_b128 v[158:161], v147 offset:2048
	ds_read_b128 v[162:165], v147 offset:3072
	ds_read_b128 v[166:169], v148
	ds_read_b128 v[170:173], v148 offset:1024
	ds_read_b128 v[174:177], v148 offset:2048
	ds_read_b128 v[178:181], v148 offset:3072
	s_add_i32 s56, s30, 2
	s_add_u32 s31, s28, 0xfffc0080
	s_addc_u32 s34, s29, -1
	s_cmp_eq_u32 s47, s30
	s_cselect_b32 s30, s53, s54
	s_cselect_b32 s35, s21, s34
	s_cselect_b32 s34, s23, s31
	s_cselect_b32 s31, s52, s55
	s_add_i32 m0, s19, 0xc000
	ds_read_b128 v[182:185], v149
	ds_read_b128 v[186:189], v149 offset:1024
	ds_read_b128 v[190:193], v149 offset:2048
	ds_read_b128 v[194:197], v149 offset:3072
	ds_read_b128 v[198:201], v149 offset:4096
	ds_read_b128 v[202:205], v149 offset:5120
	ds_read_b128 v[206:209], v149 offset:6144
	ds_read_b128 v[210:213], v149 offset:7168
	global_load_lds_dwordx4 v136, s[28:29]
	s_add_i32 m0, s19, 0xe000
	s_nop 0
	global_load_lds_dwordx4 v138, s[28:29]
	s_waitcnt vmcnt(8)
	s_waitcnt lgkmcnt(0)
	s_setprio 1
	s_barrier
	v_mfma_f32_16x16x32_bf16 v[124:127], v[150:153], v[182:185], v[124:127]
	v_mfma_f32_16x16x32_bf16 v[120:123], v[158:161], v[182:185], v[120:123]
	v_mfma_f32_16x16x32_bf16 v[108:111], v[150:153], v[190:193], v[108:111]
	v_mfma_f32_16x16x32_bf16 v[104:107], v[158:161], v[190:193], v[104:107]
	v_mfma_f32_16x16x32_bf16 v[92:95], v[150:153], v[198:201], v[92:95]
	v_mfma_f32_16x16x32_bf16 v[88:91], v[158:161], v[198:201], v[88:91]
	v_mfma_f32_16x16x32_bf16 v[76:79], v[150:153], v[206:209], v[76:79]
	v_mfma_f32_16x16x32_bf16 v[72:75], v[158:161], v[206:209], v[72:75]
	v_mfma_f32_16x16x32_bf16 v[124:127], v[154:157], v[186:189], v[124:127]
	v_mfma_f32_16x16x32_bf16 v[120:123], v[162:165], v[186:189], v[120:123]
	v_mfma_f32_16x16x32_bf16 v[108:111], v[154:157], v[194:197], v[108:111]
	v_mfma_f32_16x16x32_bf16 v[104:107], v[162:165], v[194:197], v[104:107]
	v_mfma_f32_16x16x32_bf16 v[92:95], v[154:157], v[202:205], v[92:95]
	v_mfma_f32_16x16x32_bf16 v[88:91], v[162:165], v[202:205], v[88:91]
	v_mfma_f32_16x16x32_bf16 v[76:79], v[154:157], v[210:213], v[76:79]
	v_mfma_f32_16x16x32_bf16 v[72:75], v[162:165], v[210:213], v[72:75]
	v_mfma_f32_16x16x32_bf16 v[116:119], v[166:169], v[182:185], v[116:119]
	v_mfma_f32_16x16x32_bf16 v[112:115], v[174:177], v[182:185], v[112:115]
	v_mfma_f32_16x16x32_bf16 v[100:103], v[166:169], v[190:193], v[100:103]
	v_mfma_f32_16x16x32_bf16 v[96:99], v[174:177], v[190:193], v[96:99]
	v_mfma_f32_16x16x32_bf16 v[84:87], v[166:169], v[198:201], v[84:87]
	v_mfma_f32_16x16x32_bf16 v[80:83], v[174:177], v[198:201], v[80:83]
	v_mfma_f32_16x16x32_bf16 v[68:71], v[166:169], v[206:209], v[68:71]
	v_mfma_f32_16x16x32_bf16 v[64:67], v[174:177], v[206:209], v[64:67]
	v_mfma_f32_16x16x32_bf16 v[116:119], v[170:173], v[186:189], v[116:119]
	v_mfma_f32_16x16x32_bf16 v[112:115], v[178:181], v[186:189], v[112:115]
	v_mfma_f32_16x16x32_bf16 v[100:103], v[170:173], v[194:197], v[100:103]
	v_mfma_f32_16x16x32_bf16 v[96:99], v[178:181], v[194:197], v[96:99]
	v_mfma_f32_16x16x32_bf16 v[84:87], v[170:173], v[202:205], v[84:87]
	v_mfma_f32_16x16x32_bf16 v[80:83], v[178:181], v[202:205], v[80:83]
	v_mfma_f32_16x16x32_bf16 v[68:71], v[170:173], v[210:213], v[68:71]
	v_mfma_f32_16x16x32_bf16 v[64:67], v[178:181], v[210:213], v[64:67]
	s_barrier
	s_setprio 0
	s_add_u32 s98, s30, s14
	s_addc_u32 s99, s31, s15
	s_add_u32 s100, s34, s14
	s_addc_u32 s101, s35, s15
	s_add_i32 s57, s49, s37
	s_mov_b32 m0, s57
	ds_read_b128 v[182:185], v149 offset:16384
	ds_read_b128 v[186:189], v149 offset:17408
	ds_read_b128 v[190:193], v149 offset:18432
	ds_read_b128 v[194:197], v149 offset:19456
	ds_read_b128 v[198:201], v149 offset:20480
	ds_read_b128 v[202:205], v149 offset:21504
	ds_read_b128 v[206:209], v149 offset:22528
	ds_read_b128 v[210:213], v149 offset:23552
	global_load_lds_dwordx4 v132, s[30:31]
	s_add_i32 m0, s57, 0x2000
	s_add_u32 s58, s30, 0x40000
	s_addc_u32 s59, s31, 0
	s_add_i32 s57, s50, s37
	global_load_lds_dwordx4 v128, s[30:31]
	s_mov_b32 m0, s57
	s_nop 0
	global_load_lds_dwordx4 v132, s[58:59]
	s_add_i32 m0, s57, 0x2000
	s_nop 0
	global_load_lds_dwordx4 v128, s[58:59]
	s_mov_b32 m0, s19
	s_nop 0
	global_load_lds_dwordx4 v134, s[34:35]
	s_mov_b32 m0, s40
	s_nop 0
	global_load_lds_dwordx4 v130, s[34:35]
	s_waitcnt vmcnt(8)
	s_waitcnt lgkmcnt(0)
	s_setprio 1
	s_barrier
	v_mfma_f32_16x16x32_bf16 v[60:63], v[150:153], v[182:185], v[60:63]
	v_mfma_f32_16x16x32_bf16 v[56:59], v[158:161], v[182:185], v[56:59]
	v_mfma_f32_16x16x32_bf16 v[44:47], v[150:153], v[190:193], v[44:47]
	v_mfma_f32_16x16x32_bf16 v[40:43], v[158:161], v[190:193], v[40:43]
	v_mfma_f32_16x16x32_bf16 v[28:31], v[150:153], v[198:201], v[28:31]
	v_mfma_f32_16x16x32_bf16 v[24:27], v[158:161], v[198:201], v[24:27]
	v_mfma_f32_16x16x32_bf16 v[12:15], v[150:153], v[206:209], v[12:15]
	v_mfma_f32_16x16x32_bf16 v[8:11], v[158:161], v[206:209], v[8:11]
	v_mfma_f32_16x16x32_bf16 v[60:63], v[154:157], v[186:189], v[60:63]
	v_mfma_f32_16x16x32_bf16 v[56:59], v[162:165], v[186:189], v[56:59]
	v_mfma_f32_16x16x32_bf16 v[44:47], v[154:157], v[194:197], v[44:47]
	v_mfma_f32_16x16x32_bf16 v[40:43], v[162:165], v[194:197], v[40:43]
	v_mfma_f32_16x16x32_bf16 v[28:31], v[154:157], v[202:205], v[28:31]
	v_mfma_f32_16x16x32_bf16 v[24:27], v[162:165], v[202:205], v[24:27]
	v_mfma_f32_16x16x32_bf16 v[12:15], v[154:157], v[210:213], v[12:15]
	v_mfma_f32_16x16x32_bf16 v[8:11], v[162:165], v[210:213], v[8:11]
	v_mfma_f32_16x16x32_bf16 v[52:55], v[166:169], v[182:185], v[52:55]
	v_mfma_f32_16x16x32_bf16 v[48:51], v[174:177], v[182:185], v[48:51]
	v_mfma_f32_16x16x32_bf16 v[36:39], v[166:169], v[190:193], v[36:39]
	v_mfma_f32_16x16x32_bf16 v[32:35], v[174:177], v[190:193], v[32:35]
	v_mfma_f32_16x16x32_bf16 v[20:23], v[166:169], v[198:201], v[20:23]
	v_mfma_f32_16x16x32_bf16 v[16:19], v[174:177], v[198:201], v[16:19]
	v_mfma_f32_16x16x32_bf16 v[4:7], v[166:169], v[206:209], v[4:7]
	v_mfma_f32_16x16x32_bf16 v[0:3], v[174:177], v[206:209], v[0:3]
	v_mfma_f32_16x16x32_bf16 v[52:55], v[170:173], v[186:189], v[52:55]
	v_mfma_f32_16x16x32_bf16 v[48:51], v[178:181], v[186:189], v[48:51]
	v_mfma_f32_16x16x32_bf16 v[36:39], v[170:173], v[194:197], v[36:39]
	v_mfma_f32_16x16x32_bf16 v[32:35], v[178:181], v[194:197], v[32:35]
	v_mfma_f32_16x16x32_bf16 v[20:23], v[170:173], v[202:205], v[20:23]
	v_mfma_f32_16x16x32_bf16 v[16:19], v[178:181], v[202:205], v[16:19]
	v_mfma_f32_16x16x32_bf16 v[4:7], v[170:173], v[210:213], v[4:7]
	v_mfma_f32_16x16x32_bf16 v[0:3], v[178:181], v[210:213], v[0:3]
	s_barrier
; #define PG8_STAGE(bufoff, gbase, voff) do { _Pragma("unroll") for (int _i = 0; _i < 2; ++_i) \
;         __builtin_amdgcn_global_load_lds((const unsigned*)((const char*)(gbase) + (voff)[_i]), (LAS unsigned*)(lds + (bufoff) + ldsw + _i * 8192), 16, 0, ((voff) == voffA ? AUXA : 0)); } while (0)
; #define PG8_LDA(dst, b, h) do { _Pragma("unroll") for (int m = 0; m < 4; ++m) _Pragma("unroll") for (int k = 0; k < 2; ++k) dst[m][k] = *(const LAS bf16x8*)(lds + PG8_SA(b, h) + aoff + m * 2048 + k * 1024); } while (0)
; #define PG8_LDB(dst, b, h) do { _Pragma("unroll") for (int n = 0; n < 2; ++n) _Pragma("unroll") for (int k = 0; k < 2; ++k) dst[n][k] = *(const LAS bf16x8*)(lds + PG8_SB(b, h) + boff + n * 2048 + k * 1024); } while (0)
; #define PG8_MMA(ai, bj, At, Bt) do { __builtin_amdgcn_s_setprio(1); _Pragma("unroll") for (int m = 0; m < 4; ++m) _Pragma("unroll") for (int n = 0; n < 2; ++n) _Pragma("unroll") for (int k = 0; k < 2; ++k) \
;         acc[ai][bj][m][n] = __builtin_amdgcn_mfma_f32_16x16x32_bf16(Bt[n][k], At[m][k], acc[ai][bj][m][n], 0, 0, 0); __builtin_amdgcn_s_setprio(0); } while (0)
; #define PG8_WAIT_V(n) asm volatile("s_waitcnt vmcnt(" #n ")" ::: "memory")
; #define PG8_WAIT_L(n) asm volatile("s_waitcnt lgkmcnt(" #n ")" ::: "memory")
; #define PG8_BAR __builtin_amdgcn_s_barrier()
; #define PG8_SCHED __builtin_amdgcn_sched_barrier(0)
;     ...
;             PG8_LDB(B0, 1, 0); PG8_LDB(B1, 1, 1); PG8_SCHED; PG8_LDA(At, 1, 0); PG8_STAGE(PG8_SA(0, 1), a2 + hsA, voffA);
;             PG8_WAIT_V(8); PG8_WAIT_L(0); PG8_BAR; PG8_MMA(0, 0, At, B0); PG8_MMA(0, 1, At, B1); PG8_BAR; PG8_SCHED;
;             PG8_LDA(At, 1, 1); PG8_STAGE(PG8_SB(1, 0), b3, voffB); PG8_STAGE(PG8_SB(1, 1), b3 + hsB, voffB); PG8_STAGE(PG8_SA(1, 0), a3, voffA);
;             PG8_WAIT_V(8); PG8_WAIT_L(0); PG8_BAR; PG8_MMA(1, 0, At, B0); PG8_MMA(1, 1, At, B1); PG8_BAR; PG8_SCHED;
	s_setprio 0
	s_add_i32 s57, 0, 0x18000
	s_add_i32 s58, 0, 0x1c000
	v_add_u32_e32 v162, s57, v145
	v_add_u32_e32 v178, s58, v145
	ds_read_b128 v[150:153], v162
	ds_read_b128 v[154:157], v162 offset:1024
	ds_read_b128 v[158:161], v162 offset:2048
	ds_read_b128 v[162:165], v162 offset:3072
	ds_read_b128 v[166:169], v178
	ds_read_b128 v[170:173], v178 offset:1024
	ds_read_b128 v[174:177], v178 offset:2048
	ds_read_b128 v[178:181], v178 offset:3072
	s_add_u32 s34, s34, 0x40000
	s_addc_u32 s35, s35, 0
	s_mov_b32 m0, s41
	ds_read_b128 v[182:185], v149 offset:32768
	ds_read_b128 v[186:189], v149 offset:33792
	ds_read_b128 v[190:193], v149 offset:34816
	ds_read_b128 v[194:197], v149 offset:35840
	ds_read_b128 v[198:201], v149 offset:36864
	ds_read_b128 v[202:205], v149 offset:37888
	ds_read_b128 v[206:209], v149 offset:38912
	ds_read_b128 v[210:213], v149 offset:39936
	global_load_lds_dwordx4 v134, s[34:35]
	s_mov_b32 m0, s42
	s_nop 0
	global_load_lds_dwordx4 v130, s[34:35]
	s_waitcnt vmcnt(8)
	s_waitcnt lgkmcnt(0)
	s_setprio 1
	s_barrier
	v_mfma_f32_16x16x32_bf16 v[124:127], v[150:153], v[182:185], v[124:127]
	v_mfma_f32_16x16x32_bf16 v[120:123], v[158:161], v[182:185], v[120:123]
	v_mfma_f32_16x16x32_bf16 v[108:111], v[150:153], v[190:193], v[108:111]
	v_mfma_f32_16x16x32_bf16 v[104:107], v[158:161], v[190:193], v[104:107]
	v_mfma_f32_16x16x32_bf16 v[92:95], v[150:153], v[198:201], v[92:95]
	v_mfma_f32_16x16x32_bf16 v[88:91], v[158:161], v[198:201], v[88:91]
	v_mfma_f32_16x16x32_bf16 v[76:79], v[150:153], v[206:209], v[76:79]
	v_mfma_f32_16x16x32_bf16 v[72:75], v[158:161], v[206:209], v[72:75]
	v_mfma_f32_16x16x32_bf16 v[124:127], v[154:157], v[186:189], v[124:127]
	v_mfma_f32_16x16x32_bf16 v[120:123], v[162:165], v[186:189], v[120:123]
	v_mfma_f32_16x16x32_bf16 v[108:111], v[154:157], v[194:197], v[108:111]
	v_mfma_f32_16x16x32_bf16 v[104:107], v[162:165], v[194:197], v[104:107]
	v_mfma_f32_16x16x32_bf16 v[92:95], v[154:157], v[202:205], v[92:95]
	v_mfma_f32_16x16x32_bf16 v[88:91], v[162:165], v[202:205], v[88:91]
	v_mfma_f32_16x16x32_bf16 v[76:79], v[154:157], v[210:213], v[76:79]
	v_mfma_f32_16x16x32_bf16 v[72:75], v[162:165], v[210:213], v[72:75]
	v_mfma_f32_16x16x32_bf16 v[116:119], v[166:169], v[182:185], v[116:119]
	v_mfma_f32_16x16x32_bf16 v[112:115], v[174:177], v[182:185], v[112:115]
	v_mfma_f32_16x16x32_bf16 v[100:103], v[166:169], v[190:193], v[100:103]
	v_mfma_f32_16x16x32_bf16 v[96:99], v[174:177], v[190:193], v[96:99]
	v_mfma_f32_16x16x32_bf16 v[84:87], v[166:169], v[198:201], v[84:87]
	v_mfma_f32_16x16x32_bf16 v[80:83], v[174:177], v[198:201], v[80:83]
	v_mfma_f32_16x16x32_bf16 v[68:71], v[166:169], v[206:209], v[68:71]
	v_mfma_f32_16x16x32_bf16 v[64:67], v[174:177], v[206:209], v[64:67]
	v_mfma_f32_16x16x32_bf16 v[116:119], v[170:173], v[186:189], v[116:119]
	v_mfma_f32_16x16x32_bf16 v[112:115], v[178:181], v[186:189], v[112:115]
	v_mfma_f32_16x16x32_bf16 v[100:103], v[170:173], v[194:197], v[100:103]
	v_mfma_f32_16x16x32_bf16 v[96:99], v[178:181], v[194:197], v[96:99]
	v_mfma_f32_16x16x32_bf16 v[84:87], v[170:173], v[202:205], v[84:87]
	v_mfma_f32_16x16x32_bf16 v[80:83], v[178:181], v[202:205], v[80:83]
	v_mfma_f32_16x16x32_bf16 v[68:71], v[170:173], v[210:213], v[68:71]
	v_mfma_f32_16x16x32_bf16 v[64:67], v[178:181], v[210:213], v[64:67]
	s_barrier
	s_setprio 0
	s_add_i32 s34, s57, s37
	s_mov_b32 m0, s34
	ds_read_b128 v[182:185], v149 offset:49152
	ds_read_b128 v[186:189], v149 offset:50176
	ds_read_b128 v[190:193], v149 offset:51200
	ds_read_b128 v[194:197], v149 offset:52224
	ds_read_b128 v[198:201], v149 offset:53248
	ds_read_b128 v[202:205], v149 offset:54272
	ds_read_b128 v[206:209], v149 offset:55296
	ds_read_b128 v[210:213], v149 offset:56320
	global_load_lds_dwordx4 v132, s[98:99]
	s_add_i32 m0, s34, 0x2000
	s_add_u32 s30, s30, 0x40080
	s_addc_u32 s31, s31, 0
	s_add_i32 s34, s58, s37
	global_load_lds_dwordx4 v128, s[98:99]
	s_mov_b32 m0, s34
	s_nop 0
	global_load_lds_dwordx4 v132, s[30:31]
	s_add_i32 m0, s34, 0x2000
	s_nop 0
	global_load_lds_dwordx4 v128, s[30:31]
	s_mov_b32 m0, s45
	s_nop 0
	global_load_lds_dwordx4 v134, s[100:101]
	s_mov_b32 m0, s46
	s_nop 0
	global_load_lds_dwordx4 v130, s[100:101]
	s_waitcnt vmcnt(8)
	s_waitcnt lgkmcnt(0)
	s_setprio 1
	s_barrier
	v_mfma_f32_16x16x32_bf16 v[60:63], v[150:153], v[182:185], v[60:63]
	v_mfma_f32_16x16x32_bf16 v[56:59], v[158:161], v[182:185], v[56:59]
	v_mfma_f32_16x16x32_bf16 v[44:47], v[150:153], v[190:193], v[44:47]
	v_mfma_f32_16x16x32_bf16 v[40:43], v[158:161], v[190:193], v[40:43]
	v_mfma_f32_16x16x32_bf16 v[28:31], v[150:153], v[198:201], v[28:31]
	v_mfma_f32_16x16x32_bf16 v[24:27], v[158:161], v[198:201], v[24:27]
	v_mfma_f32_16x16x32_bf16 v[12:15], v[150:153], v[206:209], v[12:15]
	v_mfma_f32_16x16x32_bf16 v[8:11], v[158:161], v[206:209], v[8:11]
	v_mfma_f32_16x16x32_bf16 v[60:63], v[154:157], v[186:189], v[60:63]
	v_mfma_f32_16x16x32_bf16 v[56:59], v[162:165], v[186:189], v[56:59]
	v_mfma_f32_16x16x32_bf16 v[44:47], v[154:157], v[194:197], v[44:47]
	v_mfma_f32_16x16x32_bf16 v[40:43], v[162:165], v[194:197], v[40:43]
	v_mfma_f32_16x16x32_bf16 v[28:31], v[154:157], v[202:205], v[28:31]
	v_mfma_f32_16x16x32_bf16 v[24:27], v[162:165], v[202:205], v[24:27]
	v_mfma_f32_16x16x32_bf16 v[12:15], v[154:157], v[210:213], v[12:15]
	v_mfma_f32_16x16x32_bf16 v[8:11], v[162:165], v[210:213], v[8:11]
	v_mfma_f32_16x16x32_bf16 v[52:55], v[166:169], v[182:185], v[52:55]
	v_mfma_f32_16x16x32_bf16 v[48:51], v[174:177], v[182:185], v[48:51]
	v_mfma_f32_16x16x32_bf16 v[36:39], v[166:169], v[190:193], v[36:39]
	v_mfma_f32_16x16x32_bf16 v[32:35], v[174:177], v[190:193], v[32:35]
	v_mfma_f32_16x16x32_bf16 v[20:23], v[166:169], v[198:201], v[20:23]
	v_mfma_f32_16x16x32_bf16 v[16:19], v[174:177], v[198:201], v[16:19]
	v_mfma_f32_16x16x32_bf16 v[4:7], v[166:169], v[206:209], v[4:7]
	v_mfma_f32_16x16x32_bf16 v[0:3], v[174:177], v[206:209], v[0:3]
	v_mfma_f32_16x16x32_bf16 v[52:55], v[170:173], v[186:189], v[52:55]
	v_mfma_f32_16x16x32_bf16 v[48:51], v[178:181], v[186:189], v[48:51]
	v_mfma_f32_16x16x32_bf16 v[36:39], v[170:173], v[194:197], v[36:39]
	v_mfma_f32_16x16x32_bf16 v[32:35], v[178:181], v[194:197], v[32:35]
	v_mfma_f32_16x16x32_bf16 v[20:23], v[170:173], v[202:205], v[20:23]
	v_mfma_f32_16x16x32_bf16 v[16:19], v[178:181], v[202:205], v[16:19]
	v_mfma_f32_16x16x32_bf16 v[4:7], v[170:173], v[210:213], v[4:7]
	v_mfma_f32_16x16x32_bf16 v[0:3], v[178:181], v[210:213], v[0:3]
	s_barrier
	s_setprio 0
	s_add_u32 s28, s28, 0x100
	s_addc_u32 s29, s29, 0
	s_add_u32 s54, s54, 0x100
	s_addc_u32 s55, s55, 0
	s_cmp_ge_i32 s56, s44
	s_mov_b32 s30, s56
	s_cbranch_scc0 .LBB0_1040

; #define PG8_STAGE(bufoff, gbase, voff) do { _Pragma("unroll") for (int _i = 0; _i < 2; ++_i) \
;         __builtin_amdgcn_global_load_lds((const unsigned*)((const char*)(gbase) + (voff)[_i]), (LAS unsigned*)(lds + (bufoff) + ldsw + _i * 8192), 16, 0, ((voff) == voffA ? AUXA : 0)); } while (0)
; #define PG8_LDA(dst, b, h) do { _Pragma("unroll") for (int m = 0; m < 4; ++m) _Pragma("unroll") for (int k = 0; k < 2; ++k) dst[m][k] = *(const LAS bf16x8*)(lds + PG8_SA(b, h) + aoff + m * 2048 + k * 1024); } while (0)
; #define PG8_LDB(dst, b, h) do { _Pragma("unroll") for (int n = 0; n < 2; ++n) _Pragma("unroll") for (int k = 0; k < 2; ++k) dst[n][k] = *(const LAS bf16x8*)(lds + PG8_SB(b, h) + boff + n * 2048 + k * 1024); } while (0)
; #define PG8_MMA(ai, bj, At, Bt) do { __builtin_amdgcn_s_setprio(1); _Pragma("unroll") for (int m = 0; m < 4; ++m) _Pragma("unroll") for (int n = 0; n < 2; ++n) _Pragma("unroll") for (int k = 0; k < 2; ++k) \
;         acc[ai][bj][m][n] = __builtin_amdgcn_mfma_f32_16x16x32_bf16(Bt[n][k], At[m][k], acc[ai][bj][m][n], 0, 0, 0); __builtin_amdgcn_s_setprio(0); } while (0)
; #define PG8_WAIT_V(n) asm volatile("s_waitcnt vmcnt(" #n ")" ::: "memory")
; #define PG8_WAIT_L(n) asm volatile("s_waitcnt lgkmcnt(" #n ")" ::: "memory")
; #define PG8_BAR __builtin_amdgcn_s_barrier()
; #define PG8_SCHED __builtin_amdgcn_sched_barrier(0)
;     ...
;             PG8_LDB(B0, 0, 0); PG8_LDB(B1, 0, 1); PG8_SCHED; PG8_LDA(At, 0, 0); PG8_STAGE(PG8_SA(1, 1), a1 + hsA, voffA);
;             if (Epi::NPRE != 0 && last) { E.pre(sv, cur, wr, fr); PG8_WAIT_V(16); } else { PG8_WAIT_V(8); }
;             PG8_WAIT_L(0); PG8_BAR; PG8_MMA(0, 0, At, B0); PG8_MMA(0, 1, At, B1); PG8_BAR; PG8_SCHED;
;             PG8_LDA(At, 0, 1); PG8_STAGE(PG8_SB(0, 0), b2, voffB); PG8_STAGE(PG8_SB(0, 1), b2 + hsB, voffB); PG8_STAGE(PG8_SA(0, 0), a2, voffA);
;             if (Epi::NPRE != 0 && last) { PG8_WAIT_V(16); } else { PG8_WAIT_V(8); }
;             PG8_WAIT_L(0); PG8_BAR; PG8_MMA(1, 0, At, B0); PG8_MMA(1, 1, At, B1); PG8_BAR; PG8_SCHED;
.LBB0_1112:
	ds_read_b128 v[150:153], v147
	ds_read_b128 v[154:157], v147 offset:1024
	ds_read_b128 v[158:161], v147 offset:2048
	ds_read_b128 v[162:165], v147 offset:3072
	ds_read_b128 v[166:169], v148
	ds_read_b128 v[170:173], v148 offset:1024
	ds_read_b128 v[174:177], v148 offset:2048
	ds_read_b128 v[178:181], v148 offset:3072
	s_add_i32 s54, s30, 2
	s_add_u32 s31, s28, 0xfffc0080
	s_addc_u32 s34, s29, -1
	s_cmp_eq_u32 s45, s30
	s_cselect_b32 s30, s51, s52
	s_cselect_b32 s35, s21, s34
	s_cselect_b32 s34, s23, s31
	s_cselect_b32 s31, s50, s53
	s_add_i32 m0, s19, 0xc000
	ds_read_b128 v[182:185], v149
	ds_read_b128 v[186:189], v149 offset:1024
	ds_read_b128 v[190:193], v149 offset:2048
	ds_read_b128 v[194:197], v149 offset:3072
	ds_read_b128 v[198:201], v149 offset:4096
	ds_read_b128 v[202:205], v149 offset:5120
	ds_read_b128 v[206:209], v149 offset:6144
	ds_read_b128 v[210:213], v149 offset:7168
	global_load_lds_dwordx4 v136, s[28:29]
	s_add_i32 m0, s19, 0xe000
	s_nop 0
	global_load_lds_dwordx4 v138, s[28:29]
	s_waitcnt vmcnt(8)
	s_waitcnt lgkmcnt(0)
	s_setprio 1
	s_barrier
	v_mfma_f32_16x16x32_bf16 v[124:127], v[150:153], v[182:185], v[124:127]
	v_mfma_f32_16x16x32_bf16 v[120:123], v[158:161], v[182:185], v[120:123]
	v_mfma_f32_16x16x32_bf16 v[108:111], v[150:153], v[190:193], v[108:111]
	v_mfma_f32_16x16x32_bf16 v[104:107], v[158:161], v[190:193], v[104:107]
	v_mfma_f32_16x16x32_bf16 v[92:95], v[150:153], v[198:201], v[92:95]
	v_mfma_f32_16x16x32_bf16 v[88:91], v[158:161], v[198:201], v[88:91]
	v_mfma_f32_16x16x32_bf16 v[76:79], v[150:153], v[206:209], v[76:79]
	v_mfma_f32_16x16x32_bf16 v[72:75], v[158:161], v[206:209], v[72:75]
	v_mfma_f32_16x16x32_bf16 v[124:127], v[154:157], v[186:189], v[124:127]
	v_mfma_f32_16x16x32_bf16 v[120:123], v[162:165], v[186:189], v[120:123]
	v_mfma_f32_16x16x32_bf16 v[108:111], v[154:157], v[194:197], v[108:111]
	v_mfma_f32_16x16x32_bf16 v[104:107], v[162:165], v[194:197], v[104:107]
	v_mfma_f32_16x16x32_bf16 v[92:95], v[154:157], v[202:205], v[92:95]
	v_mfma_f32_16x16x32_bf16 v[88:91], v[162:165], v[202:205], v[88:91]
	v_mfma_f32_16x16x32_bf16 v[76:79], v[154:157], v[210:213], v[76:79]
	v_mfma_f32_16x16x32_bf16 v[72:75], v[162:165], v[210:213], v[72:75]
	v_mfma_f32_16x16x32_bf16 v[116:119], v[166:169], v[182:185], v[116:119]
	v_mfma_f32_16x16x32_bf16 v[112:115], v[174:177], v[182:185], v[112:115]
	v_mfma_f32_16x16x32_bf16 v[100:103], v[166:169], v[190:193], v[100:103]
	v_mfma_f32_16x16x32_bf16 v[96:99], v[174:177], v[190:193], v[96:99]
	v_mfma_f32_16x16x32_bf16 v[84:87], v[166:169], v[198:201], v[84:87]
	v_mfma_f32_16x16x32_bf16 v[80:83], v[174:177], v[198:201], v[80:83]
	v_mfma_f32_16x16x32_bf16 v[68:71], v[166:169], v[206:209], v[68:71]
	v_mfma_f32_16x16x32_bf16 v[64:67], v[174:177], v[206:209], v[64:67]
	v_mfma_f32_16x16x32_bf16 v[116:119], v[170:173], v[186:189], v[116:119]
	v_mfma_f32_16x16x32_bf16 v[112:115], v[178:181], v[186:189], v[112:115]
	v_mfma_f32_16x16x32_bf16 v[100:103], v[170:173], v[194:197], v[100:103]
	v_mfma_f32_16x16x32_bf16 v[96:99], v[178:181], v[194:197], v[96:99]
	v_mfma_f32_16x16x32_bf16 v[84:87], v[170:173], v[202:205], v[84:87]
	v_mfma_f32_16x16x32_bf16 v[80:83], v[178:181], v[202:205], v[80:83]
	v_mfma_f32_16x16x32_bf16 v[68:71], v[170:173], v[210:213], v[68:71]
	v_mfma_f32_16x16x32_bf16 v[64:67], v[178:181], v[210:213], v[64:67]
	s_barrier
	s_setprio 0
	s_add_u32 s98, s30, s14
	s_addc_u32 s99, s31, s15
	s_add_u32 s100, s34, s14
	s_addc_u32 s101, s35, s15
	s_add_i32 s55, s47, s5
	s_mov_b32 m0, s55
	ds_read_b128 v[182:185], v149 offset:16384
	ds_read_b128 v[186:189], v149 offset:17408
	ds_read_b128 v[190:193], v149 offset:18432
	ds_read_b128 v[194:197], v149 offset:19456
	ds_read_b128 v[198:201], v149 offset:20480
	ds_read_b128 v[202:205], v149 offset:21504
	ds_read_b128 v[206:209], v149 offset:22528
	ds_read_b128 v[210:213], v149 offset:23552
	global_load_lds_dwordx4 v132, s[30:31]
	s_add_i32 m0, s55, 0x2000
	s_add_u32 s56, s30, 0x40000
	s_addc_u32 s57, s31, 0
	s_add_i32 s55, s48, s5
	global_load_lds_dwordx4 v128, s[30:31]
	s_mov_b32 m0, s55
	s_nop 0
	global_load_lds_dwordx4 v132, s[56:57]
	s_add_i32 m0, s55, 0x2000
	s_nop 0
	global_load_lds_dwordx4 v128, s[56:57]
	s_mov_b32 m0, s19
	s_nop 0
	global_load_lds_dwordx4 v134, s[34:35]
	s_mov_b32 m0, s38
	s_nop 0
	global_load_lds_dwordx4 v130, s[34:35]
	s_waitcnt vmcnt(8)
	s_waitcnt lgkmcnt(0)
	s_setprio 1
	s_barrier
	v_mfma_f32_16x16x32_bf16 v[60:63], v[150:153], v[182:185], v[60:63]
	v_mfma_f32_16x16x32_bf16 v[56:59], v[158:161], v[182:185], v[56:59]
	v_mfma_f32_16x16x32_bf16 v[44:47], v[150:153], v[190:193], v[44:47]
	v_mfma_f32_16x16x32_bf16 v[40:43], v[158:161], v[190:193], v[40:43]
	v_mfma_f32_16x16x32_bf16 v[28:31], v[150:153], v[198:201], v[28:31]
	v_mfma_f32_16x16x32_bf16 v[24:27], v[158:161], v[198:201], v[24:27]
	v_mfma_f32_16x16x32_bf16 v[12:15], v[150:153], v[206:209], v[12:15]
	v_mfma_f32_16x16x32_bf16 v[8:11], v[158:161], v[206:209], v[8:11]
	v_mfma_f32_16x16x32_bf16 v[60:63], v[154:157], v[186:189], v[60:63]
	v_mfma_f32_16x16x32_bf16 v[56:59], v[162:165], v[186:189], v[56:59]
	v_mfma_f32_16x16x32_bf16 v[44:47], v[154:157], v[194:197], v[44:47]
	v_mfma_f32_16x16x32_bf16 v[40:43], v[162:165], v[194:197], v[40:43]
	v_mfma_f32_16x16x32_bf16 v[28:31], v[154:157], v[202:205], v[28:31]
	v_mfma_f32_16x16x32_bf16 v[24:27], v[162:165], v[202:205], v[24:27]
	v_mfma_f32_16x16x32_bf16 v[12:15], v[154:157], v[210:213], v[12:15]
	v_mfma_f32_16x16x32_bf16 v[8:11], v[162:165], v[210:213], v[8:11]
	v_mfma_f32_16x16x32_bf16 v[52:55], v[166:169], v[182:185], v[52:55]
	v_mfma_f32_16x16x32_bf16 v[48:51], v[174:177], v[182:185], v[48:51]
	v_mfma_f32_16x16x32_bf16 v[36:39], v[166:169], v[190:193], v[36:39]
	v_mfma_f32_16x16x32_bf16 v[32:35], v[174:177], v[190:193], v[32:35]
	v_mfma_f32_16x16x32_bf16 v[20:23], v[166:169], v[198:201], v[20:23]
	v_mfma_f32_16x16x32_bf16 v[16:19], v[174:177], v[198:201], v[16:19]
	v_mfma_f32_16x16x32_bf16 v[4:7], v[166:169], v[206:209], v[4:7]
	v_mfma_f32_16x16x32_bf16 v[0:3], v[174:177], v[206:209], v[0:3]
	v_mfma_f32_16x16x32_bf16 v[52:55], v[170:173], v[186:189], v[52:55]
	v_mfma_f32_16x16x32_bf16 v[48:51], v[178:181], v[186:189], v[48:51]
	v_mfma_f32_16x16x32_bf16 v[36:39], v[170:173], v[194:197], v[36:39]
	v_mfma_f32_16x16x32_bf16 v[32:35], v[178:181], v[194:197], v[32:35]
	v_mfma_f32_16x16x32_bf16 v[20:23], v[170:173], v[202:205], v[20:23]
	v_mfma_f32_16x16x32_bf16 v[16:19], v[178:181], v[202:205], v[16:19]
	v_mfma_f32_16x16x32_bf16 v[4:7], v[170:173], v[210:213], v[4:7]
	v_mfma_f32_16x16x32_bf16 v[0:3], v[178:181], v[210:213], v[0:3]
	s_barrier
; #define PG8_STAGE(bufoff, gbase, voff) do { _Pragma("unroll") for (int _i = 0; _i < 2; ++_i) \
;         __builtin_amdgcn_global_load_lds((const unsigned*)((const char*)(gbase) + (voff)[_i]), (LAS unsigned*)(lds + (bufoff) + ldsw + _i * 8192), 16, 0, ((voff) == voffA ? AUXA : 0)); } while (0)
; #define PG8_LDA(dst, b, h) do { _Pragma("unroll") for (int m = 0; m < 4; ++m) _Pragma("unroll") for (int k = 0; k < 2; ++k) dst[m][k] = *(const LAS bf16x8*)(lds + PG8_SA(b, h) + aoff + m * 2048 + k * 1024); } while (0)
; #define PG8_LDB(dst, b, h) do { _Pragma("unroll") for (int n = 0; n < 2; ++n) _Pragma("unroll") for (int k = 0; k < 2; ++k) dst[n][k] = *(const LAS bf16x8*)(lds + PG8_SB(b, h) + boff + n * 2048 + k * 1024); } while (0)
; #define PG8_MMA(ai, bj, At, Bt) do { __builtin_amdgcn_s_setprio(1); _Pragma("unroll") for (int m = 0; m < 4; ++m) _Pragma("unroll") for (int n = 0; n < 2; ++n) _Pragma("unroll") for (int k = 0; k < 2; ++k) \
;         acc[ai][bj][m][n] = __builtin_amdgcn_mfma_f32_16x16x32_bf16(Bt[n][k], At[m][k], acc[ai][bj][m][n], 0, 0, 0); __builtin_amdgcn_s_setprio(0); } while (0)
; #define PG8_WAIT_V(n) asm volatile("s_waitcnt vmcnt(" #n ")" ::: "memory")
; #define PG8_WAIT_L(n) asm volatile("s_waitcnt lgkmcnt(" #n ")" ::: "memory")
; #define PG8_BAR __builtin_amdgcn_s_barrier()
; #define PG8_SCHED __builtin_amdgcn_sched_barrier(0)
;     ...
;             PG8_LDB(B0, 1, 0); PG8_LDB(B1, 1, 1); PG8_SCHED; PG8_LDA(At, 1, 0); PG8_STAGE(PG8_SA(0, 1), a2 + hsA, voffA);
;             PG8_WAIT_V(8); PG8_WAIT_L(0); PG8_BAR; PG8_MMA(0, 0, At, B0); PG8_MMA(0, 1, At, B1); PG8_BAR; PG8_SCHED;
;             PG8_LDA(At, 1, 1); PG8_STAGE(PG8_SB(1, 0), b3, voffB); PG8_STAGE(PG8_SB(1, 1), b3 + hsB, voffB); PG8_STAGE(PG8_SA(1, 0), a3, voffA);
;             PG8_WAIT_V(8); PG8_WAIT_L(0); PG8_BAR; PG8_MMA(1, 0, At, B0); PG8_MMA(1, 1, At, B1); PG8_BAR; PG8_SCHED;
	s_setprio 0
	s_add_i32 s55, 0, 0x18000
	s_add_i32 s56, 0, 0x1c000
	v_add_u32_e32 v162, s55, v145
	v_add_u32_e32 v178, s56, v145
	ds_read_b128 v[150:153], v162
	ds_read_b128 v[154:157], v162 offset:1024
	ds_read_b128 v[158:161], v162 offset:2048
	ds_read_b128 v[162:165], v162 offset:3072
	ds_read_b128 v[166:169], v178
	ds_read_b128 v[170:173], v178 offset:1024
	ds_read_b128 v[174:177], v178 offset:2048
	ds_read_b128 v[178:181], v178 offset:3072
	s_add_u32 s34, s34, 0x40000
	s_addc_u32 s35, s35, 0
	s_mov_b32 m0, s39
	ds_read_b128 v[182:185], v149 offset:32768
	ds_read_b128 v[186:189], v149 offset:33792
	ds_read_b128 v[190:193], v149 offset:34816
	ds_read_b128 v[194:197], v149 offset:35840
	ds_read_b128 v[198:201], v149 offset:36864
	ds_read_b128 v[202:205], v149 offset:37888
	ds_read_b128 v[206:209], v149 offset:38912
	ds_read_b128 v[210:213], v149 offset:39936
	global_load_lds_dwordx4 v134, s[34:35]
	s_mov_b32 m0, s40
	s_nop 0
	global_load_lds_dwordx4 v130, s[34:35]
	s_waitcnt vmcnt(8)
	s_waitcnt lgkmcnt(0)
	s_setprio 1
	s_barrier
	v_mfma_f32_16x16x32_bf16 v[124:127], v[150:153], v[182:185], v[124:127]
	v_mfma_f32_16x16x32_bf16 v[120:123], v[158:161], v[182:185], v[120:123]
	v_mfma_f32_16x16x32_bf16 v[108:111], v[150:153], v[190:193], v[108:111]
	v_mfma_f32_16x16x32_bf16 v[104:107], v[158:161], v[190:193], v[104:107]
	v_mfma_f32_16x16x32_bf16 v[92:95], v[150:153], v[198:201], v[92:95]
	v_mfma_f32_16x16x32_bf16 v[88:91], v[158:161], v[198:201], v[88:91]
	v_mfma_f32_16x16x32_bf16 v[76:79], v[150:153], v[206:209], v[76:79]
	v_mfma_f32_16x16x32_bf16 v[72:75], v[158:161], v[206:209], v[72:75]
	v_mfma_f32_16x16x32_bf16 v[124:127], v[154:157], v[186:189], v[124:127]
	v_mfma_f32_16x16x32_bf16 v[120:123], v[162:165], v[186:189], v[120:123]
	v_mfma_f32_16x16x32_bf16 v[108:111], v[154:157], v[194:197], v[108:111]
	v_mfma_f32_16x16x32_bf16 v[104:107], v[162:165], v[194:197], v[104:107]
	v_mfma_f32_16x16x32_bf16 v[92:95], v[154:157], v[202:205], v[92:95]
	v_mfma_f32_16x16x32_bf16 v[88:91], v[162:165], v[202:205], v[88:91]
	v_mfma_f32_16x16x32_bf16 v[76:79], v[154:157], v[210:213], v[76:79]
	v_mfma_f32_16x16x32_bf16 v[72:75], v[162:165], v[210:213], v[72:75]
	v_mfma_f32_16x16x32_bf16 v[116:119], v[166:169], v[182:185], v[116:119]
	v_mfma_f32_16x16x32_bf16 v[112:115], v[174:177], v[182:185], v[112:115]
	v_mfma_f32_16x16x32_bf16 v[100:103], v[166:169], v[190:193], v[100:103]
	v_mfma_f32_16x16x32_bf16 v[96:99], v[174:177], v[190:193], v[96:99]
	v_mfma_f32_16x16x32_bf16 v[84:87], v[166:169], v[198:201], v[84:87]
	v_mfma_f32_16x16x32_bf16 v[80:83], v[174:177], v[198:201], v[80:83]
	v_mfma_f32_16x16x32_bf16 v[68:71], v[166:169], v[206:209], v[68:71]
	v_mfma_f32_16x16x32_bf16 v[64:67], v[174:177], v[206:209], v[64:67]
	v_mfma_f32_16x16x32_bf16 v[116:119], v[170:173], v[186:189], v[116:119]
	v_mfma_f32_16x16x32_bf16 v[112:115], v[178:181], v[186:189], v[112:115]
	v_mfma_f32_16x16x32_bf16 v[100:103], v[170:173], v[194:197], v[100:103]
	v_mfma_f32_16x16x32_bf16 v[96:99], v[178:181], v[194:197], v[96:99]
	v_mfma_f32_16x16x32_bf16 v[84:87], v[170:173], v[202:205], v[84:87]
	v_mfma_f32_16x16x32_bf16 v[80:83], v[178:181], v[202:205], v[80:83]
	v_mfma_f32_16x16x32_bf16 v[68:71], v[170:173], v[210:213], v[68:71]
	v_mfma_f32_16x16x32_bf16 v[64:67], v[178:181], v[210:213], v[64:67]
	s_barrier
	s_setprio 0
	s_add_i32 s34, s55, s5
	s_mov_b32 m0, s34
	ds_read_b128 v[182:185], v149 offset:49152
	ds_read_b128 v[186:189], v149 offset:50176
	ds_read_b128 v[190:193], v149 offset:51200
	ds_read_b128 v[194:197], v149 offset:52224
	ds_read_b128 v[198:201], v149 offset:53248
	ds_read_b128 v[202:205], v149 offset:54272
	ds_read_b128 v[206:209], v149 offset:55296
	ds_read_b128 v[210:213], v149 offset:56320
	global_load_lds_dwordx4 v132, s[98:99]
	s_add_i32 m0, s34, 0x2000
	s_add_u32 s30, s30, 0x40080
	s_addc_u32 s31, s31, 0
	s_add_i32 s34, s56, s5
	global_load_lds_dwordx4 v128, s[98:99]
	s_mov_b32 m0, s34
	s_nop 0
	global_load_lds_dwordx4 v132, s[30:31]
	s_add_i32 m0, s34, 0x2000
	s_nop 0
	global_load_lds_dwordx4 v128, s[30:31]
	s_mov_b32 m0, s43
	s_nop 0
	global_load_lds_dwordx4 v134, s[100:101]
	s_mov_b32 m0, s44
	s_nop 0
	global_load_lds_dwordx4 v130, s[100:101]
	s_waitcnt vmcnt(8)
	s_waitcnt lgkmcnt(0)
	s_setprio 1
	s_barrier
	v_mfma_f32_16x16x32_bf16 v[60:63], v[150:153], v[182:185], v[60:63]
	v_mfma_f32_16x16x32_bf16 v[56:59], v[158:161], v[182:185], v[56:59]
	v_mfma_f32_16x16x32_bf16 v[44:47], v[150:153], v[190:193], v[44:47]
	v_mfma_f32_16x16x32_bf16 v[40:43], v[158:161], v[190:193], v[40:43]
	v_mfma_f32_16x16x32_bf16 v[28:31], v[150:153], v[198:201], v[28:31]
	v_mfma_f32_16x16x32_bf16 v[24:27], v[158:161], v[198:201], v[24:27]
	v_mfma_f32_16x16x32_bf16 v[12:15], v[150:153], v[206:209], v[12:15]
	v_mfma_f32_16x16x32_bf16 v[8:11], v[158:161], v[206:209], v[8:11]
	v_mfma_f32_16x16x32_bf16 v[60:63], v[154:157], v[186:189], v[60:63]
	v_mfma_f32_16x16x32_bf16 v[56:59], v[162:165], v[186:189], v[56:59]
	v_mfma_f32_16x16x32_bf16 v[44:47], v[154:157], v[194:197], v[44:47]
	v_mfma_f32_16x16x32_bf16 v[40:43], v[162:165], v[194:197], v[40:43]
	v_mfma_f32_16x16x32_bf16 v[28:31], v[154:157], v[202:205], v[28:31]
	v_mfma_f32_16x16x32_bf16 v[24:27], v[162:165], v[202:205], v[24:27]
	v_mfma_f32_16x16x32_bf16 v[12:15], v[154:157], v[210:213], v[12:15]
	v_mfma_f32_16x16x32_bf16 v[8:11], v[162:165], v[210:213], v[8:11]
	v_mfma_f32_16x16x32_bf16 v[52:55], v[166:169], v[182:185], v[52:55]
	v_mfma_f32_16x16x32_bf16 v[48:51], v[174:177], v[182:185], v[48:51]
	v_mfma_f32_16x16x32_bf16 v[36:39], v[166:169], v[190:193], v[36:39]
	v_mfma_f32_16x16x32_bf16 v[32:35], v[174:177], v[190:193], v[32:35]
	v_mfma_f32_16x16x32_bf16 v[20:23], v[166:169], v[198:201], v[20:23]
	v_mfma_f32_16x16x32_bf16 v[16:19], v[174:177], v[198:201], v[16:19]
	v_mfma_f32_16x16x32_bf16 v[4:7], v[166:169], v[206:209], v[4:7]
	v_mfma_f32_16x16x32_bf16 v[0:3], v[174:177], v[206:209], v[0:3]
	v_mfma_f32_16x16x32_bf16 v[52:55], v[170:173], v[186:189], v[52:55]
	v_mfma_f32_16x16x32_bf16 v[48:51], v[178:181], v[186:189], v[48:51]
	v_mfma_f32_16x16x32_bf16 v[36:39], v[170:173], v[194:197], v[36:39]
	v_mfma_f32_16x16x32_bf16 v[32:35], v[178:181], v[194:197], v[32:35]
	v_mfma_f32_16x16x32_bf16 v[20:23], v[170:173], v[202:205], v[20:23]
	v_mfma_f32_16x16x32_bf16 v[16:19], v[178:181], v[202:205], v[16:19]
	v_mfma_f32_16x16x32_bf16 v[4:7], v[170:173], v[210:213], v[4:7]
	v_mfma_f32_16x16x32_bf16 v[0:3], v[178:181], v[210:213], v[0:3]
	s_barrier
	s_setprio 0
	s_add_u32 s28, s28, 0x100
	s_addc_u32 s29, s29, 0
	s_add_u32 s52, s52, 0x100
	s_addc_u32 s53, s53, 0
	s_cmp_ge_i32 s54, s42
	s_mov_b32 s30, s54
	s_cbranch_scc0 .LBB0_1112

; #define PG8_STAGE(bufoff, gbase, voff) do { _Pragma("unroll") for (int _i = 0; _i < 2; ++_i) \
;         __builtin_amdgcn_global_load_lds((const unsigned*)((const char*)(gbase) + (voff)[_i]), (LAS unsigned*)(lds + (bufoff) + ldsw + _i * 8192), 16, 0, ((voff) == voffA ? AUXA : 0)); } while (0)
; #define PG8_LDA(dst, b, h) do { _Pragma("unroll") for (int m = 0; m < 4; ++m) _Pragma("unroll") for (int k = 0; k < 2; ++k) dst[m][k] = *(const LAS bf16x8*)(lds + PG8_SA(b, h) + aoff + m * 2048 + k * 1024); } while (0)
; #define PG8_LDB(dst, b, h) do { _Pragma("unroll") for (int n = 0; n < 2; ++n) _Pragma("unroll") for (int k = 0; k < 2; ++k) dst[n][k] = *(const LAS bf16x8*)(lds + PG8_SB(b, h) + boff + n * 2048 + k * 1024); } while (0)
; #define PG8_MMA(ai, bj, At, Bt) do { __builtin_amdgcn_s_setprio(1); _Pragma("unroll") for (int m = 0; m < 4; ++m) _Pragma("unroll") for (int n = 0; n < 2; ++n) _Pragma("unroll") for (int k = 0; k < 2; ++k) \
;         acc[ai][bj][m][n] = __builtin_amdgcn_mfma_f32_16x16x32_bf16(Bt[n][k], At[m][k], acc[ai][bj][m][n], 0, 0, 0); __builtin_amdgcn_s_setprio(0); } while (0)
; #define PG8_WAIT_V(n) asm volatile("s_waitcnt vmcnt(" #n ")" ::: "memory")
; #define PG8_WAIT_L(n) asm volatile("s_waitcnt lgkmcnt(" #n ")" ::: "memory")
; #define PG8_BAR __builtin_amdgcn_s_barrier()
; #define PG8_SCHED __builtin_amdgcn_sched_barrier(0)
;     ...
;             PG8_WAIT_L(0); PG8_BAR; PG8_MMA(1, 0, At, B0); PG8_MMA(1, 1, At, B1); PG8_BAR; PG8_SCHED;
;             PG8_LDB(B0, 1, 0); PG8_LDB(B1, 1, 1); PG8_SCHED; PG8_LDA(At, 1, 0); PG8_STAGE(PG8_SA(0, 1), a2 + hsA, voffA);
;             PG8_WAIT_V(8); PG8_WAIT_L(0); PG8_BAR; PG8_MMA(0, 0, At, B0); PG8_MMA(0, 1, At, B1); PG8_BAR; PG8_SCHED;
;             PG8_LDA(At, 1, 1); PG8_STAGE(PG8_SB(1, 0), b3, voffB); PG8_STAGE(PG8_SB(1, 1), b3 + hsB, voffB); PG8_STAGE(PG8_SA(1, 0), a3, voffA);
.LBB0_1184:
	s_waitcnt lgkmcnt(0)
	s_add_i32 s62, s62, 2
	s_setprio 1
	s_barrier
	v_mfma_f32_16x16x32_bf16 v[60:63], v[144:147], v[184:187], v[60:63]
	v_mfma_f32_16x16x32_bf16 v[52:55], v[152:155], v[184:187], v[52:55]
	v_mfma_f32_16x16x32_bf16 v[44:47], v[144:147], v[176:179], v[44:47]
	v_mfma_f32_16x16x32_bf16 v[36:39], v[152:155], v[176:179], v[36:39]
	v_mfma_f32_16x16x32_bf16 v[28:31], v[144:147], v[168:171], v[28:31]
	v_mfma_f32_16x16x32_bf16 v[20:23], v[152:155], v[168:171], v[20:23]
	v_mfma_f32_16x16x32_bf16 v[12:15], v[144:147], v[160:163], v[12:15]
	v_mfma_f32_16x16x32_bf16 v[4:7], v[152:155], v[160:163], v[4:7]
	v_mfma_f32_16x16x32_bf16 v[60:63], v[148:151], v[188:191], v[60:63]
	v_mfma_f32_16x16x32_bf16 v[52:55], v[156:159], v[188:191], v[52:55]
	v_mfma_f32_16x16x32_bf16 v[44:47], v[148:151], v[180:183], v[44:47]
	v_mfma_f32_16x16x32_bf16 v[36:39], v[156:159], v[180:183], v[36:39]
	v_mfma_f32_16x16x32_bf16 v[28:31], v[148:151], v[172:175], v[28:31]
	v_mfma_f32_16x16x32_bf16 v[20:23], v[156:159], v[172:175], v[20:23]
	v_mfma_f32_16x16x32_bf16 v[12:15], v[148:151], v[164:167], v[12:15]
	v_mfma_f32_16x16x32_bf16 v[4:7], v[156:159], v[164:167], v[4:7]
	v_mfma_f32_16x16x32_bf16 v[56:59], v[128:131], v[184:187], v[56:59]
	v_mfma_f32_16x16x32_bf16 v[48:51], v[136:139], v[184:187], v[48:51]
	v_mfma_f32_16x16x32_bf16 v[40:43], v[128:131], v[176:179], v[40:43]
	v_mfma_f32_16x16x32_bf16 v[32:35], v[136:139], v[176:179], v[32:35]
	v_mfma_f32_16x16x32_bf16 v[24:27], v[128:131], v[168:171], v[24:27]
	v_mfma_f32_16x16x32_bf16 v[16:19], v[136:139], v[168:171], v[16:19]
	v_mfma_f32_16x16x32_bf16 v[8:11], v[128:131], v[160:163], v[8:11]
	v_mfma_f32_16x16x32_bf16 v[0:3], v[136:139], v[160:163], v[0:3]
	v_mfma_f32_16x16x32_bf16 v[56:59], v[132:135], v[188:191], v[56:59]
	v_mfma_f32_16x16x32_bf16 v[48:51], v[140:143], v[188:191], v[48:51]
	v_mfma_f32_16x16x32_bf16 v[40:43], v[132:135], v[180:183], v[40:43]
	v_mfma_f32_16x16x32_bf16 v[32:35], v[140:143], v[180:183], v[32:35]
	v_mfma_f32_16x16x32_bf16 v[24:27], v[132:135], v[172:175], v[24:27]
	v_mfma_f32_16x16x32_bf16 v[16:19], v[140:143], v[172:175], v[16:19]
	v_mfma_f32_16x16x32_bf16 v[8:11], v[132:135], v[164:167], v[8:11]
	v_mfma_f32_16x16x32_bf16 v[0:3], v[140:143], v[164:167], v[0:3]
	s_barrier
	s_setprio 0
	s_add_i32 s36, 0, 0x18000
	s_add_i32 s37, 0, 0x1c000
	v_add_u32_e32 v140, s36, v221
	v_add_u32_e32 v156, s37, v221
	ds_read_b128 v[128:131], v140
	ds_read_b128 v[132:135], v140 offset:1024
	ds_read_b128 v[136:139], v140 offset:2048
	ds_read_b128 v[140:143], v140 offset:3072
	ds_read_b128 v[144:147], v156
	ds_read_b128 v[148:151], v156 offset:1024
	ds_read_b128 v[152:155], v156 offset:2048
	ds_read_b128 v[156:159], v156 offset:3072
	s_add_u32 s34, s34, 0x80000
	s_addc_u32 s35, s35, 0
	s_mov_b32 m0, s48
	ds_read_b128 v[160:163], v225 offset:32768
	ds_read_b128 v[164:167], v225 offset:33792
	ds_read_b128 v[168:171], v225 offset:34816
	ds_read_b128 v[172:175], v225 offset:35840
	ds_read_b128 v[176:179], v225 offset:36864
	ds_read_b128 v[180:183], v225 offset:37888
	ds_read_b128 v[184:187], v225 offset:38912
	ds_read_b128 v[188:191], v225 offset:39936
	global_load_lds_dwordx4 v198, s[34:35]
	s_mov_b32 m0, s49
	s_nop 0
	global_load_lds_dwordx4 v194, s[34:35]
	s_waitcnt vmcnt(8)
	s_waitcnt lgkmcnt(0)
	s_setprio 1
	s_barrier
; #define PG8_STAGE(bufoff, gbase, voff) do { _Pragma("unroll") for (int _i = 0; _i < 2; ++_i) \
;         __builtin_amdgcn_global_load_lds((const unsigned*)((const char*)(gbase) + (voff)[_i]), (LAS unsigned*)(lds + (bufoff) + ldsw + _i * 8192), 16, 0, ((voff) == voffA ? AUXA : 0)); } while (0)
; #define PG8_LDA(dst, b, h) do { _Pragma("unroll") for (int m = 0; m < 4; ++m) _Pragma("unroll") for (int k = 0; k < 2; ++k) dst[m][k] = *(const LAS bf16x8*)(lds + PG8_SA(b, h) + aoff + m * 2048 + k * 1024); } while (0)
; #define PG8_MMA(ai, bj, At, Bt) do { __builtin_amdgcn_s_setprio(1); _Pragma("unroll") for (int m = 0; m < 4; ++m) _Pragma("unroll") for (int n = 0; n < 2; ++n) _Pragma("unroll") for (int k = 0; k < 2; ++k) \
;         acc[ai][bj][m][n] = __builtin_amdgcn_mfma_f32_16x16x32_bf16(Bt[n][k], At[m][k], acc[ai][bj][m][n], 0, 0, 0); __builtin_amdgcn_s_setprio(0); } while (0)
; #define PG8_WAIT_V(n) asm volatile("s_waitcnt vmcnt(" #n ")" ::: "memory")
; #define PG8_WAIT_L(n) asm volatile("s_waitcnt lgkmcnt(" #n ")" ::: "memory")
; #define PG8_BAR __builtin_amdgcn_s_barrier()
; #define PG8_SCHED __builtin_amdgcn_sched_barrier(0)
;     ...
;             PG8_WAIT_V(8); PG8_WAIT_L(0); PG8_BAR; PG8_MMA(0, 0, At, B0); PG8_MMA(0, 1, At, B1); PG8_BAR; PG8_SCHED;
;             PG8_LDA(At, 1, 1); PG8_STAGE(PG8_SB(1, 0), b3, voffB); PG8_STAGE(PG8_SB(1, 1), b3 + hsB, voffB); PG8_STAGE(PG8_SA(1, 0), a3, voffA);
;             PG8_WAIT_V(8); PG8_WAIT_L(0); PG8_BAR; PG8_MMA(1, 0, At, B0); PG8_MMA(1, 1, At, B1); PG8_BAR; PG8_SCHED;
	v_mfma_f32_16x16x32_bf16 v[124:127], v[128:131], v[160:163], v[124:127]
	v_mfma_f32_16x16x32_bf16 v[116:119], v[136:139], v[160:163], v[116:119]
	v_mfma_f32_16x16x32_bf16 v[108:111], v[128:131], v[168:171], v[108:111]
	v_mfma_f32_16x16x32_bf16 v[100:103], v[136:139], v[168:171], v[100:103]
	v_mfma_f32_16x16x32_bf16 v[92:95], v[128:131], v[176:179], v[92:95]
	v_mfma_f32_16x16x32_bf16 v[84:87], v[136:139], v[176:179], v[84:87]
	v_mfma_f32_16x16x32_bf16 v[76:79], v[128:131], v[184:187], v[76:79]
	v_mfma_f32_16x16x32_bf16 v[68:71], v[136:139], v[184:187], v[68:71]
	v_mfma_f32_16x16x32_bf16 v[124:127], v[132:135], v[164:167], v[124:127]
	v_mfma_f32_16x16x32_bf16 v[116:119], v[140:143], v[164:167], v[116:119]
	v_mfma_f32_16x16x32_bf16 v[108:111], v[132:135], v[172:175], v[108:111]
	v_mfma_f32_16x16x32_bf16 v[100:103], v[140:143], v[172:175], v[100:103]
	v_mfma_f32_16x16x32_bf16 v[92:95], v[132:135], v[180:183], v[92:95]
	v_mfma_f32_16x16x32_bf16 v[84:87], v[140:143], v[180:183], v[84:87]
	v_mfma_f32_16x16x32_bf16 v[76:79], v[132:135], v[188:191], v[76:79]
	v_mfma_f32_16x16x32_bf16 v[68:71], v[140:143], v[188:191], v[68:71]
	v_mfma_f32_16x16x32_bf16 v[120:123], v[144:147], v[160:163], v[120:123]
	v_mfma_f32_16x16x32_bf16 v[112:115], v[152:155], v[160:163], v[112:115]
	v_mfma_f32_16x16x32_bf16 v[104:107], v[144:147], v[168:171], v[104:107]
	v_mfma_f32_16x16x32_bf16 v[96:99], v[152:155], v[168:171], v[96:99]
	v_mfma_f32_16x16x32_bf16 v[88:91], v[144:147], v[176:179], v[88:91]
	v_mfma_f32_16x16x32_bf16 v[80:83], v[152:155], v[176:179], v[80:83]
	v_mfma_f32_16x16x32_bf16 v[72:75], v[144:147], v[184:187], v[72:75]
	v_mfma_f32_16x16x32_bf16 v[64:67], v[152:155], v[184:187], v[64:67]
	v_mfma_f32_16x16x32_bf16 v[120:123], v[148:151], v[164:167], v[120:123]
	v_mfma_f32_16x16x32_bf16 v[112:115], v[156:159], v[164:167], v[112:115]
	v_mfma_f32_16x16x32_bf16 v[104:107], v[148:151], v[172:175], v[104:107]
	v_mfma_f32_16x16x32_bf16 v[96:99], v[156:159], v[172:175], v[96:99]
	v_mfma_f32_16x16x32_bf16 v[88:91], v[148:151], v[180:183], v[88:91]
	v_mfma_f32_16x16x32_bf16 v[80:83], v[156:159], v[180:183], v[80:83]
	v_mfma_f32_16x16x32_bf16 v[72:75], v[148:151], v[188:191], v[72:75]
	v_mfma_f32_16x16x32_bf16 v[64:67], v[156:159], v[188:191], v[64:67]
	s_barrier
	s_setprio 0
	s_add_i32 s34, s36, s5
	s_mov_b32 m0, s34
	ds_read_b128 v[160:163], v225 offset:49152
	ds_read_b128 v[164:167], v225 offset:50176
	ds_read_b128 v[168:171], v225 offset:51200
	ds_read_b128 v[172:175], v225 offset:52224
	ds_read_b128 v[176:179], v225 offset:53248
	ds_read_b128 v[180:183], v225 offset:54272
	ds_read_b128 v[184:187], v225 offset:55296
	ds_read_b128 v[188:191], v225 offset:56320
	global_load_lds_dwordx4 v196, s[98:99]
	s_add_i32 m0, s34, 0x2000
	s_add_u32 s30, s30, 0x80080
	s_addc_u32 s31, s31, 0
	s_add_i32 s34, s37, s5
	global_load_lds_dwordx4 v192, s[98:99]
	s_mov_b32 m0, s34
	s_nop 0
	global_load_lds_dwordx4 v196, s[30:31]
	s_add_i32 m0, s34, 0x2000
	s_nop 0
	global_load_lds_dwordx4 v192, s[30:31]
	s_mov_b32 m0, s52
	s_nop 0
	global_load_lds_dwordx4 v198, s[100:101]
	s_mov_b32 m0, s53
	s_nop 0
	global_load_lds_dwordx4 v194, s[100:101]
	s_waitcnt vmcnt(8)
	s_waitcnt lgkmcnt(0)
	s_setprio 1
	s_barrier
	v_mfma_f32_16x16x32_bf16 v[60:63], v[128:131], v[160:163], v[60:63]
	v_mfma_f32_16x16x32_bf16 v[52:55], v[136:139], v[160:163], v[52:55]
	v_mfma_f32_16x16x32_bf16 v[44:47], v[128:131], v[168:171], v[44:47]
	v_mfma_f32_16x16x32_bf16 v[36:39], v[136:139], v[168:171], v[36:39]
	v_mfma_f32_16x16x32_bf16 v[28:31], v[128:131], v[176:179], v[28:31]
	v_mfma_f32_16x16x32_bf16 v[20:23], v[136:139], v[176:179], v[20:23]
	v_mfma_f32_16x16x32_bf16 v[12:15], v[128:131], v[184:187], v[12:15]
	v_mfma_f32_16x16x32_bf16 v[4:7], v[136:139], v[184:187], v[4:7]
	v_mfma_f32_16x16x32_bf16 v[60:63], v[132:135], v[164:167], v[60:63]
	v_mfma_f32_16x16x32_bf16 v[52:55], v[140:143], v[164:167], v[52:55]
	v_mfma_f32_16x16x32_bf16 v[44:47], v[132:135], v[172:175], v[44:47]
	v_mfma_f32_16x16x32_bf16 v[36:39], v[140:143], v[172:175], v[36:39]
	v_mfma_f32_16x16x32_bf16 v[28:31], v[132:135], v[180:183], v[28:31]
	v_mfma_f32_16x16x32_bf16 v[20:23], v[140:143], v[180:183], v[20:23]
	v_mfma_f32_16x16x32_bf16 v[12:15], v[132:135], v[188:191], v[12:15]
	v_mfma_f32_16x16x32_bf16 v[4:7], v[140:143], v[188:191], v[4:7]
	v_mfma_f32_16x16x32_bf16 v[56:59], v[144:147], v[160:163], v[56:59]
	v_mfma_f32_16x16x32_bf16 v[48:51], v[152:155], v[160:163], v[48:51]
	v_mfma_f32_16x16x32_bf16 v[40:43], v[144:147], v[168:171], v[40:43]
	v_mfma_f32_16x16x32_bf16 v[32:35], v[152:155], v[168:171], v[32:35]
	v_mfma_f32_16x16x32_bf16 v[24:27], v[144:147], v[176:179], v[24:27]
	v_mfma_f32_16x16x32_bf16 v[16:19], v[152:155], v[176:179], v[16:19]
	v_mfma_f32_16x16x32_bf16 v[8:11], v[144:147], v[184:187], v[8:11]
	v_mfma_f32_16x16x32_bf16 v[0:3], v[152:155], v[184:187], v[0:3]
	v_mfma_f32_16x16x32_bf16 v[56:59], v[148:151], v[164:167], v[56:59]
	v_mfma_f32_16x16x32_bf16 v[48:51], v[156:159], v[164:167], v[48:51]
	v_mfma_f32_16x16x32_bf16 v[40:43], v[148:151], v[172:175], v[40:43]
	v_mfma_f32_16x16x32_bf16 v[32:35], v[156:159], v[172:175], v[32:35]
	v_mfma_f32_16x16x32_bf16 v[24:27], v[148:151], v[180:183], v[24:27]
	v_mfma_f32_16x16x32_bf16 v[16:19], v[156:159], v[180:183], v[16:19]
	v_mfma_f32_16x16x32_bf16 v[8:11], v[148:151], v[188:191], v[8:11]
	v_mfma_f32_16x16x32_bf16 v[0:3], v[156:159], v[188:191], v[0:3]
	s_barrier
	s_setprio 0
	s_add_u32 s28, s28, 0x100
	s_addc_u32 s29, s29, 0
	s_add_u32 s60, s60, 0x100
	s_addc_u32 s61, s61, 0
	s_cmp_ge_i32 s62, s51
	s_cbranch_scc1 .LBB0_1194

; #define PG8_STAGE(bufoff, gbase, voff) do { _Pragma("unroll") for (int _i = 0; _i < 2; ++_i) \
;         __builtin_amdgcn_global_load_lds((const unsigned*)((const char*)(gbase) + (voff)[_i]), (LAS unsigned*)(lds + (bufoff) + ldsw + _i * 8192), 16, 0, ((voff) == voffA ? AUXA : 0)); } while (0)
; #define PG8_LDA(dst, b, h) do { _Pragma("unroll") for (int m = 0; m < 4; ++m) _Pragma("unroll") for (int k = 0; k < 2; ++k) dst[m][k] = *(const LAS bf16x8*)(lds + PG8_SA(b, h) + aoff + m * 2048 + k * 1024); } while (0)
; #define PG8_LDB(dst, b, h) do { _Pragma("unroll") for (int n = 0; n < 2; ++n) _Pragma("unroll") for (int k = 0; k < 2; ++k) dst[n][k] = *(const LAS bf16x8*)(lds + PG8_SB(b, h) + boff + n * 2048 + k * 1024); } while (0)
; #define PG8_MMA(ai, bj, At, Bt) do { __builtin_amdgcn_s_setprio(1); _Pragma("unroll") for (int m = 0; m < 4; ++m) _Pragma("unroll") for (int n = 0; n < 2; ++n) _Pragma("unroll") for (int k = 0; k < 2; ++k) \
;         acc[ai][bj][m][n] = __builtin_amdgcn_mfma_f32_16x16x32_bf16(Bt[n][k], At[m][k], acc[ai][bj][m][n], 0, 0, 0); __builtin_amdgcn_s_setprio(0); } while (0)
; #define PG8_WAIT_V(n) asm volatile("s_waitcnt vmcnt(" #n ")" ::: "memory")
; #define PG8_WAIT_L(n) asm volatile("s_waitcnt lgkmcnt(" #n ")" ::: "memory")
; #define PG8_BAR __builtin_amdgcn_s_barrier()
; #define PG8_SCHED __builtin_amdgcn_sched_barrier(0)
;     ...
;             const char* a2 = last ? nA : cA + (size_t)(t + 2) * kstep; const char* b2 = last ? nB : cB + (size_t)(t + 2) * kstep;
;             const char* a3 = a2 + kstep; const char* b3 = b2 + kstep;
;             PG8_LDB(B0, 0, 0); PG8_LDB(B1, 0, 1); PG8_SCHED; PG8_LDA(At, 0, 0); PG8_STAGE(PG8_SA(1, 1), a1 + hsA, voffA);
;             if (Epi::NPRE != 0 && last) { E.pre(sv, cur, wr, fr); PG8_WAIT_V(16); } else { PG8_WAIT_V(8); }
;             PG8_WAIT_L(0); PG8_BAR; PG8_MMA(0, 0, At, B0); PG8_MMA(0, 1, At, B1); PG8_BAR; PG8_SCHED;
;             PG8_LDA(At, 0, 1); PG8_STAGE(PG8_SB(0, 0), b2, voffB); PG8_STAGE(PG8_SB(0, 1), b2 + hsB, voffB); PG8_STAGE(PG8_SA(0, 0), a2, voffA);
;             if (Epi::NPRE != 0 && last) { PG8_WAIT_V(16); } else { PG8_WAIT_V(8); }
.LBB0_1189:
	s_add_u32 s34, s28, 0xfff80080
	s_addc_u32 s35, s29, -1
	s_waitcnt lgkmcnt(0)
	s_and_b64 s[30:31], s[30:31], exec
	s_cselect_b32 s35, s21, s35
	s_cselect_b32 s34, s23, s34
	s_cselect_b32 s31, s58, s61
	s_cselect_b32 s30, s59, s60
	s_setprio 1
	s_barrier
	v_mfma_f32_16x16x32_bf16 v[124:127], v[144:147], v[184:187], v[124:127]
	v_mfma_f32_16x16x32_bf16 v[116:119], v[152:155], v[184:187], v[116:119]
	v_mfma_f32_16x16x32_bf16 v[108:111], v[144:147], v[176:179], v[108:111]
	v_mfma_f32_16x16x32_bf16 v[100:103], v[152:155], v[176:179], v[100:103]
	v_mfma_f32_16x16x32_bf16 v[92:95], v[144:147], v[168:171], v[92:95]
	v_mfma_f32_16x16x32_bf16 v[84:87], v[152:155], v[168:171], v[84:87]
	v_mfma_f32_16x16x32_bf16 v[76:79], v[144:147], v[160:163], v[76:79]
	v_mfma_f32_16x16x32_bf16 v[68:71], v[152:155], v[160:163], v[68:71]
	v_mfma_f32_16x16x32_bf16 v[124:127], v[148:151], v[188:191], v[124:127]
	v_mfma_f32_16x16x32_bf16 v[116:119], v[156:159], v[188:191], v[116:119]
	v_mfma_f32_16x16x32_bf16 v[108:111], v[148:151], v[180:183], v[108:111]
	v_mfma_f32_16x16x32_bf16 v[100:103], v[156:159], v[180:183], v[100:103]
	v_mfma_f32_16x16x32_bf16 v[92:95], v[148:151], v[172:175], v[92:95]
	v_mfma_f32_16x16x32_bf16 v[84:87], v[156:159], v[172:175], v[84:87]
	v_mfma_f32_16x16x32_bf16 v[76:79], v[148:151], v[164:167], v[76:79]
	v_mfma_f32_16x16x32_bf16 v[68:71], v[156:159], v[164:167], v[68:71]
	v_mfma_f32_16x16x32_bf16 v[120:123], v[128:131], v[184:187], v[120:123]
	v_mfma_f32_16x16x32_bf16 v[112:115], v[136:139], v[184:187], v[112:115]
	v_mfma_f32_16x16x32_bf16 v[104:107], v[128:131], v[176:179], v[104:107]
	v_mfma_f32_16x16x32_bf16 v[96:99], v[136:139], v[176:179], v[96:99]
	v_mfma_f32_16x16x32_bf16 v[88:91], v[128:131], v[168:171], v[88:91]
	v_mfma_f32_16x16x32_bf16 v[80:83], v[136:139], v[168:171], v[80:83]
	v_mfma_f32_16x16x32_bf16 v[72:75], v[128:131], v[160:163], v[72:75]
	v_mfma_f32_16x16x32_bf16 v[64:67], v[136:139], v[160:163], v[64:67]
	v_mfma_f32_16x16x32_bf16 v[120:123], v[132:135], v[188:191], v[120:123]
	v_mfma_f32_16x16x32_bf16 v[112:115], v[140:143], v[188:191], v[112:115]
	v_mfma_f32_16x16x32_bf16 v[104:107], v[132:135], v[180:183], v[104:107]
	v_mfma_f32_16x16x32_bf16 v[96:99], v[140:143], v[180:183], v[96:99]
	v_mfma_f32_16x16x32_bf16 v[88:91], v[132:135], v[172:175], v[88:91]
	v_mfma_f32_16x16x32_bf16 v[80:83], v[140:143], v[172:175], v[80:83]
	v_mfma_f32_16x16x32_bf16 v[72:75], v[132:135], v[164:167], v[72:75]
	v_mfma_f32_16x16x32_bf16 v[64:67], v[140:143], v[164:167], v[64:67]
	s_barrier
	s_setprio 0
	s_add_u32 s98, s30, s16
	s_addc_u32 s99, s31, s17
	s_add_u32 s100, s34, s16
	s_addc_u32 s101, s35, s17
	s_mov_b32 m0, s43
	s_add_u32 s38, s30, 0x80000
	ds_read_b128 v[184:187], v225 offset:16384
	ds_read_b128 v[188:191], v225 offset:17408
	ds_read_b128 v[176:179], v225 offset:18432
	ds_read_b128 v[180:183], v225 offset:19456
	ds_read_b128 v[168:171], v225 offset:20480
	ds_read_b128 v[172:175], v225 offset:21504
	ds_read_b128 v[160:163], v225 offset:22528
	ds_read_b128 v[164:167], v225 offset:23552
	global_load_lds_dwordx4 v196, s[30:31]
	s_mov_b32 m0, s44
	s_addc_u32 s39, s31, 0
	global_load_lds_dwordx4 v192, s[30:31]
	s_mov_b32 m0, s45
	s_nop 0
	global_load_lds_dwordx4 v196, s[38:39]
	s_mov_b32 m0, s46
	s_nop 0
	global_load_lds_dwordx4 v192, s[38:39]
	s_mov_b64 s[38:39], -1
	s_mov_b32 m0, s42
	s_and_b64 vcc, exec, s[36:37]
	global_load_lds_dwordx4 v198, s[34:35]
	s_mov_b32 m0, s47
	s_nop 0
	global_load_lds_dwordx4 v194, s[34:35]
	s_cbranch_vccz .LBB0_1191
	s_waitcnt vmcnt(8)
	s_mov_b64 s[38:39], 0

; #define PG8_STAGE(bufoff, gbase, voff) do { _Pragma("unroll") for (int _i = 0; _i < 2; ++_i) \
;         __builtin_amdgcn_global_load_lds((const unsigned*)((const char*)(gbase) + (voff)[_i]), (LAS unsigned*)(lds + (bufoff) + ldsw + _i * 8192), 16, 0, ((voff) == voffA ? AUXA : 0)); } while (0)
; #define PG8_LDA(dst, b, h) do { _Pragma("unroll") for (int m = 0; m < 4; ++m) _Pragma("unroll") for (int k = 0; k < 2; ++k) dst[m][k] = *(const LAS bf16x8*)(lds + PG8_SA(b, h) + aoff + m * 2048 + k * 1024); } while (0)
; #define PG8_LDB(dst, b, h) do { _Pragma("unroll") for (int n = 0; n < 2; ++n) _Pragma("unroll") for (int k = 0; k < 2; ++k) dst[n][k] = *(const LAS bf16x8*)(lds + PG8_SB(b, h) + boff + n * 2048 + k * 1024); } while (0)
; #define PG8_MMA(ai, bj, At, Bt) do { __builtin_amdgcn_s_setprio(1); _Pragma("unroll") for (int m = 0; m < 4; ++m) _Pragma("unroll") for (int n = 0; n < 2; ++n) _Pragma("unroll") for (int k = 0; k < 2; ++k) \
;         acc[ai][bj][m][n] = __builtin_amdgcn_mfma_f32_16x16x32_bf16(Bt[n][k], At[m][k], acc[ai][bj][m][n], 0, 0, 0); __builtin_amdgcn_s_setprio(0); } while (0)
; #define PG8_WAIT_V(n) asm volatile("s_waitcnt vmcnt(" #n ")" ::: "memory")
; #define PG8_WAIT_L(n) asm volatile("s_waitcnt lgkmcnt(" #n ")" ::: "memory")
; #define PG8_BAR __builtin_amdgcn_s_barrier()
; #define PG8_SCHED __builtin_amdgcn_sched_barrier(0)
;     ...
;             PG8_LDB(B0, 0, 0); PG8_LDB(B1, 0, 1); PG8_SCHED; PG8_LDA(At, 0, 0); PG8_STAGE(PG8_SA(1, 1), a1 + hsA, voffA);
;             if (Epi::NPRE != 0 && last) { E.pre(sv, cur, wr, fr); PG8_WAIT_V(16); } else { PG8_WAIT_V(8); }
;             PG8_WAIT_L(0); PG8_BAR; PG8_MMA(0, 0, At, B0); PG8_MMA(0, 1, At, B1); PG8_BAR; PG8_SCHED;
;             PG8_LDA(At, 0, 1); PG8_STAGE(PG8_SB(0, 0), b2, voffB); PG8_STAGE(PG8_SB(0, 1), b2 + hsB, voffB); PG8_STAGE(PG8_SA(0, 0), a2, voffA);
;             if (Epi::NPRE != 0 && last) { PG8_WAIT_V(16); } else { PG8_WAIT_V(8); }
;             PG8_WAIT_L(0); PG8_BAR; PG8_MMA(1, 0, At, B0); PG8_MMA(1, 1, At, B1); PG8_BAR; PG8_SCHED;
.LBB0_1267:
	ds_read_b128 v[128:131], v189
	ds_read_b128 v[132:135], v189 offset:1024
	ds_read_b128 v[136:139], v189 offset:2048
	ds_read_b128 v[140:143], v189 offset:3072
	ds_read_b128 v[144:147], v190
	ds_read_b128 v[148:151], v190 offset:1024
	ds_read_b128 v[168:171], v190 offset:2048
	ds_read_b128 v[172:175], v190 offset:3072
	s_add_i32 s58, s36, 2
	s_add_u32 s37, s34, 0xfff80080
	s_addc_u32 s38, s35, -1
	s_cmp_eq_u32 s49, s36
	s_cselect_b32 s36, s55, s56
	s_cselect_b32 s39, s21, s38
	s_cselect_b32 s38, s23, s37
	s_cselect_b32 s37, s29, s57
	s_add_i32 m0, s31, 0xc000
	ds_read_b128 v[176:179], v191
	ds_read_b128 v[180:183], v191 offset:1024
	ds_read_b128 v[194:197], v191 offset:2048
	ds_read_b128 v[198:201], v191 offset:3072
	ds_read_b128 v[202:205], v191 offset:4096
	ds_read_b128 v[206:209], v191 offset:5120
	ds_read_b128 v[210:213], v191 offset:6144
	ds_read_b128 v[214:217], v191 offset:7168
	global_load_lds_dwordx4 v160, s[34:35]
	s_add_i32 m0, s31, 0xe000
	s_nop 0
	global_load_lds_dwordx4 v162, s[34:35]
	s_waitcnt vmcnt(8)
	s_waitcnt lgkmcnt(0)
	s_setprio 1
	s_barrier
	v_mfma_f32_16x16x32_bf16 v[124:127], v[128:131], v[176:179], v[124:127]
	v_mfma_f32_16x16x32_bf16 v[120:123], v[136:139], v[176:179], v[120:123]
	v_mfma_f32_16x16x32_bf16 v[108:111], v[128:131], v[194:197], v[108:111]
	v_mfma_f32_16x16x32_bf16 v[104:107], v[136:139], v[194:197], v[104:107]
	v_mfma_f32_16x16x32_bf16 v[92:95], v[128:131], v[202:205], v[92:95]
	v_mfma_f32_16x16x32_bf16 v[88:91], v[136:139], v[202:205], v[88:91]
	v_mfma_f32_16x16x32_bf16 v[76:79], v[128:131], v[210:213], v[76:79]
	v_mfma_f32_16x16x32_bf16 v[72:75], v[136:139], v[210:213], v[72:75]
	v_mfma_f32_16x16x32_bf16 v[124:127], v[132:135], v[180:183], v[124:127]
	v_mfma_f32_16x16x32_bf16 v[120:123], v[140:143], v[180:183], v[120:123]
	v_mfma_f32_16x16x32_bf16 v[108:111], v[132:135], v[198:201], v[108:111]
	v_mfma_f32_16x16x32_bf16 v[104:107], v[140:143], v[198:201], v[104:107]
	v_mfma_f32_16x16x32_bf16 v[92:95], v[132:135], v[206:209], v[92:95]
	v_mfma_f32_16x16x32_bf16 v[88:91], v[140:143], v[206:209], v[88:91]
	v_mfma_f32_16x16x32_bf16 v[76:79], v[132:135], v[214:217], v[76:79]
	v_mfma_f32_16x16x32_bf16 v[72:75], v[140:143], v[214:217], v[72:75]
	v_mfma_f32_16x16x32_bf16 v[116:119], v[144:147], v[176:179], v[116:119]
	v_mfma_f32_16x16x32_bf16 v[112:115], v[168:171], v[176:179], v[112:115]
	v_mfma_f32_16x16x32_bf16 v[100:103], v[144:147], v[194:197], v[100:103]
	v_mfma_f32_16x16x32_bf16 v[96:99], v[168:171], v[194:197], v[96:99]
	v_mfma_f32_16x16x32_bf16 v[84:87], v[144:147], v[202:205], v[84:87]
	v_mfma_f32_16x16x32_bf16 v[80:83], v[168:171], v[202:205], v[80:83]
	v_mfma_f32_16x16x32_bf16 v[68:71], v[144:147], v[210:213], v[68:71]
	v_mfma_f32_16x16x32_bf16 v[64:67], v[168:171], v[210:213], v[64:67]
	v_mfma_f32_16x16x32_bf16 v[116:119], v[148:151], v[180:183], v[116:119]
	v_mfma_f32_16x16x32_bf16 v[112:115], v[172:175], v[180:183], v[112:115]
	v_mfma_f32_16x16x32_bf16 v[100:103], v[148:151], v[198:201], v[100:103]
	v_mfma_f32_16x16x32_bf16 v[96:99], v[172:175], v[198:201], v[96:99]
	v_mfma_f32_16x16x32_bf16 v[84:87], v[148:151], v[206:209], v[84:87]
	v_mfma_f32_16x16x32_bf16 v[80:83], v[172:175], v[206:209], v[80:83]
	v_mfma_f32_16x16x32_bf16 v[68:71], v[148:151], v[214:217], v[68:71]
	v_mfma_f32_16x16x32_bf16 v[64:67], v[172:175], v[214:217], v[64:67]
	s_barrier
	s_setprio 0
	s_add_u32 s98, s36, s16
	s_addc_u32 s99, s37, s17
	s_add_u32 s100, s38, s16
	s_addc_u32 s101, s39, s17
	s_add_i32 s59, s53, s41
	s_mov_b32 m0, s59
	ds_read_b128 v[176:179], v191 offset:16384
	ds_read_b128 v[180:183], v191 offset:17408
	ds_read_b128 v[194:197], v191 offset:18432
	ds_read_b128 v[198:201], v191 offset:19456
	ds_read_b128 v[202:205], v191 offset:20480
	ds_read_b128 v[206:209], v191 offset:21504
	ds_read_b128 v[210:213], v191 offset:22528
	ds_read_b128 v[214:217], v191 offset:23552
	global_load_lds_dwordx4 v154, s[36:37]
	s_add_i32 m0, s59, 0x2000
	s_add_u32 s60, s36, 0x80000
	s_addc_u32 s61, s37, 0
	s_add_i32 s59, s54, s41
	global_load_lds_dwordx4 v158, s[36:37]
	s_mov_b32 m0, s59
	s_nop 0
	global_load_lds_dwordx4 v154, s[60:61]
	s_add_i32 m0, s59, 0x2000
	s_nop 0
	global_load_lds_dwordx4 v158, s[60:61]
	s_mov_b32 m0, s31
	s_nop 0
	global_load_lds_dwordx4 v152, s[38:39]
	s_mov_b32 m0, s42
	s_nop 0
	global_load_lds_dwordx4 v156, s[38:39]
	s_waitcnt vmcnt(8)
	s_waitcnt lgkmcnt(0)
	s_setprio 1
	s_barrier
	v_mfma_f32_16x16x32_bf16 v[60:63], v[128:131], v[176:179], v[60:63]
	v_mfma_f32_16x16x32_bf16 v[56:59], v[136:139], v[176:179], v[56:59]
	v_mfma_f32_16x16x32_bf16 v[44:47], v[128:131], v[194:197], v[44:47]
	v_mfma_f32_16x16x32_bf16 v[40:43], v[136:139], v[194:197], v[40:43]
	v_mfma_f32_16x16x32_bf16 v[28:31], v[128:131], v[202:205], v[28:31]
	v_mfma_f32_16x16x32_bf16 v[24:27], v[136:139], v[202:205], v[24:27]
	v_mfma_f32_16x16x32_bf16 v[12:15], v[128:131], v[210:213], v[12:15]
	v_mfma_f32_16x16x32_bf16 v[8:11], v[136:139], v[210:213], v[8:11]
	v_mfma_f32_16x16x32_bf16 v[60:63], v[132:135], v[180:183], v[60:63]
	v_mfma_f32_16x16x32_bf16 v[56:59], v[140:143], v[180:183], v[56:59]
	v_mfma_f32_16x16x32_bf16 v[44:47], v[132:135], v[198:201], v[44:47]
	v_mfma_f32_16x16x32_bf16 v[40:43], v[140:143], v[198:201], v[40:43]
	v_mfma_f32_16x16x32_bf16 v[28:31], v[132:135], v[206:209], v[28:31]
	v_mfma_f32_16x16x32_bf16 v[24:27], v[140:143], v[206:209], v[24:27]
	v_mfma_f32_16x16x32_bf16 v[12:15], v[132:135], v[214:217], v[12:15]
	v_mfma_f32_16x16x32_bf16 v[8:11], v[140:143], v[214:217], v[8:11]
	v_mfma_f32_16x16x32_bf16 v[52:55], v[144:147], v[176:179], v[52:55]
	v_mfma_f32_16x16x32_bf16 v[48:51], v[168:171], v[176:179], v[48:51]
	v_mfma_f32_16x16x32_bf16 v[36:39], v[144:147], v[194:197], v[36:39]
	v_mfma_f32_16x16x32_bf16 v[32:35], v[168:171], v[194:197], v[32:35]
	v_mfma_f32_16x16x32_bf16 v[20:23], v[144:147], v[202:205], v[20:23]
	v_mfma_f32_16x16x32_bf16 v[16:19], v[168:171], v[202:205], v[16:19]
	v_mfma_f32_16x16x32_bf16 v[4:7], v[144:147], v[210:213], v[4:7]
	v_mfma_f32_16x16x32_bf16 v[0:3], v[168:171], v[210:213], v[0:3]
	v_mfma_f32_16x16x32_bf16 v[52:55], v[148:151], v[180:183], v[52:55]
	v_mfma_f32_16x16x32_bf16 v[48:51], v[172:175], v[180:183], v[48:51]
	v_mfma_f32_16x16x32_bf16 v[36:39], v[148:151], v[198:201], v[36:39]
	v_mfma_f32_16x16x32_bf16 v[32:35], v[172:175], v[198:201], v[32:35]
	v_mfma_f32_16x16x32_bf16 v[20:23], v[148:151], v[206:209], v[20:23]
	v_mfma_f32_16x16x32_bf16 v[16:19], v[172:175], v[206:209], v[16:19]
	v_mfma_f32_16x16x32_bf16 v[4:7], v[148:151], v[214:217], v[4:7]
	v_mfma_f32_16x16x32_bf16 v[0:3], v[172:175], v[214:217], v[0:3]
	s_barrier
; #define PG8_STAGE(bufoff, gbase, voff) do { _Pragma("unroll") for (int _i = 0; _i < 2; ++_i) \
;         __builtin_amdgcn_global_load_lds((const unsigned*)((const char*)(gbase) + (voff)[_i]), (LAS unsigned*)(lds + (bufoff) + ldsw + _i * 8192), 16, 0, ((voff) == voffA ? AUXA : 0)); } while (0)
; #define PG8_LDA(dst, b, h) do { _Pragma("unroll") for (int m = 0; m < 4; ++m) _Pragma("unroll") for (int k = 0; k < 2; ++k) dst[m][k] = *(const LAS bf16x8*)(lds + PG8_SA(b, h) + aoff + m * 2048 + k * 1024); } while (0)
; #define PG8_LDB(dst, b, h) do { _Pragma("unroll") for (int n = 0; n < 2; ++n) _Pragma("unroll") for (int k = 0; k < 2; ++k) dst[n][k] = *(const LAS bf16x8*)(lds + PG8_SB(b, h) + boff + n * 2048 + k * 1024); } while (0)
; #define PG8_MMA(ai, bj, At, Bt) do { __builtin_amdgcn_s_setprio(1); _Pragma("unroll") for (int m = 0; m < 4; ++m) _Pragma("unroll") for (int n = 0; n < 2; ++n) _Pragma("unroll") for (int k = 0; k < 2; ++k) \
;         acc[ai][bj][m][n] = __builtin_amdgcn_mfma_f32_16x16x32_bf16(Bt[n][k], At[m][k], acc[ai][bj][m][n], 0, 0, 0); __builtin_amdgcn_s_setprio(0); } while (0)
; #define PG8_WAIT_V(n) asm volatile("s_waitcnt vmcnt(" #n ")" ::: "memory")
; #define PG8_WAIT_L(n) asm volatile("s_waitcnt lgkmcnt(" #n ")" ::: "memory")
; #define PG8_BAR __builtin_amdgcn_s_barrier()
; #define PG8_SCHED __builtin_amdgcn_sched_barrier(0)
;     ...
;             PG8_LDB(B0, 1, 0); PG8_LDB(B1, 1, 1); PG8_SCHED; PG8_LDA(At, 1, 0); PG8_STAGE(PG8_SA(0, 1), a2 + hsA, voffA);
;             PG8_WAIT_V(8); PG8_WAIT_L(0); PG8_BAR; PG8_MMA(0, 0, At, B0); PG8_MMA(0, 1, At, B1); PG8_BAR; PG8_SCHED;
;             PG8_LDA(At, 1, 1); PG8_STAGE(PG8_SB(1, 0), b3, voffB); PG8_STAGE(PG8_SB(1, 1), b3 + hsB, voffB); PG8_STAGE(PG8_SA(1, 0), a3, voffA);
;             PG8_WAIT_V(8); PG8_WAIT_L(0); PG8_BAR; PG8_MMA(1, 0, At, B0); PG8_MMA(1, 1, At, B1); PG8_BAR; PG8_SCHED;
	s_setprio 0
	s_add_i32 s59, 0, 0x18000
	s_add_i32 s60, 0, 0x1c000
	v_add_u32_e32 v140, s59, v187
	v_add_u32_e32 v172, s60, v187
	ds_read_b128 v[128:131], v140
	ds_read_b128 v[132:135], v140 offset:1024
	ds_read_b128 v[136:139], v140 offset:2048
	ds_read_b128 v[140:143], v140 offset:3072
	ds_read_b128 v[144:147], v172
	ds_read_b128 v[148:151], v172 offset:1024
	ds_read_b128 v[168:171], v172 offset:2048
	ds_read_b128 v[172:175], v172 offset:3072
	s_add_u32 s38, s38, 0x80000
	s_addc_u32 s39, s39, 0
	s_mov_b32 m0, s43
	ds_read_b128 v[176:179], v191 offset:32768
	ds_read_b128 v[180:183], v191 offset:33792
	ds_read_b128 v[194:197], v191 offset:34816
	ds_read_b128 v[198:201], v191 offset:35840
	ds_read_b128 v[202:205], v191 offset:36864
	ds_read_b128 v[206:209], v191 offset:37888
	ds_read_b128 v[210:213], v191 offset:38912
	ds_read_b128 v[214:217], v191 offset:39936
	global_load_lds_dwordx4 v152, s[38:39]
	s_mov_b32 m0, s44
	s_nop 0
	global_load_lds_dwordx4 v156, s[38:39]
	s_waitcnt vmcnt(8)
	s_waitcnt lgkmcnt(0)
	s_setprio 1
	s_barrier
	v_mfma_f32_16x16x32_bf16 v[124:127], v[128:131], v[176:179], v[124:127]
	v_mfma_f32_16x16x32_bf16 v[120:123], v[136:139], v[176:179], v[120:123]
	v_mfma_f32_16x16x32_bf16 v[108:111], v[128:131], v[194:197], v[108:111]
	v_mfma_f32_16x16x32_bf16 v[104:107], v[136:139], v[194:197], v[104:107]
	v_mfma_f32_16x16x32_bf16 v[92:95], v[128:131], v[202:205], v[92:95]
	v_mfma_f32_16x16x32_bf16 v[88:91], v[136:139], v[202:205], v[88:91]
	v_mfma_f32_16x16x32_bf16 v[76:79], v[128:131], v[210:213], v[76:79]
	v_mfma_f32_16x16x32_bf16 v[72:75], v[136:139], v[210:213], v[72:75]
	v_mfma_f32_16x16x32_bf16 v[124:127], v[132:135], v[180:183], v[124:127]
	v_mfma_f32_16x16x32_bf16 v[120:123], v[140:143], v[180:183], v[120:123]
	v_mfma_f32_16x16x32_bf16 v[108:111], v[132:135], v[198:201], v[108:111]
	v_mfma_f32_16x16x32_bf16 v[104:107], v[140:143], v[198:201], v[104:107]
	v_mfma_f32_16x16x32_bf16 v[92:95], v[132:135], v[206:209], v[92:95]
	v_mfma_f32_16x16x32_bf16 v[88:91], v[140:143], v[206:209], v[88:91]
	v_mfma_f32_16x16x32_bf16 v[76:79], v[132:135], v[214:217], v[76:79]
	v_mfma_f32_16x16x32_bf16 v[72:75], v[140:143], v[214:217], v[72:75]
	v_mfma_f32_16x16x32_bf16 v[116:119], v[144:147], v[176:179], v[116:119]
	v_mfma_f32_16x16x32_bf16 v[112:115], v[168:171], v[176:179], v[112:115]
	v_mfma_f32_16x16x32_bf16 v[100:103], v[144:147], v[194:197], v[100:103]
	v_mfma_f32_16x16x32_bf16 v[96:99], v[168:171], v[194:197], v[96:99]
	v_mfma_f32_16x16x32_bf16 v[84:87], v[144:147], v[202:205], v[84:87]
	v_mfma_f32_16x16x32_bf16 v[80:83], v[168:171], v[202:205], v[80:83]
	v_mfma_f32_16x16x32_bf16 v[68:71], v[144:147], v[210:213], v[68:71]
	v_mfma_f32_16x16x32_bf16 v[64:67], v[168:171], v[210:213], v[64:67]
	v_mfma_f32_16x16x32_bf16 v[116:119], v[148:151], v[180:183], v[116:119]
	v_mfma_f32_16x16x32_bf16 v[112:115], v[172:175], v[180:183], v[112:115]
	v_mfma_f32_16x16x32_bf16 v[100:103], v[148:151], v[198:201], v[100:103]
	v_mfma_f32_16x16x32_bf16 v[96:99], v[172:175], v[198:201], v[96:99]
	v_mfma_f32_16x16x32_bf16 v[84:87], v[148:151], v[206:209], v[84:87]
	v_mfma_f32_16x16x32_bf16 v[80:83], v[172:175], v[206:209], v[80:83]
	v_mfma_f32_16x16x32_bf16 v[68:71], v[148:151], v[214:217], v[68:71]
	v_mfma_f32_16x16x32_bf16 v[64:67], v[172:175], v[214:217], v[64:67]
	s_barrier
	s_setprio 0
	s_add_i32 s38, s59, s41
	s_mov_b32 m0, s38
	ds_read_b128 v[176:179], v191 offset:49152
	ds_read_b128 v[180:183], v191 offset:50176
	ds_read_b128 v[194:197], v191 offset:51200
	ds_read_b128 v[198:201], v191 offset:52224
	ds_read_b128 v[202:205], v191 offset:53248
	ds_read_b128 v[206:209], v191 offset:54272
	ds_read_b128 v[210:213], v191 offset:55296
	ds_read_b128 v[214:217], v191 offset:56320
	global_load_lds_dwordx4 v154, s[98:99]
	s_add_i32 m0, s38, 0x2000
	s_add_u32 s36, s36, 0x80080
	s_addc_u32 s37, s37, 0
	s_add_i32 s38, s60, s41
	global_load_lds_dwordx4 v158, s[98:99]
	s_mov_b32 m0, s38
	s_nop 0
	global_load_lds_dwordx4 v154, s[36:37]
	s_add_i32 m0, s38, 0x2000
	s_nop 0
	global_load_lds_dwordx4 v158, s[36:37]
	s_mov_b32 m0, s47
	s_nop 0
	global_load_lds_dwordx4 v152, s[100:101]
	s_mov_b32 m0, s48
	s_nop 0
	global_load_lds_dwordx4 v156, s[100:101]
	s_waitcnt vmcnt(8)
	s_waitcnt lgkmcnt(0)
	s_setprio 1
	s_barrier
	v_mfma_f32_16x16x32_bf16 v[60:63], v[128:131], v[176:179], v[60:63]
	v_mfma_f32_16x16x32_bf16 v[56:59], v[136:139], v[176:179], v[56:59]
	v_mfma_f32_16x16x32_bf16 v[44:47], v[128:131], v[194:197], v[44:47]
	v_mfma_f32_16x16x32_bf16 v[40:43], v[136:139], v[194:197], v[40:43]
	v_mfma_f32_16x16x32_bf16 v[28:31], v[128:131], v[202:205], v[28:31]
	v_mfma_f32_16x16x32_bf16 v[24:27], v[136:139], v[202:205], v[24:27]
	v_mfma_f32_16x16x32_bf16 v[12:15], v[128:131], v[210:213], v[12:15]
	v_mfma_f32_16x16x32_bf16 v[8:11], v[136:139], v[210:213], v[8:11]
	v_mfma_f32_16x16x32_bf16 v[60:63], v[132:135], v[180:183], v[60:63]
	v_mfma_f32_16x16x32_bf16 v[56:59], v[140:143], v[180:183], v[56:59]
	v_mfma_f32_16x16x32_bf16 v[44:47], v[132:135], v[198:201], v[44:47]
	v_mfma_f32_16x16x32_bf16 v[40:43], v[140:143], v[198:201], v[40:43]
	v_mfma_f32_16x16x32_bf16 v[28:31], v[132:135], v[206:209], v[28:31]
	v_mfma_f32_16x16x32_bf16 v[24:27], v[140:143], v[206:209], v[24:27]
	v_mfma_f32_16x16x32_bf16 v[12:15], v[132:135], v[214:217], v[12:15]
	v_mfma_f32_16x16x32_bf16 v[8:11], v[140:143], v[214:217], v[8:11]
	v_mfma_f32_16x16x32_bf16 v[52:55], v[144:147], v[176:179], v[52:55]
	v_mfma_f32_16x16x32_bf16 v[48:51], v[168:171], v[176:179], v[48:51]
	v_mfma_f32_16x16x32_bf16 v[36:39], v[144:147], v[194:197], v[36:39]
	v_mfma_f32_16x16x32_bf16 v[32:35], v[168:171], v[194:197], v[32:35]
	v_mfma_f32_16x16x32_bf16 v[20:23], v[144:147], v[202:205], v[20:23]
	v_mfma_f32_16x16x32_bf16 v[16:19], v[168:171], v[202:205], v[16:19]
	v_mfma_f32_16x16x32_bf16 v[4:7], v[144:147], v[210:213], v[4:7]
	v_mfma_f32_16x16x32_bf16 v[0:3], v[168:171], v[210:213], v[0:3]
	v_mfma_f32_16x16x32_bf16 v[52:55], v[148:151], v[180:183], v[52:55]
	v_mfma_f32_16x16x32_bf16 v[48:51], v[172:175], v[180:183], v[48:51]
	v_mfma_f32_16x16x32_bf16 v[36:39], v[148:151], v[198:201], v[36:39]
	v_mfma_f32_16x16x32_bf16 v[32:35], v[172:175], v[198:201], v[32:35]
	v_mfma_f32_16x16x32_bf16 v[20:23], v[148:151], v[206:209], v[20:23]
	v_mfma_f32_16x16x32_bf16 v[16:19], v[172:175], v[206:209], v[16:19]
	v_mfma_f32_16x16x32_bf16 v[4:7], v[148:151], v[214:217], v[4:7]
	v_mfma_f32_16x16x32_bf16 v[0:3], v[172:175], v[214:217], v[0:3]
	s_barrier
	s_setprio 0
	s_add_u32 s34, s34, 0x100
	s_addc_u32 s35, s35, 0
	s_add_u32 s56, s56, 0x100
	s_addc_u32 s57, s57, 0
	s_cmp_ge_i32 s58, s46
	s_mov_b32 s36, s58
	s_cbranch_scc0 .LBB0_1267

; #define PG8_STAGE(bufoff, gbase, voff) do { _Pragma("unroll") for (int _i = 0; _i < 2; ++_i) \
;         __builtin_amdgcn_global_load_lds((const unsigned*)((const char*)(gbase) + (voff)[_i]), (LAS unsigned*)(lds + (bufoff) + ldsw + _i * 8192), 16, 0, ((voff) == voffA ? AUXA : 0)); } while (0)
; #define PG8_LDA(dst, b, h) do { _Pragma("unroll") for (int m = 0; m < 4; ++m) _Pragma("unroll") for (int k = 0; k < 2; ++k) dst[m][k] = *(const LAS bf16x8*)(lds + PG8_SA(b, h) + aoff + m * 2048 + k * 1024); } while (0)
; #define PG8_LDB(dst, b, h) do { _Pragma("unroll") for (int n = 0; n < 2; ++n) _Pragma("unroll") for (int k = 0; k < 2; ++k) dst[n][k] = *(const LAS bf16x8*)(lds + PG8_SB(b, h) + boff + n * 2048 + k * 1024); } while (0)
; #define PG8_MMA(ai, bj, At, Bt) do { __builtin_amdgcn_s_setprio(1); _Pragma("unroll") for (int m = 0; m < 4; ++m) _Pragma("unroll") for (int n = 0; n < 2; ++n) _Pragma("unroll") for (int k = 0; k < 2; ++k) \
;         acc[ai][bj][m][n] = __builtin_amdgcn_mfma_f32_16x16x32_bf16(Bt[n][k], At[m][k], acc[ai][bj][m][n], 0, 0, 0); __builtin_amdgcn_s_setprio(0); } while (0)
; #define PG8_WAIT_V(n) asm volatile("s_waitcnt vmcnt(" #n ")" ::: "memory")
; #define PG8_WAIT_L(n) asm volatile("s_waitcnt lgkmcnt(" #n ")" ::: "memory")
; #define PG8_BAR __builtin_amdgcn_s_barrier()
; #define PG8_SCHED __builtin_amdgcn_sched_barrier(0)
;     ...
;             PG8_WAIT_L(0); PG8_BAR; PG8_MMA(1, 0, At, B0); PG8_MMA(1, 1, At, B1); PG8_BAR; PG8_SCHED;
;             PG8_LDB(B0, 1, 0); PG8_LDB(B1, 1, 1); PG8_SCHED; PG8_LDA(At, 1, 0); PG8_STAGE(PG8_SA(0, 1), a2 + hsA, voffA);
;             PG8_WAIT_V(8); PG8_WAIT_L(0); PG8_BAR; PG8_MMA(0, 0, At, B0); PG8_MMA(0, 1, At, B1); PG8_BAR; PG8_SCHED;
;             PG8_LDA(At, 1, 1); PG8_STAGE(PG8_SB(1, 0), b3, voffB); PG8_STAGE(PG8_SB(1, 1), b3 + hsB, voffB); PG8_STAGE(PG8_SA(1, 0), a3, voffA);
.LBB0_1355:
	s_waitcnt lgkmcnt(0)
	s_add_i32 s61, s61, 2
	s_setprio 1
	s_barrier
	v_mfma_f32_16x16x32_bf16 v[60:63], v[144:147], v[184:187], v[60:63]
	v_mfma_f32_16x16x32_bf16 v[52:55], v[152:155], v[184:187], v[52:55]
	v_mfma_f32_16x16x32_bf16 v[44:47], v[144:147], v[176:179], v[44:47]
	v_mfma_f32_16x16x32_bf16 v[36:39], v[152:155], v[176:179], v[36:39]
	v_mfma_f32_16x16x32_bf16 v[28:31], v[144:147], v[168:171], v[28:31]
	v_mfma_f32_16x16x32_bf16 v[20:23], v[152:155], v[168:171], v[20:23]
	v_mfma_f32_16x16x32_bf16 v[12:15], v[144:147], v[160:163], v[12:15]
	v_mfma_f32_16x16x32_bf16 v[4:7], v[152:155], v[160:163], v[4:7]
	v_mfma_f32_16x16x32_bf16 v[60:63], v[148:151], v[188:191], v[60:63]
	v_mfma_f32_16x16x32_bf16 v[52:55], v[156:159], v[188:191], v[52:55]
	v_mfma_f32_16x16x32_bf16 v[44:47], v[148:151], v[180:183], v[44:47]
	v_mfma_f32_16x16x32_bf16 v[36:39], v[156:159], v[180:183], v[36:39]
	v_mfma_f32_16x16x32_bf16 v[28:31], v[148:151], v[172:175], v[28:31]
	v_mfma_f32_16x16x32_bf16 v[20:23], v[156:159], v[172:175], v[20:23]
	v_mfma_f32_16x16x32_bf16 v[12:15], v[148:151], v[164:167], v[12:15]
	v_mfma_f32_16x16x32_bf16 v[4:7], v[156:159], v[164:167], v[4:7]
	v_mfma_f32_16x16x32_bf16 v[56:59], v[128:131], v[184:187], v[56:59]
	v_mfma_f32_16x16x32_bf16 v[48:51], v[136:139], v[184:187], v[48:51]
	v_mfma_f32_16x16x32_bf16 v[40:43], v[128:131], v[176:179], v[40:43]
	v_mfma_f32_16x16x32_bf16 v[32:35], v[136:139], v[176:179], v[32:35]
	v_mfma_f32_16x16x32_bf16 v[24:27], v[128:131], v[168:171], v[24:27]
	v_mfma_f32_16x16x32_bf16 v[16:19], v[136:139], v[168:171], v[16:19]
	v_mfma_f32_16x16x32_bf16 v[8:11], v[128:131], v[160:163], v[8:11]
	v_mfma_f32_16x16x32_bf16 v[0:3], v[136:139], v[160:163], v[0:3]
	v_mfma_f32_16x16x32_bf16 v[56:59], v[132:135], v[188:191], v[56:59]
	v_mfma_f32_16x16x32_bf16 v[48:51], v[140:143], v[188:191], v[48:51]
	v_mfma_f32_16x16x32_bf16 v[40:43], v[132:135], v[180:183], v[40:43]
	v_mfma_f32_16x16x32_bf16 v[32:35], v[140:143], v[180:183], v[32:35]
	v_mfma_f32_16x16x32_bf16 v[24:27], v[132:135], v[172:175], v[24:27]
	v_mfma_f32_16x16x32_bf16 v[16:19], v[140:143], v[172:175], v[16:19]
	v_mfma_f32_16x16x32_bf16 v[8:11], v[132:135], v[164:167], v[8:11]
	v_mfma_f32_16x16x32_bf16 v[0:3], v[140:143], v[164:167], v[0:3]
	s_barrier
	s_setprio 0
	s_add_i32 s34, 0, 0x18000
	s_add_i32 s35, 0, 0x1c000
	v_add_u32_e32 v140, s34, v221
	v_add_u32_e32 v156, s35, v221
	ds_read_b128 v[128:131], v140
	ds_read_b128 v[132:135], v140 offset:1024
	ds_read_b128 v[136:139], v140 offset:2048
	ds_read_b128 v[140:143], v140 offset:3072
	ds_read_b128 v[144:147], v156
	ds_read_b128 v[148:151], v156 offset:1024
	ds_read_b128 v[152:155], v156 offset:2048
	ds_read_b128 v[156:159], v156 offset:3072
	s_add_u32 s30, s30, 0x80000
	s_addc_u32 s31, s31, 0
	s_mov_b32 m0, s46
	ds_read_b128 v[160:163], v225 offset:32768
	ds_read_b128 v[164:167], v225 offset:33792
	ds_read_b128 v[168:171], v225 offset:34816
	ds_read_b128 v[172:175], v225 offset:35840
	ds_read_b128 v[176:179], v225 offset:36864
	ds_read_b128 v[180:183], v225 offset:37888
	ds_read_b128 v[184:187], v225 offset:38912
	ds_read_b128 v[188:191], v225 offset:39936
	global_load_lds_dwordx4 v198, s[30:31]
	s_mov_b32 m0, s47
	s_nop 0
	global_load_lds_dwordx4 v194, s[30:31]
	s_waitcnt vmcnt(8)
	s_waitcnt lgkmcnt(0)
	s_setprio 1
	s_barrier
; #define PG8_STAGE(bufoff, gbase, voff) do { _Pragma("unroll") for (int _i = 0; _i < 2; ++_i) \
;         __builtin_amdgcn_global_load_lds((const unsigned*)((const char*)(gbase) + (voff)[_i]), (LAS unsigned*)(lds + (bufoff) + ldsw + _i * 8192), 16, 0, ((voff) == voffA ? AUXA : 0)); } while (0)
; #define PG8_LDA(dst, b, h) do { _Pragma("unroll") for (int m = 0; m < 4; ++m) _Pragma("unroll") for (int k = 0; k < 2; ++k) dst[m][k] = *(const LAS bf16x8*)(lds + PG8_SA(b, h) + aoff + m * 2048 + k * 1024); } while (0)
; #define PG8_MMA(ai, bj, At, Bt) do { __builtin_amdgcn_s_setprio(1); _Pragma("unroll") for (int m = 0; m < 4; ++m) _Pragma("unroll") for (int n = 0; n < 2; ++n) _Pragma("unroll") for (int k = 0; k < 2; ++k) \
;         acc[ai][bj][m][n] = __builtin_amdgcn_mfma_f32_16x16x32_bf16(Bt[n][k], At[m][k], acc[ai][bj][m][n], 0, 0, 0); __builtin_amdgcn_s_setprio(0); } while (0)
; #define PG8_WAIT_V(n) asm volatile("s_waitcnt vmcnt(" #n ")" ::: "memory")
; #define PG8_WAIT_L(n) asm volatile("s_waitcnt lgkmcnt(" #n ")" ::: "memory")
; #define PG8_BAR __builtin_amdgcn_s_barrier()
; #define PG8_SCHED __builtin_amdgcn_sched_barrier(0)
;     ...
;             PG8_WAIT_V(8); PG8_WAIT_L(0); PG8_BAR; PG8_MMA(0, 0, At, B0); PG8_MMA(0, 1, At, B1); PG8_BAR; PG8_SCHED;
;             PG8_LDA(At, 1, 1); PG8_STAGE(PG8_SB(1, 0), b3, voffB); PG8_STAGE(PG8_SB(1, 1), b3 + hsB, voffB); PG8_STAGE(PG8_SA(1, 0), a3, voffA);
;             PG8_WAIT_V(8); PG8_WAIT_L(0); PG8_BAR; PG8_MMA(1, 0, At, B0); PG8_MMA(1, 1, At, B1); PG8_BAR; PG8_SCHED;
	v_mfma_f32_16x16x32_bf16 v[124:127], v[128:131], v[160:163], v[124:127]
	v_mfma_f32_16x16x32_bf16 v[116:119], v[136:139], v[160:163], v[116:119]
	v_mfma_f32_16x16x32_bf16 v[108:111], v[128:131], v[168:171], v[108:111]
	v_mfma_f32_16x16x32_bf16 v[100:103], v[136:139], v[168:171], v[100:103]
	v_mfma_f32_16x16x32_bf16 v[92:95], v[128:131], v[176:179], v[92:95]
	v_mfma_f32_16x16x32_bf16 v[84:87], v[136:139], v[176:179], v[84:87]
	v_mfma_f32_16x16x32_bf16 v[76:79], v[128:131], v[184:187], v[76:79]
	v_mfma_f32_16x16x32_bf16 v[68:71], v[136:139], v[184:187], v[68:71]
	v_mfma_f32_16x16x32_bf16 v[124:127], v[132:135], v[164:167], v[124:127]
	v_mfma_f32_16x16x32_bf16 v[116:119], v[140:143], v[164:167], v[116:119]
	v_mfma_f32_16x16x32_bf16 v[108:111], v[132:135], v[172:175], v[108:111]
	v_mfma_f32_16x16x32_bf16 v[100:103], v[140:143], v[172:175], v[100:103]
	v_mfma_f32_16x16x32_bf16 v[92:95], v[132:135], v[180:183], v[92:95]
	v_mfma_f32_16x16x32_bf16 v[84:87], v[140:143], v[180:183], v[84:87]
	v_mfma_f32_16x16x32_bf16 v[76:79], v[132:135], v[188:191], v[76:79]
	v_mfma_f32_16x16x32_bf16 v[68:71], v[140:143], v[188:191], v[68:71]
	v_mfma_f32_16x16x32_bf16 v[120:123], v[144:147], v[160:163], v[120:123]
	v_mfma_f32_16x16x32_bf16 v[112:115], v[152:155], v[160:163], v[112:115]
	v_mfma_f32_16x16x32_bf16 v[104:107], v[144:147], v[168:171], v[104:107]
	v_mfma_f32_16x16x32_bf16 v[96:99], v[152:155], v[168:171], v[96:99]
	v_mfma_f32_16x16x32_bf16 v[88:91], v[144:147], v[176:179], v[88:91]
	v_mfma_f32_16x16x32_bf16 v[80:83], v[152:155], v[176:179], v[80:83]
	v_mfma_f32_16x16x32_bf16 v[72:75], v[144:147], v[184:187], v[72:75]
	v_mfma_f32_16x16x32_bf16 v[64:67], v[152:155], v[184:187], v[64:67]
	v_mfma_f32_16x16x32_bf16 v[120:123], v[148:151], v[164:167], v[120:123]
	v_mfma_f32_16x16x32_bf16 v[112:115], v[156:159], v[164:167], v[112:115]
	v_mfma_f32_16x16x32_bf16 v[104:107], v[148:151], v[172:175], v[104:107]
	v_mfma_f32_16x16x32_bf16 v[96:99], v[156:159], v[172:175], v[96:99]
	v_mfma_f32_16x16x32_bf16 v[88:91], v[148:151], v[180:183], v[88:91]
	v_mfma_f32_16x16x32_bf16 v[80:83], v[156:159], v[180:183], v[80:83]
	v_mfma_f32_16x16x32_bf16 v[72:75], v[148:151], v[188:191], v[72:75]
	v_mfma_f32_16x16x32_bf16 v[64:67], v[156:159], v[188:191], v[64:67]
	s_barrier
	s_setprio 0
	s_add_i32 s30, s34, s5
	s_mov_b32 m0, s30
	ds_read_b128 v[160:163], v225 offset:49152
	ds_read_b128 v[164:167], v225 offset:50176
	ds_read_b128 v[168:171], v225 offset:51200
	ds_read_b128 v[172:175], v225 offset:52224
	ds_read_b128 v[176:179], v225 offset:53248
	ds_read_b128 v[180:183], v225 offset:54272
	ds_read_b128 v[184:187], v225 offset:55296
	ds_read_b128 v[188:191], v225 offset:56320
	global_load_lds_dwordx4 v196, s[98:99]
	s_add_i32 m0, s30, 0x2000
	s_add_u32 s28, s28, 0x80080
	s_addc_u32 s29, s29, 0
	s_add_i32 s30, s35, s5
	global_load_lds_dwordx4 v192, s[98:99]
	s_mov_b32 m0, s30
	s_nop 0
	global_load_lds_dwordx4 v196, s[28:29]
	s_add_i32 m0, s30, 0x2000
	s_nop 0
	global_load_lds_dwordx4 v192, s[28:29]
	s_mov_b32 m0, s50
	s_nop 0
	global_load_lds_dwordx4 v198, s[100:101]
	s_mov_b32 m0, s51
	s_nop 0
	global_load_lds_dwordx4 v194, s[100:101]
	s_waitcnt vmcnt(8)
	s_waitcnt lgkmcnt(0)
	s_setprio 1
	s_barrier
	v_mfma_f32_16x16x32_bf16 v[60:63], v[128:131], v[160:163], v[60:63]
	v_mfma_f32_16x16x32_bf16 v[52:55], v[136:139], v[160:163], v[52:55]
	v_mfma_f32_16x16x32_bf16 v[44:47], v[128:131], v[168:171], v[44:47]
	v_mfma_f32_16x16x32_bf16 v[36:39], v[136:139], v[168:171], v[36:39]
	v_mfma_f32_16x16x32_bf16 v[28:31], v[128:131], v[176:179], v[28:31]
	v_mfma_f32_16x16x32_bf16 v[20:23], v[136:139], v[176:179], v[20:23]
	v_mfma_f32_16x16x32_bf16 v[12:15], v[128:131], v[184:187], v[12:15]
	v_mfma_f32_16x16x32_bf16 v[4:7], v[136:139], v[184:187], v[4:7]
	v_mfma_f32_16x16x32_bf16 v[60:63], v[132:135], v[164:167], v[60:63]
	v_mfma_f32_16x16x32_bf16 v[52:55], v[140:143], v[164:167], v[52:55]
	v_mfma_f32_16x16x32_bf16 v[44:47], v[132:135], v[172:175], v[44:47]
	v_mfma_f32_16x16x32_bf16 v[36:39], v[140:143], v[172:175], v[36:39]
	v_mfma_f32_16x16x32_bf16 v[28:31], v[132:135], v[180:183], v[28:31]
	v_mfma_f32_16x16x32_bf16 v[20:23], v[140:143], v[180:183], v[20:23]
	v_mfma_f32_16x16x32_bf16 v[12:15], v[132:135], v[188:191], v[12:15]
	v_mfma_f32_16x16x32_bf16 v[4:7], v[140:143], v[188:191], v[4:7]
	v_mfma_f32_16x16x32_bf16 v[56:59], v[144:147], v[160:163], v[56:59]
	v_mfma_f32_16x16x32_bf16 v[48:51], v[152:155], v[160:163], v[48:51]
	v_mfma_f32_16x16x32_bf16 v[40:43], v[144:147], v[168:171], v[40:43]
	v_mfma_f32_16x16x32_bf16 v[32:35], v[152:155], v[168:171], v[32:35]
	v_mfma_f32_16x16x32_bf16 v[24:27], v[144:147], v[176:179], v[24:27]
	v_mfma_f32_16x16x32_bf16 v[16:19], v[152:155], v[176:179], v[16:19]
	v_mfma_f32_16x16x32_bf16 v[8:11], v[144:147], v[184:187], v[8:11]
	v_mfma_f32_16x16x32_bf16 v[0:3], v[152:155], v[184:187], v[0:3]
	v_mfma_f32_16x16x32_bf16 v[56:59], v[148:151], v[164:167], v[56:59]
	v_mfma_f32_16x16x32_bf16 v[48:51], v[156:159], v[164:167], v[48:51]
	v_mfma_f32_16x16x32_bf16 v[40:43], v[148:151], v[172:175], v[40:43]
	v_mfma_f32_16x16x32_bf16 v[32:35], v[156:159], v[172:175], v[32:35]
	v_mfma_f32_16x16x32_bf16 v[24:27], v[148:151], v[180:183], v[24:27]
	v_mfma_f32_16x16x32_bf16 v[16:19], v[156:159], v[180:183], v[16:19]
	v_mfma_f32_16x16x32_bf16 v[8:11], v[148:151], v[188:191], v[8:11]
	v_mfma_f32_16x16x32_bf16 v[0:3], v[156:159], v[188:191], v[0:3]
	s_barrier
	s_setprio 0
	s_add_u32 s26, s26, 0x100
	s_addc_u32 s27, s27, 0
	s_add_u32 s59, s59, 0x100
	s_addc_u32 s60, s60, 0
	s_cmp_ge_i32 s61, s49
	s_cbranch_scc1 .LBB0_1365

; #define PG8_STAGE(bufoff, gbase, voff) do { _Pragma("unroll") for (int _i = 0; _i < 2; ++_i) \
;         __builtin_amdgcn_global_load_lds((const unsigned*)((const char*)(gbase) + (voff)[_i]), (LAS unsigned*)(lds + (bufoff) + ldsw + _i * 8192), 16, 0, ((voff) == voffA ? AUXA : 0)); } while (0)
; #define PG8_LDA(dst, b, h) do { _Pragma("unroll") for (int m = 0; m < 4; ++m) _Pragma("unroll") for (int k = 0; k < 2; ++k) dst[m][k] = *(const LAS bf16x8*)(lds + PG8_SA(b, h) + aoff + m * 2048 + k * 1024); } while (0)
; #define PG8_LDB(dst, b, h) do { _Pragma("unroll") for (int n = 0; n < 2; ++n) _Pragma("unroll") for (int k = 0; k < 2; ++k) dst[n][k] = *(const LAS bf16x8*)(lds + PG8_SB(b, h) + boff + n * 2048 + k * 1024); } while (0)
; #define PG8_MMA(ai, bj, At, Bt) do { __builtin_amdgcn_s_setprio(1); _Pragma("unroll") for (int m = 0; m < 4; ++m) _Pragma("unroll") for (int n = 0; n < 2; ++n) _Pragma("unroll") for (int k = 0; k < 2; ++k) \
;         acc[ai][bj][m][n] = __builtin_amdgcn_mfma_f32_16x16x32_bf16(Bt[n][k], At[m][k], acc[ai][bj][m][n], 0, 0, 0); __builtin_amdgcn_s_setprio(0); } while (0)
; #define PG8_WAIT_V(n) asm volatile("s_waitcnt vmcnt(" #n ")" ::: "memory")
; #define PG8_WAIT_L(n) asm volatile("s_waitcnt lgkmcnt(" #n ")" ::: "memory")
; #define PG8_BAR __builtin_amdgcn_s_barrier()
; #define PG8_SCHED __builtin_amdgcn_sched_barrier(0)
;     ...
;             const char* a2 = last ? nA : cA + (size_t)(t + 2) * kstep; const char* b2 = last ? nB : cB + (size_t)(t + 2) * kstep;
;             const char* a3 = a2 + kstep; const char* b3 = b2 + kstep;
;             PG8_LDB(B0, 0, 0); PG8_LDB(B1, 0, 1); PG8_SCHED; PG8_LDA(At, 0, 0); PG8_STAGE(PG8_SA(1, 1), a1 + hsA, voffA);
;             if (Epi::NPRE != 0 && last) { E.pre(sv, cur, wr, fr); PG8_WAIT_V(16); } else { PG8_WAIT_V(8); }
;             PG8_WAIT_L(0); PG8_BAR; PG8_MMA(0, 0, At, B0); PG8_MMA(0, 1, At, B1); PG8_BAR; PG8_SCHED;
;             PG8_LDA(At, 0, 1); PG8_STAGE(PG8_SB(0, 0), b2, voffB); PG8_STAGE(PG8_SB(0, 1), b2 + hsB, voffB); PG8_STAGE(PG8_SA(0, 0), a2, voffA);
;             if (Epi::NPRE != 0 && last) { PG8_WAIT_V(16); } else { PG8_WAIT_V(8); }
.LBB0_1360:
	s_add_u32 s30, s26, 0xfff80080
	s_addc_u32 s31, s27, -1
	s_waitcnt lgkmcnt(0)
	s_and_b64 s[28:29], s[28:29], exec
	s_cselect_b32 s31, s19, s31
	s_cselect_b32 s30, s21, s30
	s_cselect_b32 s29, s57, s60
	s_cselect_b32 s28, s58, s59
	s_setprio 1
	s_barrier
	v_mfma_f32_16x16x32_bf16 v[124:127], v[144:147], v[184:187], v[124:127]
	v_mfma_f32_16x16x32_bf16 v[116:119], v[152:155], v[184:187], v[116:119]
	v_mfma_f32_16x16x32_bf16 v[108:111], v[144:147], v[176:179], v[108:111]
	v_mfma_f32_16x16x32_bf16 v[100:103], v[152:155], v[176:179], v[100:103]
	v_mfma_f32_16x16x32_bf16 v[92:95], v[144:147], v[168:171], v[92:95]
	v_mfma_f32_16x16x32_bf16 v[84:87], v[152:155], v[168:171], v[84:87]
	v_mfma_f32_16x16x32_bf16 v[76:79], v[144:147], v[160:163], v[76:79]
	v_mfma_f32_16x16x32_bf16 v[68:71], v[152:155], v[160:163], v[68:71]
	v_mfma_f32_16x16x32_bf16 v[124:127], v[148:151], v[188:191], v[124:127]
	v_mfma_f32_16x16x32_bf16 v[116:119], v[156:159], v[188:191], v[116:119]
	v_mfma_f32_16x16x32_bf16 v[108:111], v[148:151], v[180:183], v[108:111]
	v_mfma_f32_16x16x32_bf16 v[100:103], v[156:159], v[180:183], v[100:103]
	v_mfma_f32_16x16x32_bf16 v[92:95], v[148:151], v[172:175], v[92:95]
	v_mfma_f32_16x16x32_bf16 v[84:87], v[156:159], v[172:175], v[84:87]
	v_mfma_f32_16x16x32_bf16 v[76:79], v[148:151], v[164:167], v[76:79]
	v_mfma_f32_16x16x32_bf16 v[68:71], v[156:159], v[164:167], v[68:71]
	v_mfma_f32_16x16x32_bf16 v[120:123], v[128:131], v[184:187], v[120:123]
	v_mfma_f32_16x16x32_bf16 v[112:115], v[136:139], v[184:187], v[112:115]
	v_mfma_f32_16x16x32_bf16 v[104:107], v[128:131], v[176:179], v[104:107]
	v_mfma_f32_16x16x32_bf16 v[96:99], v[136:139], v[176:179], v[96:99]
	v_mfma_f32_16x16x32_bf16 v[88:91], v[128:131], v[168:171], v[88:91]
	v_mfma_f32_16x16x32_bf16 v[80:83], v[136:139], v[168:171], v[80:83]
	v_mfma_f32_16x16x32_bf16 v[72:75], v[128:131], v[160:163], v[72:75]
	v_mfma_f32_16x16x32_bf16 v[64:67], v[136:139], v[160:163], v[64:67]
	v_mfma_f32_16x16x32_bf16 v[120:123], v[132:135], v[188:191], v[120:123]
	v_mfma_f32_16x16x32_bf16 v[112:115], v[140:143], v[188:191], v[112:115]
	v_mfma_f32_16x16x32_bf16 v[104:107], v[132:135], v[180:183], v[104:107]
	v_mfma_f32_16x16x32_bf16 v[96:99], v[140:143], v[180:183], v[96:99]
	v_mfma_f32_16x16x32_bf16 v[88:91], v[132:135], v[172:175], v[88:91]
	v_mfma_f32_16x16x32_bf16 v[80:83], v[140:143], v[172:175], v[80:83]
	v_mfma_f32_16x16x32_bf16 v[72:75], v[132:135], v[164:167], v[72:75]
	v_mfma_f32_16x16x32_bf16 v[64:67], v[140:143], v[164:167], v[64:67]
	s_barrier
	s_setprio 0
	s_add_u32 s98, s28, s14
	s_addc_u32 s99, s29, s15
	s_add_u32 s100, s30, s14
	s_addc_u32 s101, s31, s15
	s_mov_b32 m0, s41
	s_add_u32 s36, s28, 0x80000
	ds_read_b128 v[184:187], v225 offset:16384
	ds_read_b128 v[188:191], v225 offset:17408
	ds_read_b128 v[176:179], v225 offset:18432
	ds_read_b128 v[180:183], v225 offset:19456
	ds_read_b128 v[168:171], v225 offset:20480
	ds_read_b128 v[172:175], v225 offset:21504
	ds_read_b128 v[160:163], v225 offset:22528
	ds_read_b128 v[164:167], v225 offset:23552
	global_load_lds_dwordx4 v196, s[28:29]
	s_mov_b32 m0, s42
	s_addc_u32 s37, s29, 0
	global_load_lds_dwordx4 v192, s[28:29]
	s_mov_b32 m0, s43
	s_nop 0
	global_load_lds_dwordx4 v196, s[36:37]
	s_mov_b32 m0, s44
	s_nop 0
	global_load_lds_dwordx4 v192, s[36:37]
	s_mov_b64 s[36:37], -1
	s_mov_b32 m0, s40
	s_and_b64 vcc, exec, s[34:35]
	global_load_lds_dwordx4 v198, s[30:31]
	s_mov_b32 m0, s45
	s_nop 0
	global_load_lds_dwordx4 v194, s[30:31]
	s_cbranch_vccz .LBB0_1362
	s_waitcnt vmcnt(8)
	s_mov_b64 s[36:37], 0

; #define PG8_STAGE(bufoff, gbase, voff) do { _Pragma("unroll") for (int _i = 0; _i < 2; ++_i) \
;         __builtin_amdgcn_global_load_lds((const unsigned*)((const char*)(gbase) + (voff)[_i]), (LAS unsigned*)(lds + (bufoff) + ldsw + _i * 8192), 16, 0, ((voff) == voffA ? AUXA : 0)); } while (0)
; #define PG8_LDA(dst, b, h) do { _Pragma("unroll") for (int m = 0; m < 4; ++m) _Pragma("unroll") for (int k = 0; k < 2; ++k) dst[m][k] = *(const LAS bf16x8*)(lds + PG8_SA(b, h) + aoff + m * 2048 + k * 1024); } while (0)
; #define PG8_LDB(dst, b, h) do { _Pragma("unroll") for (int n = 0; n < 2; ++n) _Pragma("unroll") for (int k = 0; k < 2; ++k) dst[n][k] = *(const LAS bf16x8*)(lds + PG8_SB(b, h) + boff + n * 2048 + k * 1024); } while (0)
; #define PG8_MMA(ai, bj, At, Bt) do { __builtin_amdgcn_s_setprio(1); _Pragma("unroll") for (int m = 0; m < 4; ++m) _Pragma("unroll") for (int n = 0; n < 2; ++n) _Pragma("unroll") for (int k = 0; k < 2; ++k) \
;         acc[ai][bj][m][n] = __builtin_amdgcn_mfma_f32_16x16x32_bf16(Bt[n][k], At[m][k], acc[ai][bj][m][n], 0, 0, 0); __builtin_amdgcn_s_setprio(0); } while (0)
; #define PG8_WAIT_V(n) asm volatile("s_waitcnt vmcnt(" #n ")" ::: "memory")
; #define PG8_WAIT_L(n) asm volatile("s_waitcnt lgkmcnt(" #n ")" ::: "memory")
; #define PG8_BAR __builtin_amdgcn_s_barrier()
; #define PG8_SCHED __builtin_amdgcn_sched_barrier(0)
;     ...
;             PG8_LDB(B0, 0, 0); PG8_LDB(B1, 0, 1); PG8_SCHED; PG8_LDA(At, 0, 0); PG8_STAGE(PG8_SA(1, 1), a1 + hsA, voffA);
;             if (Epi::NPRE != 0 && last) { E.pre(sv, cur, wr, fr); PG8_WAIT_V(16); } else { PG8_WAIT_V(8); }
;             PG8_WAIT_L(0); PG8_BAR; PG8_MMA(0, 0, At, B0); PG8_MMA(0, 1, At, B1); PG8_BAR; PG8_SCHED;
;             PG8_LDA(At, 0, 1); PG8_STAGE(PG8_SB(0, 0), b2, voffB); PG8_STAGE(PG8_SB(0, 1), b2 + hsB, voffB); PG8_STAGE(PG8_SA(0, 0), a2, voffA);
;             if (Epi::NPRE != 0 && last) { PG8_WAIT_V(16); } else { PG8_WAIT_V(8); }
;             PG8_WAIT_L(0); PG8_BAR; PG8_MMA(1, 0, At, B0); PG8_MMA(1, 1, At, B1); PG8_BAR; PG8_SCHED;
.LBB0_1440:
	ds_read_b128 v[144:147], v159
	ds_read_b128 v[148:151], v159 offset:1024
	ds_read_b128 v[152:155], v159 offset:2048
	ds_read_b128 v[162:165], v159 offset:3072
	ds_read_b128 v[166:169], v160
	ds_read_b128 v[170:173], v160 offset:1024
	ds_read_b128 v[174:177], v160 offset:2048
	ds_read_b128 v[178:181], v160 offset:3072
	s_add_i32 s46, s18, 2
	s_add_u32 s19, s16, 0xffea0080
	s_addc_u32 s20, s17, -1
	s_cmp_eq_u32 s36, s18
	s_cselect_b32 s18, s14, s44
	s_cselect_b32 s21, s5, s20
	s_cselect_b32 s20, s4, s19
	s_cselect_b32 s19, s15, s45
	s_add_i32 m0, s26, 0xc000
	ds_read_b128 v[182:185], v161
	ds_read_b128 v[186:189], v161 offset:1024
	ds_read_b128 v[190:193], v161 offset:2048
	ds_read_b128 v[194:197], v161 offset:3072
	ds_read_b128 v[198:201], v161 offset:4096
	ds_read_b128 v[202:205], v161 offset:5120
	ds_read_b128 v[206:209], v161 offset:6144
	ds_read_b128 v[210:213], v161 offset:7168
	global_load_lds_dwordx4 v136, s[16:17]
	s_add_i32 m0, s26, 0xe000
	s_nop 0
	global_load_lds_dwordx4 v138, s[16:17]
	s_waitcnt vmcnt(8)
	s_waitcnt lgkmcnt(0)
	s_setprio 1
	s_barrier
	v_mfma_f32_16x16x32_bf16 v[124:127], v[144:147], v[182:185], v[124:127]
	v_mfma_f32_16x16x32_bf16 v[120:123], v[152:155], v[182:185], v[120:123]
	v_mfma_f32_16x16x32_bf16 v[116:119], v[144:147], v[190:193], v[116:119]
	v_mfma_f32_16x16x32_bf16 v[112:115], v[152:155], v[190:193], v[112:115]
	v_mfma_f32_16x16x32_bf16 v[104:107], v[144:147], v[198:201], v[104:107]
	v_mfma_f32_16x16x32_bf16 v[96:99], v[152:155], v[198:201], v[96:99]
	v_mfma_f32_16x16x32_bf16 v[88:91], v[144:147], v[206:209], v[88:91]
	v_mfma_f32_16x16x32_bf16 v[80:83], v[152:155], v[206:209], v[80:83]
	v_mfma_f32_16x16x32_bf16 v[124:127], v[148:151], v[186:189], v[124:127]
	v_mfma_f32_16x16x32_bf16 v[120:123], v[162:165], v[186:189], v[120:123]
	v_mfma_f32_16x16x32_bf16 v[116:119], v[148:151], v[194:197], v[116:119]
	v_mfma_f32_16x16x32_bf16 v[112:115], v[162:165], v[194:197], v[112:115]
	v_mfma_f32_16x16x32_bf16 v[104:107], v[148:151], v[202:205], v[104:107]
	v_mfma_f32_16x16x32_bf16 v[96:99], v[162:165], v[202:205], v[96:99]
	v_mfma_f32_16x16x32_bf16 v[88:91], v[148:151], v[210:213], v[88:91]
	v_mfma_f32_16x16x32_bf16 v[80:83], v[162:165], v[210:213], v[80:83]
	v_mfma_f32_16x16x32_bf16 v[108:111], v[166:169], v[182:185], v[108:111]
	v_mfma_f32_16x16x32_bf16 v[100:103], v[174:177], v[182:185], v[100:103]
	v_mfma_f32_16x16x32_bf16 v[92:95], v[166:169], v[190:193], v[92:95]
	v_mfma_f32_16x16x32_bf16 v[84:87], v[174:177], v[190:193], v[84:87]
	v_mfma_f32_16x16x32_bf16 v[76:79], v[166:169], v[198:201], v[76:79]
	v_mfma_f32_16x16x32_bf16 v[72:75], v[174:177], v[198:201], v[72:75]
	v_mfma_f32_16x16x32_bf16 v[68:71], v[166:169], v[206:209], v[68:71]
	v_mfma_f32_16x16x32_bf16 v[64:67], v[174:177], v[206:209], v[64:67]
	v_mfma_f32_16x16x32_bf16 v[108:111], v[170:173], v[186:189], v[108:111]
	v_mfma_f32_16x16x32_bf16 v[100:103], v[178:181], v[186:189], v[100:103]
	v_mfma_f32_16x16x32_bf16 v[92:95], v[170:173], v[194:197], v[92:95]
	v_mfma_f32_16x16x32_bf16 v[84:87], v[178:181], v[194:197], v[84:87]
	v_mfma_f32_16x16x32_bf16 v[76:79], v[170:173], v[202:205], v[76:79]
	v_mfma_f32_16x16x32_bf16 v[72:75], v[178:181], v[202:205], v[72:75]
	v_mfma_f32_16x16x32_bf16 v[68:71], v[170:173], v[210:213], v[68:71]
	v_mfma_f32_16x16x32_bf16 v[64:67], v[178:181], v[210:213], v[64:67]
	s_barrier
	s_setprio 0
	s_add_u32 s98, s18, s8
	s_addc_u32 s99, s19, s9
	s_add_u32 s100, s20, s8
	s_addc_u32 s101, s21, s9
	s_add_i32 s47, s38, s23
	s_mov_b32 m0, s47
	ds_read_b128 v[182:185], v161 offset:16384
	ds_read_b128 v[186:189], v161 offset:17408
	ds_read_b128 v[190:193], v161 offset:18432
	ds_read_b128 v[194:197], v161 offset:19456
	ds_read_b128 v[198:201], v161 offset:20480
	ds_read_b128 v[202:205], v161 offset:21504
	ds_read_b128 v[206:209], v161 offset:22528
	ds_read_b128 v[210:213], v161 offset:23552
	global_load_lds_dwordx4 v132, s[18:19]
	s_add_i32 m0, s47, 0x2000
	s_add_u32 s48, s18, 0x160000
	s_addc_u32 s49, s19, 0
	s_add_i32 s47, s39, s23
	global_load_lds_dwordx4 v128, s[18:19]
	s_mov_b32 m0, s47
	s_nop 0
	global_load_lds_dwordx4 v132, s[48:49]
	s_add_i32 m0, s47, 0x2000
	s_nop 0
	global_load_lds_dwordx4 v128, s[48:49]
	s_mov_b32 m0, s26
	s_nop 0
	global_load_lds_dwordx4 v134, s[20:21]
	s_mov_b32 m0, s27
	s_nop 0
	global_load_lds_dwordx4 v130, s[20:21]
	s_waitcnt vmcnt(8)
	s_waitcnt lgkmcnt(0)
	s_setprio 1
	s_barrier
	v_mfma_f32_16x16x32_bf16 v[60:63], v[144:147], v[182:185], v[60:63]
	v_mfma_f32_16x16x32_bf16 v[56:59], v[152:155], v[182:185], v[56:59]
	v_mfma_f32_16x16x32_bf16 v[52:55], v[144:147], v[190:193], v[52:55]
	v_mfma_f32_16x16x32_bf16 v[48:51], v[152:155], v[190:193], v[48:51]
	v_mfma_f32_16x16x32_bf16 v[40:43], v[144:147], v[198:201], v[40:43]
	v_mfma_f32_16x16x32_bf16 v[32:35], v[152:155], v[198:201], v[32:35]
	v_mfma_f32_16x16x32_bf16 v[24:27], v[144:147], v[206:209], v[24:27]
	v_mfma_f32_16x16x32_bf16 v[16:19], v[152:155], v[206:209], v[16:19]
	v_mfma_f32_16x16x32_bf16 v[60:63], v[148:151], v[186:189], v[60:63]
	v_mfma_f32_16x16x32_bf16 v[56:59], v[162:165], v[186:189], v[56:59]
	v_mfma_f32_16x16x32_bf16 v[52:55], v[148:151], v[194:197], v[52:55]
	v_mfma_f32_16x16x32_bf16 v[48:51], v[162:165], v[194:197], v[48:51]
	v_mfma_f32_16x16x32_bf16 v[40:43], v[148:151], v[202:205], v[40:43]
	v_mfma_f32_16x16x32_bf16 v[32:35], v[162:165], v[202:205], v[32:35]
	v_mfma_f32_16x16x32_bf16 v[24:27], v[148:151], v[210:213], v[24:27]
	v_mfma_f32_16x16x32_bf16 v[16:19], v[162:165], v[210:213], v[16:19]
	v_mfma_f32_16x16x32_bf16 v[44:47], v[166:169], v[182:185], v[44:47]
	v_mfma_f32_16x16x32_bf16 v[36:39], v[174:177], v[182:185], v[36:39]
	v_mfma_f32_16x16x32_bf16 v[28:31], v[166:169], v[190:193], v[28:31]
	v_mfma_f32_16x16x32_bf16 v[20:23], v[174:177], v[190:193], v[20:23]
	v_mfma_f32_16x16x32_bf16 v[12:15], v[166:169], v[198:201], v[12:15]
	v_mfma_f32_16x16x32_bf16 v[8:11], v[174:177], v[198:201], v[8:11]
	v_mfma_f32_16x16x32_bf16 v[4:7], v[166:169], v[206:209], v[4:7]
	v_mfma_f32_16x16x32_bf16 v[0:3], v[174:177], v[206:209], v[0:3]
	v_mfma_f32_16x16x32_bf16 v[44:47], v[170:173], v[186:189], v[44:47]
	v_mfma_f32_16x16x32_bf16 v[36:39], v[178:181], v[186:189], v[36:39]
	v_mfma_f32_16x16x32_bf16 v[28:31], v[170:173], v[194:197], v[28:31]
	v_mfma_f32_16x16x32_bf16 v[20:23], v[178:181], v[194:197], v[20:23]
	v_mfma_f32_16x16x32_bf16 v[12:15], v[170:173], v[202:205], v[12:15]
	v_mfma_f32_16x16x32_bf16 v[8:11], v[178:181], v[202:205], v[8:11]
	v_mfma_f32_16x16x32_bf16 v[4:7], v[170:173], v[210:213], v[4:7]
	v_mfma_f32_16x16x32_bf16 v[0:3], v[178:181], v[210:213], v[0:3]
	s_barrier
; #define PG8_STAGE(bufoff, gbase, voff) do { _Pragma("unroll") for (int _i = 0; _i < 2; ++_i) \
;         __builtin_amdgcn_global_load_lds((const unsigned*)((const char*)(gbase) + (voff)[_i]), (LAS unsigned*)(lds + (bufoff) + ldsw + _i * 8192), 16, 0, ((voff) == voffA ? AUXA : 0)); } while (0)
; #define PG8_LDA(dst, b, h) do { _Pragma("unroll") for (int m = 0; m < 4; ++m) _Pragma("unroll") for (int k = 0; k < 2; ++k) dst[m][k] = *(const LAS bf16x8*)(lds + PG8_SA(b, h) + aoff + m * 2048 + k * 1024); } while (0)
; #define PG8_LDB(dst, b, h) do { _Pragma("unroll") for (int n = 0; n < 2; ++n) _Pragma("unroll") for (int k = 0; k < 2; ++k) dst[n][k] = *(const LAS bf16x8*)(lds + PG8_SB(b, h) + boff + n * 2048 + k * 1024); } while (0)
; #define PG8_MMA(ai, bj, At, Bt) do { __builtin_amdgcn_s_setprio(1); _Pragma("unroll") for (int m = 0; m < 4; ++m) _Pragma("unroll") for (int n = 0; n < 2; ++n) _Pragma("unroll") for (int k = 0; k < 2; ++k) \
;         acc[ai][bj][m][n] = __builtin_amdgcn_mfma_f32_16x16x32_bf16(Bt[n][k], At[m][k], acc[ai][bj][m][n], 0, 0, 0); __builtin_amdgcn_s_setprio(0); } while (0)
; #define PG8_WAIT_V(n) asm volatile("s_waitcnt vmcnt(" #n ")" ::: "memory")
; #define PG8_WAIT_L(n) asm volatile("s_waitcnt lgkmcnt(" #n ")" ::: "memory")
; #define PG8_BAR __builtin_amdgcn_s_barrier()
; #define PG8_SCHED __builtin_amdgcn_sched_barrier(0)
;     ...
;             PG8_LDB(B0, 1, 0); PG8_LDB(B1, 1, 1); PG8_SCHED; PG8_LDA(At, 1, 0); PG8_STAGE(PG8_SA(0, 1), a2 + hsA, voffA);
;             PG8_WAIT_V(8); PG8_WAIT_L(0); PG8_BAR; PG8_MMA(0, 0, At, B0); PG8_MMA(0, 1, At, B1); PG8_BAR; PG8_SCHED;
;             PG8_LDA(At, 1, 1); PG8_STAGE(PG8_SB(1, 0), b3, voffB); PG8_STAGE(PG8_SB(1, 1), b3 + hsB, voffB); PG8_STAGE(PG8_SA(1, 0), a3, voffA);
	s_setprio 0
	s_add_i32 s47, 0, 0x18000
	s_add_i32 s48, 0, 0x1c000
	v_add_u32_e32 v162, s47, v157
	v_add_u32_e32 v178, s48, v157
	ds_read_b128 v[144:147], v162
	ds_read_b128 v[148:151], v162 offset:1024
	ds_read_b128 v[152:155], v162 offset:2048
	ds_read_b128 v[162:165], v162 offset:3072
	ds_read_b128 v[166:169], v178
	ds_read_b128 v[170:173], v178 offset:1024
	ds_read_b128 v[174:177], v178 offset:2048
	ds_read_b128 v[178:181], v178 offset:3072
	s_add_u32 s20, s20, 0x160000
	s_addc_u32 s21, s21, 0
	s_mov_b32 m0, s28
	ds_read_b128 v[182:185], v161 offset:32768
	ds_read_b128 v[186:189], v161 offset:33792
	ds_read_b128 v[190:193], v161 offset:34816
	ds_read_b128 v[194:197], v161 offset:35840
	ds_read_b128 v[198:201], v161 offset:36864
	ds_read_b128 v[202:205], v161 offset:37888
	ds_read_b128 v[206:209], v161 offset:38912
	ds_read_b128 v[210:213], v161 offset:39936
	global_load_lds_dwordx4 v134, s[20:21]
	s_mov_b32 m0, s29
	s_nop 0
	global_load_lds_dwordx4 v130, s[20:21]
	s_waitcnt vmcnt(8)
	s_waitcnt lgkmcnt(0)
	s_setprio 1
	s_barrier
	v_mfma_f32_16x16x32_bf16 v[124:127], v[144:147], v[182:185], v[124:127]
	v_mfma_f32_16x16x32_bf16 v[120:123], v[152:155], v[182:185], v[120:123]
	v_mfma_f32_16x16x32_bf16 v[116:119], v[144:147], v[190:193], v[116:119]
	v_mfma_f32_16x16x32_bf16 v[112:115], v[152:155], v[190:193], v[112:115]
	v_mfma_f32_16x16x32_bf16 v[104:107], v[144:147], v[198:201], v[104:107]
	v_mfma_f32_16x16x32_bf16 v[96:99], v[152:155], v[198:201], v[96:99]
	v_mfma_f32_16x16x32_bf16 v[88:91], v[144:147], v[206:209], v[88:91]
	v_mfma_f32_16x16x32_bf16 v[80:83], v[152:155], v[206:209], v[80:83]
	v_mfma_f32_16x16x32_bf16 v[124:127], v[148:151], v[186:189], v[124:127]
	v_mfma_f32_16x16x32_bf16 v[120:123], v[162:165], v[186:189], v[120:123]
	v_mfma_f32_16x16x32_bf16 v[116:119], v[148:151], v[194:197], v[116:119]
	v_mfma_f32_16x16x32_bf16 v[112:115], v[162:165], v[194:197], v[112:115]
	v_mfma_f32_16x16x32_bf16 v[104:107], v[148:151], v[202:205], v[104:107]
	v_mfma_f32_16x16x32_bf16 v[96:99], v[162:165], v[202:205], v[96:99]
	v_mfma_f32_16x16x32_bf16 v[88:91], v[148:151], v[210:213], v[88:91]
	v_mfma_f32_16x16x32_bf16 v[80:83], v[162:165], v[210:213], v[80:83]
	v_mfma_f32_16x16x32_bf16 v[108:111], v[166:169], v[182:185], v[108:111]
	v_mfma_f32_16x16x32_bf16 v[100:103], v[174:177], v[182:185], v[100:103]
	v_mfma_f32_16x16x32_bf16 v[92:95], v[166:169], v[190:193], v[92:95]
	v_mfma_f32_16x16x32_bf16 v[84:87], v[174:177], v[190:193], v[84:87]
	v_mfma_f32_16x16x32_bf16 v[76:79], v[166:169], v[198:201], v[76:79]
	v_mfma_f32_16x16x32_bf16 v[72:75], v[174:177], v[198:201], v[72:75]
	v_mfma_f32_16x16x32_bf16 v[68:71], v[166:169], v[206:209], v[68:71]
	v_mfma_f32_16x16x32_bf16 v[64:67], v[174:177], v[206:209], v[64:67]
	v_mfma_f32_16x16x32_bf16 v[108:111], v[170:173], v[186:189], v[108:111]
	v_mfma_f32_16x16x32_bf16 v[100:103], v[178:181], v[186:189], v[100:103]
	v_mfma_f32_16x16x32_bf16 v[92:95], v[170:173], v[194:197], v[92:95]
	v_mfma_f32_16x16x32_bf16 v[84:87], v[178:181], v[194:197], v[84:87]
	v_mfma_f32_16x16x32_bf16 v[76:79], v[170:173], v[202:205], v[76:79]
	v_mfma_f32_16x16x32_bf16 v[72:75], v[178:181], v[202:205], v[72:75]
	v_mfma_f32_16x16x32_bf16 v[68:71], v[170:173], v[210:213], v[68:71]
	v_mfma_f32_16x16x32_bf16 v[64:67], v[178:181], v[210:213], v[64:67]
	s_barrier
	s_setprio 0
	s_add_i32 s20, s47, s23
	s_mov_b32 m0, s20
	ds_read_b128 v[182:185], v161 offset:49152
	ds_read_b128 v[186:189], v161 offset:50176
	ds_read_b128 v[190:193], v161 offset:51200
	ds_read_b128 v[194:197], v161 offset:52224
	ds_read_b128 v[198:201], v161 offset:53248
	ds_read_b128 v[202:205], v161 offset:54272
	ds_read_b128 v[206:209], v161 offset:55296
	ds_read_b128 v[210:213], v161 offset:56320
	global_load_lds_dwordx4 v132, s[98:99]
	s_add_i32 m0, s20, 0x2000
	s_add_u32 s18, s18, 0x160080
	s_addc_u32 s19, s19, 0
	s_add_i32 s20, s48, s23
	global_load_lds_dwordx4 v128, s[98:99]
	s_mov_b32 m0, s20
	s_nop 0
	global_load_lds_dwordx4 v132, s[18:19]
	s_add_i32 m0, s20, 0x2000
	s_nop 0
	global_load_lds_dwordx4 v128, s[18:19]
	s_mov_b32 m0, s34
	s_nop 0
	global_load_lds_dwordx4 v134, s[100:101]
	s_mov_b32 m0, s35
	s_nop 0
	global_load_lds_dwordx4 v130, s[100:101]
	s_waitcnt vmcnt(8)
	s_waitcnt lgkmcnt(0)
	s_setprio 1
	s_barrier
; #define PG8_MMA(ai, bj, At, Bt) do { __builtin_amdgcn_s_setprio(1); _Pragma("unroll") for (int m = 0; m < 4; ++m) _Pragma("unroll") for (int n = 0; n < 2; ++n) _Pragma("unroll") for (int k = 0; k < 2; ++k) \
;         acc[ai][bj][m][n] = __builtin_amdgcn_mfma_f32_16x16x32_bf16(Bt[n][k], At[m][k], acc[ai][bj][m][n], 0, 0, 0); __builtin_amdgcn_s_setprio(0); } while (0)
; #define PG8_WAIT_V(n) asm volatile("s_waitcnt vmcnt(" #n ")" ::: "memory")
; #define PG8_WAIT_L(n) asm volatile("s_waitcnt lgkmcnt(" #n ")" ::: "memory")
; #define PG8_BAR __builtin_amdgcn_s_barrier()
; #define PG8_SCHED __builtin_amdgcn_sched_barrier(0)
;     ...
;             PG8_WAIT_V(8); PG8_WAIT_L(0); PG8_BAR; PG8_MMA(1, 0, At, B0); PG8_MMA(1, 1, At, B1); PG8_BAR; PG8_SCHED;
;     __device__ __forceinline__ void operator()(const Acc& acc, const Unit& u, int wr, int wc, int fr, int fq, const float (&sv8)[8]) const {
;     ...
;                     const f32x4 y0 = xr[m][bj][0] + acc[ai][bj][m][0] * scale, y1 = xr[m][bj][1] + acc[ai][bj][m][1] * scale;
	v_mfma_f32_16x16x32_bf16 v[60:63], v[144:147], v[182:185], v[60:63]
	v_mfma_f32_16x16x32_bf16 v[56:59], v[152:155], v[182:185], v[56:59]
	v_mfma_f32_16x16x32_bf16 v[52:55], v[144:147], v[190:193], v[52:55]
	v_mfma_f32_16x16x32_bf16 v[48:51], v[152:155], v[190:193], v[48:51]
	v_mfma_f32_16x16x32_bf16 v[40:43], v[144:147], v[198:201], v[40:43]
	v_mfma_f32_16x16x32_bf16 v[32:35], v[152:155], v[198:201], v[32:35]
	v_mfma_f32_16x16x32_bf16 v[24:27], v[144:147], v[206:209], v[24:27]
	v_mfma_f32_16x16x32_bf16 v[16:19], v[152:155], v[206:209], v[16:19]
	v_mfma_f32_16x16x32_bf16 v[60:63], v[148:151], v[186:189], v[60:63]
	v_mfma_f32_16x16x32_bf16 v[56:59], v[162:165], v[186:189], v[56:59]
	v_mfma_f32_16x16x32_bf16 v[52:55], v[148:151], v[194:197], v[52:55]
	v_mfma_f32_16x16x32_bf16 v[48:51], v[162:165], v[194:197], v[48:51]
	v_mfma_f32_16x16x32_bf16 v[40:43], v[148:151], v[202:205], v[40:43]
	v_mfma_f32_16x16x32_bf16 v[32:35], v[162:165], v[202:205], v[32:35]
	v_mfma_f32_16x16x32_bf16 v[24:27], v[148:151], v[210:213], v[24:27]
	v_mfma_f32_16x16x32_bf16 v[16:19], v[162:165], v[210:213], v[16:19]
	v_mfma_f32_16x16x32_bf16 v[44:47], v[166:169], v[182:185], v[44:47]
	v_mfma_f32_16x16x32_bf16 v[36:39], v[174:177], v[182:185], v[36:39]
	v_mfma_f32_16x16x32_bf16 v[28:31], v[166:169], v[190:193], v[28:31]
	v_mfma_f32_16x16x32_bf16 v[20:23], v[174:177], v[190:193], v[20:23]
	v_mfma_f32_16x16x32_bf16 v[12:15], v[166:169], v[198:201], v[12:15]
	v_mfma_f32_16x16x32_bf16 v[8:11], v[174:177], v[198:201], v[8:11]
	v_mfma_f32_16x16x32_bf16 v[4:7], v[166:169], v[206:209], v[4:7]
	v_mfma_f32_16x16x32_bf16 v[0:3], v[174:177], v[206:209], v[0:3]
	v_mfma_f32_16x16x32_bf16 v[44:47], v[170:173], v[186:189], v[44:47]
	v_mfma_f32_16x16x32_bf16 v[36:39], v[178:181], v[186:189], v[36:39]
	v_mfma_f32_16x16x32_bf16 v[28:31], v[170:173], v[194:197], v[28:31]
	v_mfma_f32_16x16x32_bf16 v[20:23], v[178:181], v[194:197], v[20:23]
	v_mfma_f32_16x16x32_bf16 v[12:15], v[170:173], v[202:205], v[12:15]
	v_mfma_f32_16x16x32_bf16 v[8:11], v[178:181], v[202:205], v[8:11]
	v_mfma_f32_16x16x32_bf16 v[4:7], v[170:173], v[210:213], v[4:7]
	v_mfma_f32_16x16x32_bf16 v[0:3], v[178:181], v[210:213], v[0:3]
	s_barrier
	s_setprio 0
	s_add_u32 s16, s16, 0x100
	s_addc_u32 s17, s17, 0
	s_add_u32 s44, s44, 0x100
	s_addc_u32 s45, s45, 0
	s_cmp_ge_i32 s46, s31
	s_mov_b32 s18, s46
	s_cbranch_scc0 .LBB0_1440
	v_pk_mul_f32 v[126:127], v[126:127], 0.5 op_sel_hi:[1,0]
	v_pk_mul_f32 v[146:147], v[124:125], 0.5 op_sel_hi:[1,0]
	v_pk_mul_f32 v[144:145], v[122:123], 0.5 op_sel_hi:[1,0]
	v_pk_mul_f32 v[124:125], v[120:121], 0.5 op_sel_hi:[1,0]
	v_pk_mul_f32 v[154:155], v[110:111], 0.5 op_sel_hi:[1,0]
	v_pk_mul_f32 v[152:153], v[108:109], 0.5 op_sel_hi:[1,0]
	v_pk_mul_f32 v[150:151], v[102:103], 0.5 op_sel_hi:[1,0]
	v_pk_mul_f32 v[148:149], v[100:101], 0.5 op_sel_hi:[1,0]
	v_pk_mul_f32 v[118:119], v[118:119], 0.5 op_sel_hi:[1,0]
	v_pk_mul_f32 v[116:117], v[116:117], 0.5 op_sel_hi:[1,0]
	v_pk_mul_f32 v[110:111], v[114:115], 0.5 op_sel_hi:[1,0]
	v_pk_mul_f32 v[108:109], v[112:113], 0.5 op_sel_hi:[1,0]
	v_pk_mul_f32 v[122:123], v[94:95], 0.5 op_sel_hi:[1,0]
	v_pk_mul_f32 v[120:121], v[92:93], 0.5 op_sel_hi:[1,0]
	v_pk_mul_f32 v[114:115], v[86:87], 0.5 op_sel_hi:[1,0]
	v_pk_mul_f32 v[112:113], v[84:85], 0.5 op_sel_hi:[1,0]
	v_pk_mul_f32 v[102:103], v[106:107], 0.5 op_sel_hi:[1,0]
	v_pk_mul_f32 v[100:101], v[104:105], 0.5 op_sel_hi:[1,0]
	v_pk_mul_f32 v[94:95], v[98:99], 0.5 op_sel_hi:[1,0]
	v_pk_mul_f32 v[92:93], v[96:97], 0.5 op_sel_hi:[1,0]
	v_pk_mul_f32 v[106:107], v[78:79], 0.5 op_sel_hi:[1,0]
	v_pk_mul_f32 v[104:105], v[76:77], 0.5 op_sel_hi:[1,0]
	v_pk_mul_f32 v[98:99], v[74:75], 0.5 op_sel_hi:[1,0]
	v_pk_mul_f32 v[96:97], v[72:73], 0.5 op_sel_hi:[1,0]
	v_pk_mul_f32 v[86:87], v[90:91], 0.5 op_sel_hi:[1,0]
	v_pk_mul_f32 v[84:85], v[88:89], 0.5 op_sel_hi:[1,0]
	v_pk_mul_f32 v[78:79], v[82:83], 0.5 op_sel_hi:[1,0]
	v_pk_mul_f32 v[76:77], v[80:81], 0.5 op_sel_hi:[1,0]
	v_pk_mul_f32 v[90:91], v[70:71], 0.5 op_sel_hi:[1,0]
	v_pk_mul_f32 v[88:89], v[68:69], 0.5 op_sel_hi:[1,0]
	v_pk_mul_f32 v[82:83], v[66:67], 0.5 op_sel_hi:[1,0]
	v_pk_mul_f32 v[80:81], v[64:65], 0.5 op_sel_hi:[1,0]
	v_pk_mul_f32 v[66:67], v[62:63], 0.5 op_sel_hi:[1,0]
	v_pk_mul_f32 v[64:65], v[60:61], 0.5 op_sel_hi:[1,0]
	v_pk_mul_f32 v[62:63], v[58:59], 0.5 op_sel_hi:[1,0]
	v_pk_mul_f32 v[60:61], v[56:57], 0.5 op_sel_hi:[1,0]
	v_pk_mul_f32 v[74:75], v[46:47], 0.5 op_sel_hi:[1,0]
	v_pk_mul_f32 v[72:73], v[44:45], 0.5 op_sel_hi:[1,0]
	v_pk_mul_f32 v[70:71], v[38:39], 0.5 op_sel_hi:[1,0]
	v_pk_mul_f32 v[68:69], v[36:37], 0.5 op_sel_hi:[1,0]
	v_pk_mul_f32 v[54:55], v[54:55], 0.5 op_sel_hi:[1,0]
	v_pk_mul_f32 v[52:53], v[52:53], 0.5 op_sel_hi:[1,0]
	v_pk_mul_f32 v[46:47], v[50:51], 0.5 op_sel_hi:[1,0]
	v_pk_mul_f32 v[44:45], v[48:49], 0.5 op_sel_hi:[1,0]
	v_pk_mul_f32 v[58:59], v[30:31], 0.5 op_sel_hi:[1,0]
	v_pk_mul_f32 v[56:57], v[28:29], 0.5 op_sel_hi:[1,0]
	v_pk_mul_f32 v[50:51], v[22:23], 0.5 op_sel_hi:[1,0]
	v_pk_mul_f32 v[48:49], v[20:21], 0.5 op_sel_hi:[1,0]
	v_pk_mul_f32 v[30:31], v[42:43], 0.5 op_sel_hi:[1,0]
	v_pk_mul_f32 v[28:29], v[40:41], 0.5 op_sel_hi:[1,0]
	v_pk_mul_f32 v[22:23], v[34:35], 0.5 op_sel_hi:[1,0]
	v_pk_mul_f32 v[20:21], v[32:33], 0.5 op_sel_hi:[1,0]
	v_pk_mul_f32 v[38:39], v[14:15], 0.5 op_sel_hi:[1,0]
	v_pk_mul_f32 v[36:37], v[12:13], 0.5 op_sel_hi:[1,0]
	v_pk_mul_f32 v[34:35], v[10:11], 0.5 op_sel_hi:[1,0]
	v_pk_mul_f32 v[32:33], v[8:9], 0.5 op_sel_hi:[1,0]
	v_pk_mul_f32 v[14:15], v[26:27], 0.5 op_sel_hi:[1,0]
	v_pk_mul_f32 v[12:13], v[24:25], 0.5 op_sel_hi:[1,0]
	v_pk_mul_f32 v[10:11], v[18:19], 0.5 op_sel_hi:[1,0]
	v_pk_mul_f32 v[8:9], v[16:17], 0.5 op_sel_hi:[1,0]
	v_pk_mul_f32 v[6:7], v[6:7], 0.5 op_sel_hi:[1,0]
	v_pk_mul_f32 v[4:5], v[4:5], 0.5 op_sel_hi:[1,0]
	v_pk_mul_f32 v[2:3], v[2:3], 0.5 op_sel_hi:[1,0]
	v_pk_mul_f32 v[0:1], v[0:1], 0.5 op_sel_hi:[1,0]
